# v27 + sc1 (write-through, dropped from L2) on the 16-byte output stores of all eight GEMM epilogues
# baseline (speedup 1.0000x reference)
; __device__ __forceinline__ unsigned cvt_pk_bf16(float lo, float hi) { unsigned r; asm volatile("v_cvt_pk_bf16_f32 %0, %1, %2" : "=v"(r) : "v"(lo), "v"(hi)); return r; }
; __device__ __forceinline__ unsigned cvt_pk_bf16(float lo, float hi) { unsigned r; asm volatile("v_cvt_pk_bf16_f32 %0, %1, %2" : "=v"(r) : "v"(lo), "v"(hi)); return r; }
; __device__ __forceinline__ float ssq_rstd(const ssq_t* ssq, int row) { return __builtin_amdgcn_rsqf((float)ssq[row] * (SSQ_UNFIX * RMS_INV_D) + RMS_EPS); }
;     __device__ __forceinline__ void operator()(const f32x4 (&acc)[2][2][4][2], const Unit& u, int wr, int wc, int fr, int fq) const {
;         const int row0 = u.pm * BM + wr * 64 + fr, col0 = u.pn * BM + wc * 32 + 8 * fq;
;         float rs[2][4];
; #pragma unroll
;         for (int ai = 0; ai < 2; ++ai)
; #pragma unroll
;             for (int m = 0; m < 4; ++m) rs[ai][m] = SCALE ? ssq_rstd(ssq, row0 + ai * HALF + m * 16) : 1.0f;
; #pragma unroll
;         for (int ai = 0; ai < 2; ++ai)
; #pragma unroll
;             for (int m = 0; m < 4; ++m) { const int row = row0 + ai * HALF + m * 16; bf16_t* rowp = O + (size_t)row * ldc + col0;
; #pragma unroll
;                 for (int bj = 0; bj < 2; ++bj) { const f32x2 r2 = {rs[ai][m], rs[ai][m]}; const f32x4 a0 = acc[ai][bj][m][0], a1 = acc[ai][bj][m][1];
;                     const f32x2 p0 = (f32x2){a0[0], a0[1]} * r2, p1 = (f32x2){a0[2], a0[3]} * r2, p2 = (f32x2){a1[0], a1[1]} * r2, p3 = (f32x2){a1[2], a1[3]} * r2;
;                     u32x4 w; w.x = cvt_pk_bf16(p0.x, p0.y); w.y = cvt_pk_bf16(p1.x, p1.y); w.z = cvt_pk_bf16(p2.x, p2.y); w.w = cvt_pk_bf16(p3.x, p3.y);
;                     *(u32x4*)(rowp + bj * HALF) = w; } }
.Lepi_rest_676:
	v_add_u32_e32 v157, 0x80, v150
	v_add_u32_e32 v159, 0x90, v150
	v_add_u32_e32 v163, 0xa0, v150
	s_andn2_b64 vcc, exec, s[0:1]
	s_mov_b64 s[0:1], -1
	s_waitcnt vmcnt(0)
	v_ffbh_u32_e32 v146, v173
	v_min_u32_e32 v146, 32, v146
	v_ffbh_u32_e32 v160, v169
	v_lshlrev_b64 v[172:173], v146, v[172:173]
	v_min_u32_e32 v160, 32, v160
	v_ffbh_u32_e32 v165, v171
	v_ffbh_u32_e32 v167, v181
	v_min_u32_e32 v172, 1, v172
	v_lshlrev_b64 v[168:169], v160, v[168:169]
	v_min_u32_e32 v165, 32, v165
	v_min_u32_e32 v167, 32, v167
	v_or_b32_e32 v172, v173, v172
	v_min_u32_e32 v168, 1, v168
	v_lshlrev_b64 v[170:171], v165, v[170:171]
	v_lshlrev_b64 v[180:181], v167, v[180:181]
	v_cvt_f32_u32_e32 v172, v172
	v_or_b32_e32 v168, v169, v168
	v_min_u32_e32 v170, 1, v170
	v_min_u32_e32 v173, 1, v180
	v_cvt_f32_u32_e32 v168, v168
	v_ffbh_u32_e32 v151, v175
	v_or_b32_e32 v169, v171, v170
	v_or_b32_e32 v170, v181, v173
	v_ffbh_u32_e32 v152, v177
	v_ffbh_u32_e32 v154, v179
	v_min_u32_e32 v151, 32, v151
	v_ffbh_u32_e32 v182, v149
	v_sub_u32_e32 v146, 32, v146
	v_cvt_f32_u32_e32 v170, v170
	v_min_u32_e32 v152, 32, v152
	v_min_u32_e32 v154, 32, v154
	v_lshlrev_b64 v[174:175], v151, v[174:175]
	v_min_u32_e32 v182, 32, v182
	v_sub_u32_e32 v160, 32, v160
	v_ldexp_f32 v146, v172, v146
	v_lshlrev_b64 v[176:177], v152, v[176:177]
	v_lshlrev_b64 v[178:179], v154, v[178:179]
	v_min_u32_e32 v174, 1, v174
	v_lshlrev_b64 v[148:149], v182, v[148:149]
	v_fmamk_f32 v146, v146, 0x2d800000, v162
	v_ldexp_f32 v160, v168, v160
	v_sub_u32_e32 v167, 32, v167
	v_min_u32_e32 v176, 1, v176
	v_min_u32_e32 v178, 1, v178
	v_or_b32_e32 v174, v175, v174
	v_min_u32_e32 v148, 1, v148
	v_rsq_f32_e32 v168, v146
	v_fmamk_f32 v146, v160, 0x2d800000, v162
	v_or_b32_e32 v175, v177, v176
	v_or_b32_e32 v176, v179, v178
	v_cvt_f32_u32_e32 v171, v174
	v_cvt_f32_u32_e32 v169, v169
	v_ldexp_f32 v167, v170, v167
	v_rsq_f32_e32 v170, v146
	v_or_b32_e32 v146, v149, v148
	v_cvt_f32_u32_e32 v174, v176
	v_cvt_f32_u32_e32 v146, v146
	v_sub_u32_e32 v151, 32, v151
	v_sub_u32_e32 v165, 32, v165
	v_sub_u32_e32 v154, 32, v154
	v_ldexp_f32 v151, v171, v151
	v_ldexp_f32 v165, v169, v165
	v_sub_u32_e32 v148, 32, v182
	v_lshl_or_b32 v176, s47, 8, v155
	v_ldexp_f32 v154, v174, v154
	v_fmamk_f32 v151, v151, 0x2d800000, v162
	v_fmamk_f32 v165, v165, 0x2d800000, v162
	v_ldexp_f32 v146, v146, v148
	v_ashrrev_i32_e32 v177, 31, v176
	v_mov_b64_e32 v[148:149], s[38:39]
	v_fmamk_f32 v169, v154, 0x2d800000, v162
	v_rsq_f32_e32 v160, v151
	v_rsq_f32_e32 v172, v165
	v_add_u32_e32 v165, 0xb0, v150
	v_mad_i64_i32 v[178:179], s[20:21], v150, s37, v[148:149]
	v_lshlrev_b64 v[150:151], 1, v[176:177]
	v_lshl_add_u64 v[176:177], v[178:179], 0, v[150:151]
	v_pk_mul_f32 v[118:119], v[118:119], v[168:169] op_sel_hi:[1,0]
	v_pk_mul_f32 v[120:121], v[120:121], v[168:169] op_sel_hi:[1,0]
	v_pk_mul_f32 v[178:179], v[114:115], v[168:169] op_sel_hi:[1,0]
	v_cvt_pk_bf16_f32 v114, v118, v119
	v_cvt_pk_bf16_f32 v115, v120, v121
	v_pk_mul_f32 v[180:181], v[116:117], v[168:169] op_sel_hi:[1,0]
	v_cvt_pk_bf16_f32 v116, v178, v179
	v_pk_mul_f32 v[118:119], v[122:123], v[168:169] op_sel_hi:[1,0]
	v_cvt_pk_bf16_f32 v117, v180, v181
	global_store_dwordx4 v[176:177], v[114:117], off sc1
	v_pk_mul_f32 v[120:121], v[124:125], v[168:169] op_sel_hi:[1,0]
	v_cvt_f32_u32_e32 v173, v175
	v_pk_mul_f32 v[114:115], v[126:127], v[168:169] op_sel_hi:[1,0]
	v_pk_mul_f32 v[116:117], v[128:129], v[168:169] op_sel_hi:[1,0]
	v_cvt_pk_bf16_f32 v114, v114, v115
	v_pk_mul_f32 v[102:103], v[102:103], v[170:171] op_sel_hi:[1,0]
	v_cvt_pk_bf16_f32 v115, v116, v117
	v_cvt_pk_bf16_f32 v116, v118, v119
	v_cvt_pk_bf16_f32 v117, v120, v121
	global_store_dwordx4 v[176:177], v[114:117], off offset:256 sc1
	v_pk_mul_f32 v[104:105], v[104:105], v[170:171] op_sel_hi:[1,0]
	v_pk_mul_f32 v[118:119], v[100:101], v[170:171] op_sel_hi:[1,0]
	v_mad_i64_i32 v[114:115], s[20:21], v166, s37, v[148:149]
	v_lshl_add_u64 v[114:115], v[114:115], 0, v[150:151]
	v_pk_mul_f32 v[116:117], v[98:99], v[170:171] op_sel_hi:[1,0]
	v_cvt_pk_bf16_f32 v98, v102, v103
	v_cvt_pk_bf16_f32 v99, v104, v105
	v_fmamk_f32 v167, v167, 0x2d800000, v162
	v_cvt_pk_bf16_f32 v100, v116, v117
	v_cvt_pk_bf16_f32 v101, v118, v119
	global_store_dwordx4 v[114:115], v[98:101], off sc1
	v_pk_mul_f32 v[102:103], v[106:107], v[170:171] op_sel_hi:[1,0]
	v_pk_mul_f32 v[104:105], v[108:109], v[170:171] op_sel_hi:[1,0]
	v_pk_mul_f32 v[98:99], v[110:111], v[170:171] op_sel_hi:[1,0]
	v_pk_mul_f32 v[100:101], v[112:113], v[170:171] op_sel_hi:[1,0]
	v_cvt_pk_bf16_f32 v98, v98, v99
	v_rsq_f32_e32 v174, v167
	v_cvt_pk_bf16_f32 v99, v100, v101
	v_cvt_pk_bf16_f32 v100, v102, v103
	v_cvt_pk_bf16_f32 v101, v104, v105
	global_store_dwordx4 v[114:115], v[98:101], off offset:256 sc1
	v_pk_mul_f32 v[86:87], v[86:87], v[172:173] op_sel_hi:[1,0]
	v_pk_mul_f32 v[88:89], v[88:89], v[172:173] op_sel_hi:[1,0]
	v_mad_i64_i32 v[98:99], s[20:21], v158, s37, v[148:149]
	v_lshl_add_u64 v[98:99], v[98:99], 0, v[150:151]
	v_pk_mul_f32 v[100:101], v[82:83], v[172:173] op_sel_hi:[1,0]
	v_cvt_pk_bf16_f32 v82, v86, v87
	v_cvt_pk_bf16_f32 v83, v88, v89
	v_pk_mul_f32 v[102:103], v[84:85], v[172:173] op_sel_hi:[1,0]
	v_cvt_pk_bf16_f32 v84, v100, v101
	v_pk_mul_f32 v[86:87], v[90:91], v[172:173] op_sel_hi:[1,0]
	v_cvt_pk_bf16_f32 v85, v102, v103
	global_store_dwordx4 v[98:99], v[82:85], off sc1
	v_pk_mul_f32 v[88:89], v[92:93], v[172:173] op_sel_hi:[1,0]
	v_pk_mul_f32 v[70:71], v[70:71], v[174:175] op_sel_hi:[1,0]
	v_pk_mul_f32 v[82:83], v[94:95], v[172:173] op_sel_hi:[1,0]
	v_pk_mul_f32 v[84:85], v[96:97], v[172:173] op_sel_hi:[1,0]
	v_cvt_pk_bf16_f32 v82, v82, v83
; __device__ __forceinline__ unsigned cvt_pk_bf16(float lo, float hi) { unsigned r; asm volatile("v_cvt_pk_bf16_f32 %0, %1, %2" : "=v"(r) : "v"(lo), "v"(hi)); return r; }
; __device__ __forceinline__ unsigned cvt_pk_bf16(float lo, float hi) { unsigned r; asm volatile("v_cvt_pk_bf16_f32 %0, %1, %2" : "=v"(r) : "v"(lo), "v"(hi)); return r; }
; #define PG8_BAR __builtin_amdgcn_s_barrier()
;     __device__ __forceinline__ void operator()(const f32x4 (&acc)[2][2][4][2], const Unit& u, int wr, int wc, int fr, int fq) const {
;     ...
;             for (int m = 0; m < 4; ++m) { const int row = row0 + ai * HALF + m * 16; bf16_t* rowp = O + (size_t)row * ldc + col0;
; #pragma unroll
;                 for (int bj = 0; bj < 2; ++bj) { const f32x2 r2 = {rs[ai][m], rs[ai][m]}; const f32x4 a0 = acc[ai][bj][m][0], a1 = acc[ai][bj][m][1];
;                     const f32x2 p0 = (f32x2){a0[0], a0[1]} * r2, p1 = (f32x2){a0[2], a0[3]} * r2, p2 = (f32x2){a1[0], a1[1]} * r2, p3 = (f32x2){a1[2], a1[3]} * r2;
;                     u32x4 w; w.x = cvt_pk_bf16(p0.x, p0.y); w.y = cvt_pk_bf16(p1.x, p1.y); w.z = cvt_pk_bf16(p2.x, p2.y); w.w = cvt_pk_bf16(p3.x, p3.y);
;                     *(u32x4*)(rowp + bj * HALF) = w; } }
; template <class Epi, class Sched, bool ALIGN_EPI = false, bool SP2 = false>
; __device__ __forceinline__ void gemm_phase(PG8_LAS unsigned char* lds, const Gemm g, const Sched& S, const Epi& E) {
;     ...
; #pragma unroll
;         for (int a = 0; a < 2; ++a)
; #pragma unroll
;             for (int b = 0; b < 2; ++b)
; #pragma unroll
;                 for (int m = 0; m < 4; ++m)
; #pragma unroll
;                     for (int n = 0; n < 2; ++n) { d64x2 z_; asm volatile("v_mov_b64 %0, 0\n\tv_mov_b64 %1, 0" : "=v"(z_.x), "=v"(z_.y)); acc[a][b][m][n] = __builtin_bit_cast(f32x4, z_); }
;         cur = nxt; cA = nA; cB = nB; ++ui;
;         if constexpr (ALIGN_EPI) { if (wr == 1) PG8_BAR; }
	v_pk_mul_f32 v[72:73], v[72:73], v[174:175] op_sel_hi:[1,0]
	v_cvt_pk_bf16_f32 v83, v84, v85
	v_cvt_pk_bf16_f32 v84, v86, v87
	v_cvt_pk_bf16_f32 v85, v88, v89
	global_store_dwordx4 v[98:99], v[82:85], off offset:256 sc1
	v_sub_u32_e32 v152, 32, v152
	v_pk_mul_f32 v[86:87], v[68:69], v[174:175] op_sel_hi:[1,0]
	v_mad_i64_i32 v[82:83], s[20:21], v156, s37, v[148:149]
	v_lshl_add_u64 v[82:83], v[82:83], 0, v[150:151]
	v_pk_mul_f32 v[84:85], v[66:67], v[174:175] op_sel_hi:[1,0]
	v_cvt_pk_bf16_f32 v66, v70, v71
	v_cvt_pk_bf16_f32 v67, v72, v73
	v_ldexp_f32 v152, v173, v152
	v_cvt_pk_bf16_f32 v68, v84, v85
	v_cvt_pk_bf16_f32 v69, v86, v87
	global_store_dwordx4 v[82:83], v[66:69], off sc1
	v_fmamk_f32 v152, v152, 0x2d800000, v162
	v_pk_mul_f32 v[70:71], v[74:75], v[174:175] op_sel_hi:[1,0]
	v_pk_mul_f32 v[66:67], v[78:79], v[174:175] op_sel_hi:[1,0]
	v_pk_mul_f32 v[68:69], v[80:81], v[174:175] op_sel_hi:[1,0]
	v_cvt_pk_bf16_f32 v66, v66, v67
	v_pk_mul_f32 v[72:73], v[76:77], v[174:175] op_sel_hi:[1,0]
	v_cvt_pk_bf16_f32 v67, v68, v69
	v_cvt_pk_bf16_f32 v68, v70, v71
	v_rsq_f32_e32 v154, v152
	v_cvt_pk_bf16_f32 v69, v72, v73
	global_store_dwordx4 v[82:83], v[66:69], off offset:256 sc1
	v_pk_mul_f32 v[54:55], v[54:55], v[160:161] op_sel_hi:[1,0]
	v_pk_mul_f32 v[56:57], v[56:57], v[160:161] op_sel_hi:[1,0]
	v_mad_i64_i32 v[66:67], s[20:21], v157, s37, v[148:149]
	v_lshl_add_u64 v[66:67], v[66:67], 0, v[150:151]
	v_pk_mul_f32 v[68:69], v[50:51], v[160:161] op_sel_hi:[1,0]
	v_cvt_pk_bf16_f32 v50, v54, v55
	v_cvt_pk_bf16_f32 v51, v56, v57
	v_pk_mul_f32 v[70:71], v[52:53], v[160:161] op_sel_hi:[1,0]
	v_cvt_pk_bf16_f32 v52, v68, v69
	v_pk_mul_f32 v[54:55], v[58:59], v[160:161] op_sel_hi:[1,0]
	v_cvt_pk_bf16_f32 v53, v70, v71
	global_store_dwordx4 v[66:67], v[50:53], off sc1
	v_pk_mul_f32 v[56:57], v[60:61], v[160:161] op_sel_hi:[1,0]
	v_rsq_f32_e32 v152, v169
	v_pk_mul_f32 v[50:51], v[62:63], v[160:161] op_sel_hi:[1,0]
	v_pk_mul_f32 v[52:53], v[64:65], v[160:161] op_sel_hi:[1,0]
	v_cvt_pk_bf16_f32 v50, v50, v51
	v_pk_mul_f32 v[38:39], v[38:39], v[154:155] op_sel_hi:[1,0]
	v_cvt_pk_bf16_f32 v51, v52, v53
	v_cvt_pk_bf16_f32 v52, v54, v55
	v_cvt_pk_bf16_f32 v53, v56, v57
	global_store_dwordx4 v[66:67], v[50:53], off offset:256 sc1
	v_pk_mul_f32 v[40:41], v[40:41], v[154:155] op_sel_hi:[1,0]
	v_pk_mul_f32 v[54:55], v[36:37], v[154:155] op_sel_hi:[1,0]
	v_mad_i64_i32 v[50:51], s[20:21], v159, s37, v[148:149]
	v_lshl_add_u64 v[50:51], v[50:51], 0, v[150:151]
	v_pk_mul_f32 v[52:53], v[34:35], v[154:155] op_sel_hi:[1,0]
	v_cvt_pk_bf16_f32 v34, v38, v39
	v_cvt_pk_bf16_f32 v35, v40, v41
	v_fmamk_f32 v146, v146, 0x2d800000, v162
	v_cvt_pk_bf16_f32 v36, v52, v53
	v_cvt_pk_bf16_f32 v37, v54, v55
	global_store_dwordx4 v[50:51], v[34:37], off sc1
	v_pk_mul_f32 v[38:39], v[42:43], v[154:155] op_sel_hi:[1,0]
	v_pk_mul_f32 v[40:41], v[44:45], v[154:155] op_sel_hi:[1,0]
	v_pk_mul_f32 v[34:35], v[46:47], v[154:155] op_sel_hi:[1,0]
	v_pk_mul_f32 v[36:37], v[48:49], v[154:155] op_sel_hi:[1,0]
	v_cvt_pk_bf16_f32 v34, v34, v35
	v_rsq_f32_e32 v146, v146
	v_cvt_pk_bf16_f32 v35, v36, v37
	v_cvt_pk_bf16_f32 v36, v38, v39
	v_cvt_pk_bf16_f32 v37, v40, v41
	global_store_dwordx4 v[50:51], v[34:37], off offset:256 sc1
	v_pk_mul_f32 v[22:23], v[22:23], v[152:153] op_sel_hi:[1,0]
	v_pk_mul_f32 v[24:25], v[24:25], v[152:153] op_sel_hi:[1,0]
	v_mad_i64_i32 v[34:35], s[20:21], v163, s37, v[148:149]
	v_lshl_add_u64 v[34:35], v[34:35], 0, v[150:151]
	v_pk_mul_f32 v[36:37], v[18:19], v[152:153] op_sel_hi:[1,0]
	v_cvt_pk_bf16_f32 v18, v22, v23
	v_cvt_pk_bf16_f32 v19, v24, v25
	v_pk_mul_f32 v[38:39], v[20:21], v[152:153] op_sel_hi:[1,0]
	v_cvt_pk_bf16_f32 v20, v36, v37
	v_pk_mul_f32 v[22:23], v[26:27], v[152:153] op_sel_hi:[1,0]
	v_cvt_pk_bf16_f32 v21, v38, v39
	global_store_dwordx4 v[34:35], v[18:21], off sc1
	v_pk_mul_f32 v[24:25], v[28:29], v[152:153] op_sel_hi:[1,0]
	v_pk_mul_f32 v[6:7], v[6:7], v[146:147] op_sel_hi:[1,0]
	v_pk_mul_f32 v[18:19], v[30:31], v[152:153] op_sel_hi:[1,0]
	v_pk_mul_f32 v[20:21], v[32:33], v[152:153] op_sel_hi:[1,0]
	v_cvt_pk_bf16_f32 v18, v18, v19
	v_pk_mul_f32 v[8:9], v[8:9], v[146:147] op_sel_hi:[1,0]
	v_cvt_pk_bf16_f32 v19, v20, v21
	v_cvt_pk_bf16_f32 v20, v22, v23
	v_cvt_pk_bf16_f32 v21, v24, v25
	global_store_dwordx4 v[34:35], v[18:21], off offset:256 sc1
	v_pk_mul_f32 v[22:23], v[4:5], v[146:147] op_sel_hi:[1,0]
	s_nop 0
	v_mad_i64_i32 v[18:19], s[20:21], v165, s37, v[148:149]
	v_lshl_add_u64 v[18:19], v[18:19], 0, v[150:151]
	v_pk_mul_f32 v[20:21], v[2:3], v[146:147] op_sel_hi:[1,0]
	v_cvt_pk_bf16_f32 v2, v6, v7
	v_cvt_pk_bf16_f32 v3, v8, v9
	v_pk_mul_f32 v[6:7], v[14:15], v[146:147] op_sel_hi:[1,0]
	v_cvt_pk_bf16_f32 v4, v20, v21
	v_cvt_pk_bf16_f32 v5, v22, v23
	global_store_dwordx4 v[18:19], v[2:5], off sc1
	v_pk_mul_f32 v[8:9], v[16:17], v[146:147] op_sel_hi:[1,0]
	s_nop 0
	v_pk_mul_f32 v[2:3], v[10:11], v[146:147] op_sel_hi:[1,0]
	v_pk_mul_f32 v[4:5], v[12:13], v[146:147] op_sel_hi:[1,0]
	v_cvt_pk_bf16_f32 v2, v2, v3
	s_nop 0
	v_cvt_pk_bf16_f32 v3, v4, v5
	v_cvt_pk_bf16_f32 v4, v6, v7
	v_cvt_pk_bf16_f32 v5, v8, v9
	global_store_dwordx4 v[18:19], v[2:5], off offset:256 sc1
	s_cbranch_vccnz .LBB0_669
	s_andn2_b64 vcc, exec, s[4:5]
	v_mov_b64 v[118:119], 0
	v_mov_b64 v[120:121], 0
	v_mov_b64 v[114:115], 0
	v_mov_b64 v[116:117], 0
	v_mov_b64 v[102:103], 0
	v_mov_b64 v[104:105], 0
	v_mov_b64 v[98:99], 0
	v_mov_b64 v[100:101], 0
	v_mov_b64 v[86:87], 0
	v_mov_b64 v[88:89], 0
	v_mov_b64 v[82:83], 0
	v_mov_b64 v[84:85], 0
	v_mov_b64 v[70:71], 0
	v_mov_b64 v[72:73], 0
	v_mov_b64 v[66:67], 0
	v_mov_b64 v[68:69], 0
	v_mov_b64 v[126:127], 0
	v_mov_b64 v[128:129], 0
	v_mov_b64 v[122:123], 0
	v_mov_b64 v[124:125], 0
	v_mov_b64 v[110:111], 0
	v_mov_b64 v[112:113], 0
	v_mov_b64 v[106:107], 0
	v_mov_b64 v[108:109], 0
	v_mov_b64 v[94:95], 0
	v_mov_b64 v[96:97], 0
	v_mov_b64 v[90:91], 0
	v_mov_b64 v[92:93], 0
	v_mov_b64 v[78:79], 0
	v_mov_b64 v[80:81], 0
	v_mov_b64 v[74:75], 0
	v_mov_b64 v[76:77], 0
	v_mov_b64 v[54:55], 0
	v_mov_b64 v[56:57], 0
	v_mov_b64 v[50:51], 0
	v_mov_b64 v[52:53], 0
	v_mov_b64 v[38:39], 0
	v_mov_b64 v[40:41], 0
	v_mov_b64 v[34:35], 0
	v_mov_b64 v[36:37], 0
	v_mov_b64 v[22:23], 0
	v_mov_b64 v[24:25], 0
	v_mov_b64 v[18:19], 0
	v_mov_b64 v[20:21], 0
	v_mov_b64 v[6:7], 0
	v_mov_b64 v[8:9], 0
	v_mov_b64 v[2:3], 0
	v_mov_b64 v[4:5], 0
	v_mov_b64 v[62:63], 0
	v_mov_b64 v[64:65], 0
	v_mov_b64 v[58:59], 0
	v_mov_b64 v[60:61], 0
	v_mov_b64 v[46:47], 0
	v_mov_b64 v[48:49], 0
	v_mov_b64 v[42:43], 0
	v_mov_b64 v[44:45], 0
	v_mov_b64 v[30:31], 0
	v_mov_b64 v[32:33], 0
	v_mov_b64 v[26:27], 0
	v_mov_b64 v[28:29], 0
	v_mov_b64 v[10:11], 0
	v_mov_b64 v[12:13], 0
	v_mov_b64 v[14:15], 0
	v_mov_b64 v[16:17], 0
	s_cbranch_vccnz .LBB0_668
	s_barrier
	s_branch .LBB0_668

; __device__ __forceinline__ unsigned cvt_pk_bf16(float lo, float hi) { unsigned r; asm volatile("v_cvt_pk_bf16_f32 %0, %1, %2" : "=v"(r) : "v"(lo), "v"(hi)); return r; }
; __device__ __forceinline__ unsigned cvt_pk_bf16(float lo, float hi) { unsigned r; asm volatile("v_cvt_pk_bf16_f32 %0, %1, %2" : "=v"(r) : "v"(lo), "v"(hi)); return r; }
;     __device__ __forceinline__ void operator()(const f32x4 (&acc)[2][2][4][2], const Unit& u, int wr, int wc, int fr, int fq) const {
;     ...
;                 for (int bj = 0; bj < 2; ++bj) { const size_t off = (size_t)(row0 + ai * HALF + m * 16) * ldc + col0 + bj * HALF;
;                     if (BASE_F32) { const float* bp = (const float*)base + off; b0[m][bj] = *(const f32x4*)bp; b1[m][bj] = *(const f32x4*)(bp + 4); }
;                     else { const u32x4 r = *(const u32x4*)((const bf16_t*)base + off);
;                         b0[m][bj] = (f32x4){__uint_as_float(r.x << 16), __uint_as_float(r.x & 0xffff0000u), __uint_as_float(r.y << 16), __uint_as_float(r.y & 0xffff0000u)};
;                         b1[m][bj] = (f32x4){__uint_as_float(r.z << 16), __uint_as_float(r.z & 0xffff0000u), __uint_as_float(r.w << 16), __uint_as_float(r.w & 0xffff0000u)}; } }
; #pragma unroll
;             for (int m = 0; m < 4; ++m) { const int row = row0 + ai * HALF + m * 16; const size_t off = (size_t)row * ldc + col0; f32x2 q2 = {0.f, 0.f};
; #pragma unroll
;                 for (int bj = 0; bj < 2; ++bj) { const f32x4 v0 = acc[ai][bj][m][0] + b0[m][bj], v1 = acc[ai][bj][m][1] + b1[m][bj];
;                     { const f32x2 e0 = {v0[0], v0[1]}, e1 = {v0[2], v0[3]}, e2 = {v1[0], v1[1]}, e3 = {v1[2], v1[3]}; q2 = e0 * e0 + q2; q2 = e1 * e1 + q2; q2 = e2 * e2 + q2; q2 = e3 * e3 + q2; }
;                     u32x4 w; w.x = cvt_pk_bf16(v0[0], v0[1]); w.y = cvt_pk_bf16(v0[2], v0[3]); w.z = cvt_pk_bf16(v1[0], v1[1]); w.w = cvt_pk_bf16(v1[2], v1[3]);
;                     *(u32x4*)(out + off + bj * HALF) = w; }
;                 float q = q2.x + q2.y; q += __shfl_xor(q, 16); q += __shfl_xor(q, 32);
;                 if (fq == 0) atomicAdd(ssq + row, (ssq_t)(q * SSQ_FIX + 0.5f)); }
.Lepi_rest_1042:
	v_and_b32_e32 v200, 64, v186
	v_xor_b32_e32 v187, 16, v186
	v_add_u32_e32 v200, 64, v200
	v_xor_b32_e32 v201, 32, v186
	v_cmp_lt_i32_e32 vcc, v187, v200
	v_lshl_add_u64 v[198:199], s[96:97], 0, v[198:199]
	v_lshl_add_u64 v[196:197], v[198:199], 0, v[196:197]
	v_cndmask_b32_e32 v187, v186, v187, vcc
	v_cmp_lt_i32_e32 vcc, v201, v200
	v_lshlrev_b32_e32 v187, 2, v187
	s_waitcnt vmcnt(0)
	v_lshlrev_b32_e32 v198, 16, v188
	v_and_b32_e32 v199, 0xffff0000, v188
	v_lshlrev_b32_e32 v188, 16, v189
	v_and_b32_e32 v189, 0xffff0000, v189
	v_cndmask_b32_e32 v206, v186, v201, vcc
	v_lshlrev_b32_e32 v200, 16, v190
	v_and_b32_e32 v201, 0xffff0000, v190
	v_lshlrev_b32_e32 v190, 16, v191
	v_and_b32_e32 v191, 0xffff0000, v191
	v_pk_add_f32 v[116:117], v[116:117], v[188:189]
	v_pk_add_f32 v[188:189], v[114:115], v[198:199]
	v_pk_add_f32 v[120:121], v[120:121], v[190:191]
	v_pk_mul_f32 v[190:191], v[116:117], v[116:117]
	v_pk_add_f32 v[118:119], v[118:119], v[200:201]
	v_cvt_pk_bf16_f32 v114, v188, v189
	v_cvt_pk_bf16_f32 v115, v116, v117
	v_pk_fma_f32 v[116:117], v[188:189], v[188:189], v[190:191]
	v_lshlrev_b32_e32 v202, 16, v192
	v_and_b32_e32 v203, 0xffff0000, v192
	v_pk_fma_f32 v[116:117], v[118:119], v[118:119], v[116:117]
	v_lshlrev_b32_e32 v192, 16, v193
	v_and_b32_e32 v193, 0xffff0000, v193
	v_pk_add_f32 v[122:123], v[122:123], v[202:203]
	v_pk_fma_f32 v[116:117], v[120:121], v[120:121], v[116:117]
	v_lshlrev_b32_e32 v204, 16, v194
	v_and_b32_e32 v205, 0xffff0000, v194
	v_pk_add_f32 v[124:125], v[124:125], v[192:193]
	v_pk_fma_f32 v[116:117], v[122:123], v[122:123], v[116:117]
	v_lshlrev_b32_e32 v194, 16, v195
	v_and_b32_e32 v195, 0xffff0000, v195
	v_pk_add_f32 v[126:127], v[126:127], v[204:205]
	v_pk_fma_f32 v[116:117], v[124:125], v[124:125], v[116:117]
	v_pk_add_f32 v[128:129], v[128:129], v[194:195]
	v_pk_fma_f32 v[116:117], v[126:127], v[126:127], v[116:117]
	s_nop 0
	v_pk_fma_f32 v[116:117], v[128:129], v[128:129], v[116:117]
	s_nop 0
	v_add_f32_e32 v188, v116, v117
	ds_bpermute_b32 v189, v187, v188
	v_cvt_pk_bf16_f32 v116, v118, v119
	v_cvt_pk_bf16_f32 v117, v120, v121
	global_store_dwordx4 v[196:197], v[114:117], off sc1
	v_cvt_pk_bf16_f32 v118, v122, v123
	v_cvt_pk_bf16_f32 v119, v124, v125
	v_cvt_pk_bf16_f32 v120, v126, v127
	v_cvt_pk_bf16_f32 v121, v128, v129
	global_store_dwordx4 v[196:197], v[118:121], off offset:256 sc1
	s_waitcnt lgkmcnt(0)
	v_add_f32_e32 v115, v188, v189
	v_lshlrev_b32_e32 v114, 2, v206
	ds_bpermute_b32 v116, v114, v115
	s_and_saveexec_b64 s[20:21], s[0:1]
	s_cbranch_execz .LBB0_1044
	s_waitcnt lgkmcnt(0)
	v_add_f32_e32 v115, v115, v116
	v_fma_f32 v115, v115, s64, 0.5
	v_trunc_f32_e32 v115, v115
	v_mul_f32_e32 v116, 0x2f800000, v115
	v_floor_f32_e32 v117, v116
	v_fmac_f32_e32 v115, 0xcf800000, v117
	v_cvt_u32_f32_e32 v116, v115
	v_cvt_u32_f32_e32 v117, v117
	v_lshl_add_u64 v[118:119], v[176:177], 3, s[4:5]
	global_atomic_add_x2 v[118:119], v[116:117], off
.LBB0_1044:
	s_or_b64 exec, exec, s[20:21]
	v_lshlrev_b32_e32 v120, 16, v151
	v_and_b32_e32 v121, 0xffff0000, v151
	v_lshlrev_b32_e32 v118, 16, v150
	v_and_b32_e32 v119, 0xffff0000, v150
	v_lshlrev_b32_e32 v122, 16, v152
	v_and_b32_e32 v123, 0xffff0000, v152
	v_lshlrev_b32_e32 v124, 16, v153
	v_and_b32_e32 v125, 0xffff0000, v153
	v_pk_add_f32 v[108:109], v[108:109], v[120:121]
	v_pk_add_f32 v[106:107], v[106:107], v[118:119]
	v_pk_add_f32 v[118:119], v[100:101], v[124:125]
	v_pk_add_f32 v[100:101], v[98:99], v[122:123]
	v_pk_mul_f32 v[98:99], v[108:109], v[108:109]
	v_lshlrev_b32_e32 v126, 16, v146
	v_pk_fma_f32 v[98:99], v[106:107], v[106:107], v[98:99]
	v_and_b32_e32 v127, 0xffff0000, v146
	v_pk_fma_f32 v[98:99], v[100:101], v[100:101], v[98:99]
	v_lshlrev_b32_e32 v128, 16, v147
	v_and_b32_e32 v129, 0xffff0000, v147
	v_pk_fma_f32 v[120:121], v[118:119], v[118:119], v[98:99]
	v_cvt_pk_bf16_f32 v98, v106, v107
	v_cvt_pk_bf16_f32 v99, v108, v109
	v_pk_add_f32 v[108:109], v[110:111], v[126:127]
	v_lshlrev_b32_e32 v146, 16, v148
	v_and_b32_e32 v147, 0xffff0000, v148
	v_pk_add_f32 v[106:107], v[112:113], v[128:129]
	v_pk_fma_f32 v[110:111], v[108:109], v[108:109], v[120:121]
	v_lshlrev_b32_e32 v148, 16, v149
	v_and_b32_e32 v149, 0xffff0000, v149
	v_pk_add_f32 v[102:103], v[102:103], v[146:147]
	v_pk_fma_f32 v[110:111], v[106:107], v[106:107], v[110:111]
	v_pk_add_f32 v[104:105], v[104:105], v[148:149]
	v_pk_fma_f32 v[110:111], v[102:103], v[102:103], v[110:111]
	s_waitcnt lgkmcnt(0)
	v_lshlrev_b64 v[116:117], 12, v[182:183]
	v_pk_fma_f32 v[110:111], v[104:105], v[104:105], v[110:111]
	v_cvt_pk_bf16_f32 v100, v100, v101
	v_cvt_pk_bf16_f32 v101, v118, v119
	s_nop 0
	v_add_f32_e32 v112, v110, v111
	ds_bpermute_b32 v113, v187, v112
	v_lshl_add_u64 v[110:111], v[116:117], 1, s[96:97]
	v_lshl_add_u64 v[110:111], v[172:173], 1, v[110:111]
	global_store_dwordx4 v[110:111], v[98:101], off sc1
	s_waitcnt lgkmcnt(0)
	s_nop 0
	v_add_f32_e32 v98, v112, v113
	ds_bpermute_b32 v99, v114, v98
	v_cvt_pk_bf16_f32 v100, v108, v109
	v_cvt_pk_bf16_f32 v101, v106, v107
	v_cvt_pk_bf16_f32 v102, v102, v103
	v_cvt_pk_bf16_f32 v103, v104, v105
	global_store_dwordx4 v[110:111], v[100:103], off offset:256 sc1
	s_and_saveexec_b64 s[20:21], s[0:1]
	s_cbranch_execz .LBB0_1046
	s_waitcnt lgkmcnt(0)
	v_add_f32_e32 v98, v98, v99
	v_fma_f32 v98, v98, s64, 0.5
	v_trunc_f32_e32 v98, v98
	v_mul_f32_e32 v99, 0x2f800000, v98
	v_floor_f32_e32 v99, v99
	v_fmac_f32_e32 v98, 0xcf800000, v99
	v_cvt_u32_f32_e32 v98, v98
	v_cvt_u32_f32_e32 v99, v99
	v_lshl_add_u64 v[100:101], v[182:183], 3, s[4:5]
	global_atomic_add_x2 v[100:101], v[98:99], off
; __device__ __forceinline__ unsigned cvt_pk_bf16(float lo, float hi) { unsigned r; asm volatile("v_cvt_pk_bf16_f32 %0, %1, %2" : "=v"(r) : "v"(lo), "v"(hi)); return r; }
; __device__ __forceinline__ unsigned cvt_pk_bf16(float lo, float hi) { unsigned r; asm volatile("v_cvt_pk_bf16_f32 %0, %1, %2" : "=v"(r) : "v"(lo), "v"(hi)); return r; }
;     __device__ __forceinline__ void operator()(const f32x4 (&acc)[2][2][4][2], const Unit& u, int wr, int wc, int fr, int fq) const {
;     ...
;                 for (int bj = 0; bj < 2; ++bj) { const size_t off = (size_t)(row0 + ai * HALF + m * 16) * ldc + col0 + bj * HALF;
;                     if (BASE_F32) { const float* bp = (const float*)base + off; b0[m][bj] = *(const f32x4*)bp; b1[m][bj] = *(const f32x4*)(bp + 4); }
;                     else { const u32x4 r = *(const u32x4*)((const bf16_t*)base + off);
;                         b0[m][bj] = (f32x4){__uint_as_float(r.x << 16), __uint_as_float(r.x & 0xffff0000u), __uint_as_float(r.y << 16), __uint_as_float(r.y & 0xffff0000u)};
;                         b1[m][bj] = (f32x4){__uint_as_float(r.z << 16), __uint_as_float(r.z & 0xffff0000u), __uint_as_float(r.w << 16), __uint_as_float(r.w & 0xffff0000u)}; } }
; #pragma unroll
;             for (int m = 0; m < 4; ++m) { const int row = row0 + ai * HALF + m * 16; const size_t off = (size_t)row * ldc + col0; f32x2 q2 = {0.f, 0.f};
; #pragma unroll
;                 for (int bj = 0; bj < 2; ++bj) { const f32x4 v0 = acc[ai][bj][m][0] + b0[m][bj], v1 = acc[ai][bj][m][1] + b1[m][bj];
;                     { const f32x2 e0 = {v0[0], v0[1]}, e1 = {v0[2], v0[3]}, e2 = {v1[0], v1[1]}, e3 = {v1[2], v1[3]}; q2 = e0 * e0 + q2; q2 = e1 * e1 + q2; q2 = e2 * e2 + q2; q2 = e3 * e3 + q2; }
;                     u32x4 w; w.x = cvt_pk_bf16(v0[0], v0[1]); w.y = cvt_pk_bf16(v0[2], v0[3]); w.z = cvt_pk_bf16(v1[0], v1[1]); w.w = cvt_pk_bf16(v1[2], v1[3]);
;                     *(u32x4*)(out + off + bj * HALF) = w; }
;                 float q = q2.x + q2.y; q += __shfl_xor(q, 16); q += __shfl_xor(q, 32);
;                 if (fq == 0) atomicAdd(ssq + row, (ssq_t)(q * SSQ_FIX + 0.5f)); }
.LBB0_1046:
	s_or_b64 exec, exec, s[20:21]
	v_lshlrev_b32_e32 v102, 16, v143
	v_and_b32_e32 v103, 0xffff0000, v143
	v_lshlrev_b32_e32 v100, 16, v142
	v_and_b32_e32 v101, 0xffff0000, v142
	v_lshlrev_b32_e32 v104, 16, v144
	v_and_b32_e32 v105, 0xffff0000, v144
	v_lshlrev_b32_e32 v106, 16, v145
	v_and_b32_e32 v107, 0xffff0000, v145
	v_pk_add_f32 v[92:93], v[92:93], v[102:103]
	v_pk_add_f32 v[90:91], v[90:91], v[100:101]
	v_pk_add_f32 v[100:101], v[84:85], v[106:107]
	v_pk_add_f32 v[84:85], v[82:83], v[104:105]
	v_pk_mul_f32 v[82:83], v[92:93], v[92:93]
	v_lshlrev_b32_e32 v108, 16, v138
	v_pk_fma_f32 v[82:83], v[90:91], v[90:91], v[82:83]
	v_and_b32_e32 v109, 0xffff0000, v138
	v_pk_fma_f32 v[82:83], v[84:85], v[84:85], v[82:83]
	v_lshlrev_b32_e32 v110, 16, v139
	v_and_b32_e32 v111, 0xffff0000, v139
	v_pk_fma_f32 v[102:103], v[100:101], v[100:101], v[82:83]
	v_cvt_pk_bf16_f32 v82, v90, v91
	v_cvt_pk_bf16_f32 v83, v92, v93
	v_pk_add_f32 v[92:93], v[94:95], v[108:109]
	v_lshlrev_b32_e32 v112, 16, v140
	v_and_b32_e32 v113, 0xffff0000, v140
	v_pk_add_f32 v[90:91], v[96:97], v[110:111]
	v_pk_fma_f32 v[94:95], v[92:93], v[92:93], v[102:103]
	v_lshlrev_b32_e32 v116, 16, v141
	v_and_b32_e32 v117, 0xffff0000, v141
	v_pk_add_f32 v[86:87], v[86:87], v[112:113]
	v_pk_fma_f32 v[94:95], v[90:91], v[90:91], v[94:95]
	v_pk_add_f32 v[88:89], v[88:89], v[116:117]
	v_pk_fma_f32 v[94:95], v[86:87], v[86:87], v[94:95]
	s_waitcnt lgkmcnt(0)
	v_lshlrev_b64 v[98:99], 12, v[180:181]
	v_pk_fma_f32 v[94:95], v[88:89], v[88:89], v[94:95]
	v_cvt_pk_bf16_f32 v84, v84, v85
	v_cvt_pk_bf16_f32 v85, v100, v101
	s_nop 0
	v_add_f32_e32 v96, v94, v95
	ds_bpermute_b32 v97, v187, v96
	v_lshl_add_u64 v[94:95], v[98:99], 1, s[96:97]
	v_lshl_add_u64 v[94:95], v[172:173], 1, v[94:95]
	global_store_dwordx4 v[94:95], v[82:85], off sc1
	s_waitcnt lgkmcnt(0)
	s_nop 0
	v_add_f32_e32 v82, v96, v97
	ds_bpermute_b32 v83, v114, v82
	v_cvt_pk_bf16_f32 v84, v92, v93
	v_cvt_pk_bf16_f32 v85, v90, v91
	v_cvt_pk_bf16_f32 v86, v86, v87
	v_cvt_pk_bf16_f32 v87, v88, v89
	global_store_dwordx4 v[94:95], v[84:87], off offset:256 sc1
	s_and_saveexec_b64 s[20:21], s[0:1]
	s_cbranch_execz .LBB0_1048
	s_waitcnt lgkmcnt(0)
	v_add_f32_e32 v82, v82, v83
	v_fma_f32 v82, v82, s64, 0.5
	v_trunc_f32_e32 v82, v82
	v_mul_f32_e32 v83, 0x2f800000, v82
	v_floor_f32_e32 v83, v83
	v_fmac_f32_e32 v82, 0xcf800000, v83
	v_cvt_u32_f32_e32 v82, v82
	v_cvt_u32_f32_e32 v83, v83
	v_lshl_add_u64 v[84:85], v[180:181], 3, s[4:5]
	global_atomic_add_x2 v[84:85], v[82:83], off
.LBB0_1048:
	s_or_b64 exec, exec, s[20:21]
	v_lshlrev_b32_e32 v86, 16, v135
	v_and_b32_e32 v87, 0xffff0000, v135
	v_lshlrev_b32_e32 v84, 16, v134
	v_and_b32_e32 v85, 0xffff0000, v134
	v_lshlrev_b32_e32 v88, 16, v136
	v_and_b32_e32 v89, 0xffff0000, v136
	v_lshlrev_b32_e32 v90, 16, v137
	v_and_b32_e32 v91, 0xffff0000, v137
	v_pk_add_f32 v[76:77], v[76:77], v[86:87]
	v_pk_add_f32 v[74:75], v[74:75], v[84:85]
	v_pk_add_f32 v[84:85], v[68:69], v[90:91]
	v_pk_add_f32 v[68:69], v[66:67], v[88:89]
	v_pk_mul_f32 v[66:67], v[76:77], v[76:77]
	v_lshlrev_b32_e32 v92, 16, v130
	v_pk_fma_f32 v[66:67], v[74:75], v[74:75], v[66:67]
	v_and_b32_e32 v93, 0xffff0000, v130
	v_pk_fma_f32 v[66:67], v[68:69], v[68:69], v[66:67]
	v_lshlrev_b32_e32 v94, 16, v131
	v_and_b32_e32 v95, 0xffff0000, v131
	v_pk_fma_f32 v[86:87], v[84:85], v[84:85], v[66:67]
	v_cvt_pk_bf16_f32 v66, v74, v75
	v_cvt_pk_bf16_f32 v67, v76, v77
	v_pk_add_f32 v[76:77], v[78:79], v[92:93]
	v_lshlrev_b32_e32 v96, 16, v132
	v_and_b32_e32 v97, 0xffff0000, v132
	v_pk_add_f32 v[74:75], v[80:81], v[94:95]
	v_pk_fma_f32 v[78:79], v[76:77], v[76:77], v[86:87]
	v_lshlrev_b32_e32 v98, 16, v133
	v_and_b32_e32 v99, 0xffff0000, v133
	v_pk_add_f32 v[70:71], v[70:71], v[96:97]
	v_pk_fma_f32 v[78:79], v[74:75], v[74:75], v[78:79]
	v_pk_add_f32 v[72:73], v[72:73], v[98:99]
	v_pk_fma_f32 v[78:79], v[70:71], v[70:71], v[78:79]
	s_waitcnt lgkmcnt(0)
	v_lshlrev_b64 v[82:83], 12, v[178:179]
	v_pk_fma_f32 v[78:79], v[72:73], v[72:73], v[78:79]
	v_cvt_pk_bf16_f32 v68, v68, v69
	v_cvt_pk_bf16_f32 v69, v84, v85
	s_nop 0
	v_add_f32_e32 v80, v78, v79
	ds_bpermute_b32 v81, v187, v80
	v_lshl_add_u64 v[78:79], v[82:83], 1, s[96:97]
	v_lshl_add_u64 v[78:79], v[172:173], 1, v[78:79]
	global_store_dwordx4 v[78:79], v[66:69], off sc1
	s_waitcnt lgkmcnt(0)
	s_nop 0
	v_add_f32_e32 v66, v80, v81
	ds_bpermute_b32 v67, v114, v66
	v_cvt_pk_bf16_f32 v68, v76, v77
	v_cvt_pk_bf16_f32 v69, v74, v75
	v_cvt_pk_bf16_f32 v70, v70, v71
	v_cvt_pk_bf16_f32 v71, v72, v73
	global_store_dwordx4 v[78:79], v[68:71], off offset:256 sc1
	s_and_saveexec_b64 s[20:21], s[0:1]
	s_cbranch_execz .LBB0_1050
	s_waitcnt lgkmcnt(0)
	v_add_f32_e32 v66, v66, v67
	v_fma_f32 v66, v66, s64, 0.5
	v_trunc_f32_e32 v66, v66
	v_mul_f32_e32 v67, 0x2f800000, v66
	v_floor_f32_e32 v67, v67
	v_fmac_f32_e32 v66, 0xcf800000, v67
	v_cvt_u32_f32_e32 v66, v66
	v_cvt_u32_f32_e32 v67, v67
	v_lshl_add_u64 v[68:69], v[178:179], 3, s[4:5]
	global_atomic_add_x2 v[68:69], v[66:67], off
; __device__ __forceinline__ unsigned cvt_pk_bf16(float lo, float hi) { unsigned r; asm volatile("v_cvt_pk_bf16_f32 %0, %1, %2" : "=v"(r) : "v"(lo), "v"(hi)); return r; }
; __device__ __forceinline__ unsigned cvt_pk_bf16(float lo, float hi) { unsigned r; asm volatile("v_cvt_pk_bf16_f32 %0, %1, %2" : "=v"(r) : "v"(lo), "v"(hi)); return r; }
;     __device__ __forceinline__ void operator()(const f32x4 (&acc)[2][2][4][2], const Unit& u, int wr, int wc, int fr, int fq) const {
;     ...
;                 for (int bj = 0; bj < 2; ++bj) { const size_t off = (size_t)(row0 + ai * HALF + m * 16) * ldc + col0 + bj * HALF;
;                     if (BASE_F32) { const float* bp = (const float*)base + off; b0[m][bj] = *(const f32x4*)bp; b1[m][bj] = *(const f32x4*)(bp + 4); }
;                     else { const u32x4 r = *(const u32x4*)((const bf16_t*)base + off);
;                         b0[m][bj] = (f32x4){__uint_as_float(r.x << 16), __uint_as_float(r.x & 0xffff0000u), __uint_as_float(r.y << 16), __uint_as_float(r.y & 0xffff0000u)};
;                         b1[m][bj] = (f32x4){__uint_as_float(r.z << 16), __uint_as_float(r.z & 0xffff0000u), __uint_as_float(r.w << 16), __uint_as_float(r.w & 0xffff0000u)}; } }
; #pragma unroll
;             for (int m = 0; m < 4; ++m) { const int row = row0 + ai * HALF + m * 16; const size_t off = (size_t)row * ldc + col0; f32x2 q2 = {0.f, 0.f};
; #pragma unroll
;                 for (int bj = 0; bj < 2; ++bj) { const f32x4 v0 = acc[ai][bj][m][0] + b0[m][bj], v1 = acc[ai][bj][m][1] + b1[m][bj];
;                     { const f32x2 e0 = {v0[0], v0[1]}, e1 = {v0[2], v0[3]}, e2 = {v1[0], v1[1]}, e3 = {v1[2], v1[3]}; q2 = e0 * e0 + q2; q2 = e1 * e1 + q2; q2 = e2 * e2 + q2; q2 = e3 * e3 + q2; }
;                     u32x4 w; w.x = cvt_pk_bf16(v0[0], v0[1]); w.y = cvt_pk_bf16(v0[2], v0[3]); w.z = cvt_pk_bf16(v1[0], v1[1]); w.w = cvt_pk_bf16(v1[2], v1[3]);
;                     *(u32x4*)(out + off + bj * HALF) = w; }
;                 float q = q2.x + q2.y; q += __shfl_xor(q, 16); q += __shfl_xor(q, 32);
;                 if (fq == 0) atomicAdd(ssq + row, (ssq_t)(q * SSQ_FIX + 0.5f)); }
.LBB0_1050:
	s_or_b64 exec, exec, s[20:21]
	v_add_u32_e32 v96, 0x80, v176
	v_ashrrev_i32_e32 v97, 31, v96
	v_lshlrev_b64 v[106:107], 13, v[96:97]
	s_waitcnt lgkmcnt(0)
	v_lshl_add_u64 v[66:67], v[174:175], 0, v[106:107]
	global_load_dwordx4 v[98:101], v[66:67], off
	global_load_dwordx4 v[102:105], v[66:67], off offset:256
	v_add_u32_e32 v94, 0x90, v176
	v_add_u32_e32 v92, 0xa0, v176
	v_add_u32_e32 v90, 0xb0, v176
	v_ashrrev_i32_e32 v95, 31, v94
	v_ashrrev_i32_e32 v93, 31, v92
	v_ashrrev_i32_e32 v91, 31, v90
	v_lshlrev_b64 v[66:67], 13, v[94:95]
	v_lshlrev_b64 v[68:69], 13, v[92:93]
	v_lshlrev_b64 v[70:71], 13, v[90:91]
	v_lshl_add_u64 v[66:67], v[174:175], 0, v[66:67]
	v_lshl_add_u64 v[68:69], v[174:175], 0, v[68:69]
	v_lshl_add_u64 v[108:109], v[174:175], 0, v[70:71]
	global_load_dwordx4 v[86:89], v[66:67], off
	global_load_dwordx4 v[82:85], v[66:67], off offset:256
	global_load_dwordx4 v[78:81], v[68:69], off
	global_load_dwordx4 v[74:77], v[68:69], off offset:256
	global_load_dwordx4 v[70:73], v[108:109], off
	s_nop 0
	global_load_dwordx4 v[66:69], v[108:109], off offset:256
	s_waitcnt vmcnt(7)
	v_lshlrev_b32_e32 v108, 16, v98
	v_and_b32_e32 v109, 0xffff0000, v98
	v_lshlrev_b32_e32 v98, 16, v99
	v_and_b32_e32 v99, 0xffff0000, v99
	s_waitcnt vmcnt(6)
	v_lshlrev_b32_e32 v112, 16, v102
	v_and_b32_e32 v113, 0xffff0000, v102
	v_lshlrev_b32_e32 v102, 16, v103
	v_and_b32_e32 v103, 0xffff0000, v103
	v_pk_add_f32 v[60:61], v[60:61], v[98:99]
	v_lshlrev_b32_e32 v110, 16, v100
	v_and_b32_e32 v111, 0xffff0000, v100
	v_lshlrev_b32_e32 v100, 16, v101
	v_and_b32_e32 v101, 0xffff0000, v101
	v_lshlrev_b32_e32 v116, 16, v104
	v_and_b32_e32 v117, 0xffff0000, v104
	v_lshlrev_b32_e32 v104, 16, v105
	v_and_b32_e32 v105, 0xffff0000, v105
	v_pk_add_f32 v[58:59], v[58:59], v[108:109]
	v_pk_add_f32 v[64:65], v[64:65], v[102:103]
	v_pk_mul_f32 v[102:103], v[60:61], v[60:61]
	v_pk_add_f32 v[56:57], v[56:57], v[100:101]
	v_pk_add_f32 v[98:99], v[54:55], v[110:111]
	v_pk_add_f32 v[100:101], v[52:53], v[104:105]
	v_cvt_pk_bf16_f32 v52, v58, v59
	v_pk_fma_f32 v[58:59], v[58:59], v[58:59], v[102:103]
	v_pk_add_f32 v[62:63], v[62:63], v[112:113]
	v_pk_fma_f32 v[58:59], v[98:99], v[98:99], v[58:59]
	v_cvt_pk_bf16_f32 v53, v60, v61
	v_cvt_pk_bf16_f32 v54, v98, v99
	v_cvt_pk_bf16_f32 v55, v56, v57
	s_nop 0
	v_pk_fma_f32 v[56:57], v[56:57], v[56:57], v[58:59]
	v_pk_add_f32 v[58:59], v[50:51], v[116:117]
	v_pk_fma_f32 v[50:51], v[62:63], v[62:63], v[56:57]
	s_nop 0
	v_pk_fma_f32 v[50:51], v[64:65], v[64:65], v[50:51]
	s_nop 0
	v_pk_fma_f32 v[50:51], v[58:59], v[58:59], v[50:51]
	s_nop 0
	v_pk_fma_f32 v[50:51], v[100:101], v[100:101], v[50:51]
	s_nop 0
	v_add_f32_e32 v60, v50, v51
	ds_bpermute_b32 v61, v187, v60
	v_lshl_add_u64 v[50:51], s[96:97], 0, v[106:107]
	v_lshl_add_u64 v[56:57], v[172:173], 1, v[50:51]
	global_store_dwordx4 v[56:57], v[52:55], off sc1
	s_waitcnt lgkmcnt(0)
	v_add_f32_e32 v50, v60, v61
	ds_bpermute_b32 v51, v114, v50
	v_cvt_pk_bf16_f32 v52, v62, v63
	v_cvt_pk_bf16_f32 v53, v64, v65
	v_cvt_pk_bf16_f32 v54, v58, v59
	v_cvt_pk_bf16_f32 v55, v100, v101
	global_store_dwordx4 v[56:57], v[52:55], off offset:256 sc1
	s_and_saveexec_b64 s[20:21], s[0:1]
	s_cbranch_execz .LBB0_1052
	s_waitcnt lgkmcnt(0)
	v_add_f32_e32 v50, v50, v51
	v_fma_f32 v50, v50, s64, 0.5
	v_trunc_f32_e32 v50, v50
	v_mul_f32_e32 v51, 0x2f800000, v50
	v_floor_f32_e32 v51, v51
	v_fmac_f32_e32 v50, 0xcf800000, v51
	v_cvt_u32_f32_e32 v50, v50
	v_cvt_u32_f32_e32 v51, v51
	v_lshl_add_u64 v[52:53], v[96:97], 3, s[4:5]
	global_atomic_add_x2 v[52:53], v[50:51], off
.LBB0_1052:
	s_or_b64 exec, exec, s[20:21]
	s_waitcnt vmcnt(7)
	v_lshlrev_b32_e32 v54, 16, v87
	v_and_b32_e32 v55, 0xffff0000, v87
	v_lshlrev_b32_e32 v52, 16, v86
	v_and_b32_e32 v53, 0xffff0000, v86
	v_lshlrev_b32_e32 v56, 16, v88
	v_and_b32_e32 v57, 0xffff0000, v88
	v_lshlrev_b32_e32 v58, 16, v89
	v_and_b32_e32 v59, 0xffff0000, v89
	v_pk_add_f32 v[44:45], v[44:45], v[54:55]
	v_pk_add_f32 v[42:43], v[42:43], v[52:53]
	v_pk_add_f32 v[52:53], v[36:37], v[58:59]
	v_pk_add_f32 v[36:37], v[34:35], v[56:57]
	v_pk_mul_f32 v[34:35], v[44:45], v[44:45]
	s_waitcnt vmcnt(6)
	v_lshlrev_b32_e32 v60, 16, v82
	v_pk_fma_f32 v[34:35], v[42:43], v[42:43], v[34:35]
	v_and_b32_e32 v61, 0xffff0000, v82
	v_pk_fma_f32 v[34:35], v[36:37], v[36:37], v[34:35]
	v_lshlrev_b32_e32 v62, 16, v83
	v_and_b32_e32 v63, 0xffff0000, v83
	v_pk_fma_f32 v[54:55], v[52:53], v[52:53], v[34:35]
	v_cvt_pk_bf16_f32 v34, v42, v43
	v_cvt_pk_bf16_f32 v35, v44, v45
	v_pk_add_f32 v[44:45], v[46:47], v[60:61]
	v_lshlrev_b32_e32 v64, 16, v84
	v_and_b32_e32 v65, 0xffff0000, v84
	v_pk_add_f32 v[42:43], v[48:49], v[62:63]
	v_pk_fma_f32 v[46:47], v[44:45], v[44:45], v[54:55]
	v_lshlrev_b32_e32 v82, 16, v85
	v_and_b32_e32 v83, 0xffff0000, v85
	v_pk_add_f32 v[38:39], v[38:39], v[64:65]
	v_pk_fma_f32 v[46:47], v[42:43], v[42:43], v[46:47]
	v_pk_add_f32 v[40:41], v[40:41], v[82:83]
	v_pk_fma_f32 v[46:47], v[38:39], v[38:39], v[46:47]
	s_waitcnt lgkmcnt(0)
	v_lshlrev_b64 v[50:51], 12, v[94:95]
	v_pk_fma_f32 v[46:47], v[40:41], v[40:41], v[46:47]
	v_cvt_pk_bf16_f32 v36, v36, v37
	v_cvt_pk_bf16_f32 v37, v52, v53
	s_nop 0
	v_add_f32_e32 v48, v46, v47
	ds_bpermute_b32 v49, v187, v48
	v_lshl_add_u64 v[46:47], v[50:51], 1, s[96:97]
	v_lshl_add_u64 v[46:47], v[172:173], 1, v[46:47]
	global_store_dwordx4 v[46:47], v[34:37], off sc1
	s_waitcnt lgkmcnt(0)
	s_nop 0
	v_add_f32_e32 v34, v48, v49
	ds_bpermute_b32 v35, v114, v34
	v_cvt_pk_bf16_f32 v36, v44, v45
	v_cvt_pk_bf16_f32 v37, v42, v43
	v_cvt_pk_bf16_f32 v38, v38, v39
	v_cvt_pk_bf16_f32 v39, v40, v41
	global_store_dwordx4 v[46:47], v[36:39], off offset:256 sc1
	s_and_saveexec_b64 s[20:21], s[0:1]
	s_cbranch_execz .LBB0_1054
	s_waitcnt lgkmcnt(0)
	v_add_f32_e32 v34, v34, v35
	v_fma_f32 v34, v34, s64, 0.5
	v_trunc_f32_e32 v34, v34
	v_mul_f32_e32 v35, 0x2f800000, v34
	v_floor_f32_e32 v35, v35
	v_fmac_f32_e32 v34, 0xcf800000, v35
	v_cvt_u32_f32_e32 v34, v34
	v_cvt_u32_f32_e32 v35, v35
	v_lshl_add_u64 v[36:37], v[94:95], 3, s[4:5]
	global_atomic_add_x2 v[36:37], v[34:35], off
; __device__ __forceinline__ unsigned cvt_pk_bf16(float lo, float hi) { unsigned r; asm volatile("v_cvt_pk_bf16_f32 %0, %1, %2" : "=v"(r) : "v"(lo), "v"(hi)); return r; }
; __device__ __forceinline__ unsigned cvt_pk_bf16(float lo, float hi) { unsigned r; asm volatile("v_cvt_pk_bf16_f32 %0, %1, %2" : "=v"(r) : "v"(lo), "v"(hi)); return r; }
;     __device__ __forceinline__ void operator()(const f32x4 (&acc)[2][2][4][2], const Unit& u, int wr, int wc, int fr, int fq) const {
;     ...
;                 for (int bj = 0; bj < 2; ++bj) { const size_t off = (size_t)(row0 + ai * HALF + m * 16) * ldc + col0 + bj * HALF;
;                     if (BASE_F32) { const float* bp = (const float*)base + off; b0[m][bj] = *(const f32x4*)bp; b1[m][bj] = *(const f32x4*)(bp + 4); }
;                     else { const u32x4 r = *(const u32x4*)((const bf16_t*)base + off);
;                         b0[m][bj] = (f32x4){__uint_as_float(r.x << 16), __uint_as_float(r.x & 0xffff0000u), __uint_as_float(r.y << 16), __uint_as_float(r.y & 0xffff0000u)};
;                         b1[m][bj] = (f32x4){__uint_as_float(r.z << 16), __uint_as_float(r.z & 0xffff0000u), __uint_as_float(r.w << 16), __uint_as_float(r.w & 0xffff0000u)}; } }
; #pragma unroll
;             for (int m = 0; m < 4; ++m) { const int row = row0 + ai * HALF + m * 16; const size_t off = (size_t)row * ldc + col0; f32x2 q2 = {0.f, 0.f};
; #pragma unroll
;                 for (int bj = 0; bj < 2; ++bj) { const f32x4 v0 = acc[ai][bj][m][0] + b0[m][bj], v1 = acc[ai][bj][m][1] + b1[m][bj];
;                     { const f32x2 e0 = {v0[0], v0[1]}, e1 = {v0[2], v0[3]}, e2 = {v1[0], v1[1]}, e3 = {v1[2], v1[3]}; q2 = e0 * e0 + q2; q2 = e1 * e1 + q2; q2 = e2 * e2 + q2; q2 = e3 * e3 + q2; }
;                     u32x4 w; w.x = cvt_pk_bf16(v0[0], v0[1]); w.y = cvt_pk_bf16(v0[2], v0[3]); w.z = cvt_pk_bf16(v1[0], v1[1]); w.w = cvt_pk_bf16(v1[2], v1[3]);
;                     *(u32x4*)(out + off + bj * HALF) = w; }
;                 float q = q2.x + q2.y; q += __shfl_xor(q, 16); q += __shfl_xor(q, 32);
;                 if (fq == 0) atomicAdd(ssq + row, (ssq_t)(q * SSQ_FIX + 0.5f)); }
.LBB0_1054:
	s_or_b64 exec, exec, s[20:21]
	s_waitcnt vmcnt(7)
	v_lshlrev_b32_e32 v38, 16, v79
	v_and_b32_e32 v39, 0xffff0000, v79
	v_lshlrev_b32_e32 v36, 16, v78
	v_and_b32_e32 v37, 0xffff0000, v78
	v_lshlrev_b32_e32 v40, 16, v80
	v_and_b32_e32 v41, 0xffff0000, v80
	v_lshlrev_b32_e32 v42, 16, v81
	v_and_b32_e32 v43, 0xffff0000, v81
	v_pk_add_f32 v[28:29], v[28:29], v[38:39]
	v_pk_add_f32 v[26:27], v[26:27], v[36:37]
	v_pk_add_f32 v[36:37], v[20:21], v[42:43]
	v_pk_add_f32 v[20:21], v[18:19], v[40:41]
	v_pk_mul_f32 v[18:19], v[28:29], v[28:29]
	s_waitcnt vmcnt(6)
	v_lshlrev_b32_e32 v44, 16, v74
	v_pk_fma_f32 v[18:19], v[26:27], v[26:27], v[18:19]
	v_and_b32_e32 v45, 0xffff0000, v74
	v_pk_fma_f32 v[18:19], v[20:21], v[20:21], v[18:19]
	v_lshlrev_b32_e32 v46, 16, v75
	v_and_b32_e32 v47, 0xffff0000, v75
	v_pk_fma_f32 v[38:39], v[36:37], v[36:37], v[18:19]
	v_cvt_pk_bf16_f32 v18, v26, v27
	v_cvt_pk_bf16_f32 v19, v28, v29
	v_pk_add_f32 v[28:29], v[30:31], v[44:45]
	v_lshlrev_b32_e32 v48, 16, v76
	v_and_b32_e32 v49, 0xffff0000, v76
	v_pk_add_f32 v[26:27], v[32:33], v[46:47]
	v_pk_fma_f32 v[30:31], v[28:29], v[28:29], v[38:39]
	v_lshlrev_b32_e32 v50, 16, v77
	v_and_b32_e32 v51, 0xffff0000, v77
	v_pk_add_f32 v[22:23], v[22:23], v[48:49]
	v_pk_fma_f32 v[30:31], v[26:27], v[26:27], v[30:31]
	v_pk_add_f32 v[24:25], v[24:25], v[50:51]
	v_pk_fma_f32 v[30:31], v[22:23], v[22:23], v[30:31]
	s_waitcnt lgkmcnt(0)
	v_lshlrev_b64 v[34:35], 12, v[92:93]
	v_pk_fma_f32 v[30:31], v[24:25], v[24:25], v[30:31]
	v_cvt_pk_bf16_f32 v20, v20, v21
	v_cvt_pk_bf16_f32 v21, v36, v37
	s_nop 0
	v_add_f32_e32 v32, v30, v31
	ds_bpermute_b32 v33, v187, v32
	v_lshl_add_u64 v[30:31], v[34:35], 1, s[96:97]
	v_lshl_add_u64 v[30:31], v[172:173], 1, v[30:31]
	global_store_dwordx4 v[30:31], v[18:21], off sc1
	s_waitcnt lgkmcnt(0)
	s_nop 0
	v_add_f32_e32 v18, v32, v33
	ds_bpermute_b32 v19, v114, v18
	v_cvt_pk_bf16_f32 v20, v28, v29
	v_cvt_pk_bf16_f32 v21, v26, v27
	v_cvt_pk_bf16_f32 v22, v22, v23
	v_cvt_pk_bf16_f32 v23, v24, v25
	global_store_dwordx4 v[30:31], v[20:23], off offset:256 sc1
	s_and_saveexec_b64 s[20:21], s[0:1]
	s_cbranch_execz .LBB0_1056
	s_waitcnt lgkmcnt(0)
	v_add_f32_e32 v18, v18, v19
	v_fma_f32 v18, v18, s64, 0.5
	v_trunc_f32_e32 v18, v18
	v_mul_f32_e32 v19, 0x2f800000, v18
	v_floor_f32_e32 v19, v19
	v_fmac_f32_e32 v18, 0xcf800000, v19
	v_cvt_u32_f32_e32 v18, v18
	v_cvt_u32_f32_e32 v19, v19
	v_lshl_add_u64 v[20:21], v[92:93], 3, s[4:5]
	global_atomic_add_x2 v[20:21], v[18:19], off
.LBB0_1056:
	s_or_b64 exec, exec, s[20:21]
	s_waitcnt vmcnt(7)
	v_lshlrev_b32_e32 v22, 16, v71
	v_and_b32_e32 v23, 0xffff0000, v71
	v_lshlrev_b32_e32 v20, 16, v70
	v_and_b32_e32 v21, 0xffff0000, v70
	v_lshlrev_b32_e32 v24, 16, v72
	v_and_b32_e32 v25, 0xffff0000, v72
	v_lshlrev_b32_e32 v26, 16, v73
	v_and_b32_e32 v27, 0xffff0000, v73
	v_pk_add_f32 v[8:9], v[8:9], v[22:23]
	v_pk_add_f32 v[6:7], v[6:7], v[20:21]
	v_pk_add_f32 v[20:21], v[4:5], v[26:27]
	v_pk_add_f32 v[4:5], v[2:3], v[24:25]
	v_pk_mul_f32 v[2:3], v[8:9], v[8:9]
	s_waitcnt vmcnt(6)
	v_lshlrev_b32_e32 v28, 16, v66
	v_pk_fma_f32 v[2:3], v[6:7], v[6:7], v[2:3]
	v_and_b32_e32 v29, 0xffff0000, v66
	v_pk_fma_f32 v[2:3], v[4:5], v[4:5], v[2:3]
	v_lshlrev_b32_e32 v30, 16, v67
	v_and_b32_e32 v31, 0xffff0000, v67
	v_lshlrev_b32_e32 v32, 16, v68
	v_and_b32_e32 v33, 0xffff0000, v68
	v_pk_fma_f32 v[22:23], v[20:21], v[20:21], v[2:3]
	v_cvt_pk_bf16_f32 v2, v6, v7
	v_cvt_pk_bf16_f32 v3, v8, v9
	v_pk_add_f32 v[8:9], v[10:11], v[28:29]
	v_pk_add_f32 v[6:7], v[12:13], v[30:31]
	v_pk_add_f32 v[12:13], v[14:15], v[32:33]
	v_pk_fma_f32 v[14:15], v[8:9], v[8:9], v[22:23]
	v_lshlrev_b32_e32 v34, 16, v69
	v_and_b32_e32 v35, 0xffff0000, v69
	v_pk_fma_f32 v[14:15], v[6:7], v[6:7], v[14:15]
	v_pk_add_f32 v[10:11], v[16:17], v[34:35]
	v_pk_fma_f32 v[14:15], v[12:13], v[12:13], v[14:15]
	s_waitcnt lgkmcnt(0)
	v_lshlrev_b64 v[18:19], 12, v[90:91]
	v_pk_fma_f32 v[14:15], v[10:11], v[10:11], v[14:15]
	v_cvt_pk_bf16_f32 v4, v4, v5
	v_cvt_pk_bf16_f32 v5, v20, v21
	s_nop 0
	v_add_f32_e32 v16, v14, v15
	ds_bpermute_b32 v17, v187, v16
	v_lshl_add_u64 v[14:15], v[18:19], 1, s[96:97]
	v_lshl_add_u64 v[14:15], v[172:173], 1, v[14:15]
	global_store_dwordx4 v[14:15], v[2:5], off sc1
	s_waitcnt lgkmcnt(0)
	s_nop 0
	v_add_f32_e32 v2, v16, v17
	ds_bpermute_b32 v3, v114, v2
	v_cvt_pk_bf16_f32 v4, v8, v9
	v_cvt_pk_bf16_f32 v5, v6, v7
	v_cvt_pk_bf16_f32 v6, v12, v13
	v_cvt_pk_bf16_f32 v7, v10, v11
	global_store_dwordx4 v[14:15], v[4:7], off offset:256 sc1
	s_and_saveexec_b64 s[20:21], s[0:1]
	s_cbranch_execz .LBB0_1058
	s_waitcnt lgkmcnt(0)
	v_add_f32_e32 v2, v2, v3
	v_fma_f32 v2, v2, s64, 0.5
	v_trunc_f32_e32 v2, v2
	v_mul_f32_e32 v3, 0x2f800000, v2
	v_floor_f32_e32 v3, v3
	v_fmac_f32_e32 v2, 0xcf800000, v3
	v_cvt_u32_f32_e32 v2, v2
	v_cvt_u32_f32_e32 v3, v3
	v_lshl_add_u64 v[4:5], v[90:91], 3, s[4:5]
	global_atomic_add_x2 v[4:5], v[2:3], off

; __device__ __forceinline__ unsigned cvt_pk_bf16(float lo, float hi) { unsigned r; asm volatile("v_cvt_pk_bf16_f32 %0, %1, %2" : "=v"(r) : "v"(lo), "v"(hi)); return r; }
; __device__ __forceinline__ unsigned cvt_pk_bf16(float lo, float hi) { unsigned r; asm volatile("v_cvt_pk_bf16_f32 %0, %1, %2" : "=v"(r) : "v"(lo), "v"(hi)); return r; }
; __device__ __forceinline__ float ssq_rstd(const ssq_t* ssq, int row) { return __builtin_amdgcn_rsqf((float)ssq[row] * (SSQ_UNFIX * RMS_INV_D) + RMS_EPS); }
;     __device__ __forceinline__ void operator()(const f32x4 (&acc)[2][2][4][2], const Unit& u, int wr, int wc, int fr, int fq) const {
;     ...
;             for (int m = 0; m < 4; ++m) rs[ai][m] = ssq_rstd(ssq, row0 + ai * HALF + m * 16);
; #pragma unroll
;         for (int ai = 0; ai < 2; ++ai)
; #pragma unroll
;             for (int m = 0; m < 4; ++m) { const int row = row0 + ai * HALF + m * 16; bf16_t* rowp = O + (size_t)row * ldc + col0; float a[8];
; #pragma unroll
;                 for (int n = 0; n < 2; ++n)
; #pragma unroll
;                     for (int i = 0; i < 4; i += 2) {
;                         const f32x2 r2 = {rs[ai][m], rs[ai][m]};
;                         const f32x2 g = (f32x2){acc[ai][0][m][n][i], acc[ai][0][m][n][i + 1]} * r2, up = (f32x2){acc[ai][1][m][n][i], acc[ai][1][m][n][i + 1]} * r2;
;                         const f32x2 t = g * (f32x2){-1.4426950408889634f, -1.4426950408889634f};
;                         const f32x2 d = (f32x2){__builtin_amdgcn_exp2f(t.x), __builtin_amdgcn_exp2f(t.y)} + (f32x2){1.0f, 1.0f};
;                         const f32x2 o2 = (g * up) * (f32x2){__builtin_amdgcn_rcpf(d.x), __builtin_amdgcn_rcpf(d.y)};
;                         a[4 * n + i] = o2.x; a[4 * n + i + 1] = o2.y; }
;                 u32x4 w; w.x = cvt_pk_bf16(a[0], a[1]); w.y = cvt_pk_bf16(a[2], a[3]); w.z = cvt_pk_bf16(a[4], a[5]); w.w = cvt_pk_bf16(a[6], a[7]);
;                 *(u32x4*)rowp = w; }
.Lepi_rest_1129:
	v_add_u32_e32 v165, 0x80, v168
	v_add_u32_e32 v163, 0x90, v168
	v_add_u32_e32 v161, 0xa0, v168
	s_andn2_b64 vcc, exec, s[0:1]
	s_mov_b64 s[0:1], -1
	s_waitcnt vmcnt(0)
	v_ffbh_u32_e32 v146, v173
	v_min_u32_e32 v146, 32, v146
	v_lshlrev_b64 v[172:173], v146, v[172:173]
	v_ffbh_u32_e32 v158, v171
	v_min_u32_e32 v158, 32, v158
	v_min_u32_e32 v169, 1, v172
	v_lshlrev_b64 v[170:171], v158, v[170:171]
	v_or_b32_e32 v169, v173, v169
	v_min_u32_e32 v170, 1, v170
	v_cvt_f32_u32_e32 v169, v169
	v_ffbh_u32_e32 v150, v175
	v_ffbh_u32_e32 v152, v177
	v_ffbh_u32_e32 v154, v179
	v_ffbh_u32_e32 v162, v181
	v_or_b32_e32 v170, v171, v170
	v_min_u32_e32 v150, 32, v150
	v_min_u32_e32 v152, 32, v152
	v_min_u32_e32 v154, 32, v154
	v_min_u32_e32 v162, 32, v162
	v_cvt_f32_u32_e32 v170, v170
	v_sub_u32_e32 v146, 32, v146
	v_lshlrev_b64 v[174:175], v150, v[174:175]
	v_lshlrev_b64 v[176:177], v152, v[176:177]
	v_lshlrev_b64 v[178:179], v154, v[178:179]
	v_lshlrev_b64 v[180:181], v162, v[180:181]
	v_min_u32_e32 v172, 1, v174
	v_min_u32_e32 v174, 1, v176
	v_min_u32_e32 v176, 1, v178
	v_min_u32_e32 v178, 1, v180
	v_ldexp_f32 v146, v169, v146
	v_sub_u32_e32 v158, 32, v158
	v_or_b32_e32 v171, v181, v178
	v_fmamk_f32 v146, v146, 0x2d800000, v159
	v_cvt_f32_u32_e32 v171, v171
	v_ldexp_f32 v158, v170, v158
	v_rsq_f32_e32 v170, v146
	v_or_b32_e32 v172, v175, v172
	v_or_b32_e32 v174, v177, v174
	v_or_b32_e32 v175, v179, v176
	v_pk_mul_f32 v[122:123], v[122:123], v[170:171] op_sel_hi:[1,0]
	v_pk_mul_f32 v[124:125], v[124:125], v[170:171] op_sel_hi:[1,0]
	v_pk_mul_f32 v[176:177], v[122:123], s[10:11] op_sel_hi:[1,0]
	v_pk_mul_f32 v[178:179], v[124:125], s[10:11] op_sel_hi:[1,0]
	v_exp_f32_e32 v176, v176
	v_exp_f32_e32 v177, v177
	v_exp_f32_e32 v178, v178
	v_exp_f32_e32 v179, v179
	v_ffbh_u32_e32 v157, v183
	v_pk_add_f32 v[176:177], v[176:177], 1.0 op_sel_hi:[1,0]
	v_min_u32_e32 v157, 32, v157
	v_pk_mul_f32 v[126:127], v[126:127], v[170:171] op_sel_hi:[1,0]
	v_rcp_f32_e32 v176, v176
	v_rcp_f32_e32 v177, v177
	v_lshlrev_b64 v[182:183], v157, v[182:183]
	v_pk_mul_f32 v[122:123], v[122:123], v[126:127]
	v_pk_mul_f32 v[126:127], v[128:129], v[170:171] op_sel_hi:[1,0]
	v_pk_add_f32 v[128:129], v[178:179], 1.0 op_sel_hi:[1,0]
	v_min_u32_e32 v173, 1, v182
	v_rcp_f32_e32 v128, v128
	v_rcp_f32_e32 v129, v129
	v_or_b32_e32 v173, v183, v173
	v_pk_mul_f32 v[114:115], v[114:115], v[170:171] op_sel_hi:[1,0]
	v_cvt_f32_u32_e32 v173, v173
	v_pk_mul_f32 v[122:123], v[122:123], v[176:177]
	v_pk_mul_f32 v[176:177], v[114:115], s[10:11] op_sel_hi:[1,0]
	v_pk_mul_f32 v[124:125], v[124:125], v[126:127]
	v_exp_f32_e32 v176, v176
	v_exp_f32_e32 v177, v177
	v_pk_mul_f32 v[116:117], v[116:117], v[170:171] op_sel_hi:[1,0]
	v_ffbh_u32_e32 v167, v149
	v_cvt_f32_u32_e32 v172, v172
	v_pk_mul_f32 v[124:125], v[124:125], v[128:129]
	v_pk_mul_f32 v[128:129], v[116:117], s[10:11] op_sel_hi:[1,0]
	v_min_u32_e32 v167, 32, v167
	v_sub_u32_e32 v157, 32, v157
	v_exp_f32_e32 v128, v128
	v_exp_f32_e32 v129, v129
	v_lshlrev_b64 v[148:149], v167, v[148:149]
	v_ldexp_f32 v157, v173, v157
	v_sub_u32_e32 v150, 32, v150
	v_min_u32_e32 v148, 1, v148
	v_fmamk_f32 v146, v157, 0x2d800000, v159
	v_pk_mul_f32 v[118:119], v[118:119], v[170:171] op_sel_hi:[1,0]
	v_pk_add_f32 v[126:127], v[176:177], 1.0 op_sel_hi:[1,0]
	v_cvt_f32_u32_e32 v174, v174
	v_cvt_f32_u32_e32 v175, v175
	v_ldexp_f32 v150, v172, v150
	v_rsq_f32_e32 v172, v146
	v_or_b32_e32 v146, v149, v148
	v_pk_mul_f32 v[114:115], v[114:115], v[118:119]
	v_rcp_f32_e32 v118, v126
	v_rcp_f32_e32 v119, v127
	v_cvt_f32_u32_e32 v146, v146
	v_pk_add_f32 v[126:127], v[128:129], 1.0 op_sel_hi:[1,0]
	v_sub_u32_e32 v152, 32, v152
	v_rcp_f32_e32 v126, v126
	v_rcp_f32_e32 v127, v127
	v_sub_u32_e32 v154, 32, v154
	v_sub_u32_e32 v162, 32, v162
	v_ldexp_f32 v152, v174, v152
	v_ldexp_f32 v154, v175, v154
	v_sub_u32_e32 v148, 32, v167
	v_lshl_or_b32 v174, s63, 7, v153
	v_pk_mul_f32 v[118:119], v[114:115], v[118:119]
	v_pk_mul_f32 v[114:115], v[120:121], v[170:171] op_sel_hi:[1,0]
	v_ldexp_f32 v162, v171, v162
	v_fmamk_f32 v150, v150, 0x2d800000, v159
	v_fmamk_f32 v169, v154, 0x2d800000, v159
	v_fmamk_f32 v157, v158, 0x2d800000, v159
	v_ldexp_f32 v146, v146, v148
	v_ashrrev_i32_e32 v175, 31, v174
	v_mov_b64_e32 v[148:149], s[38:39]
	v_pk_mul_f32 v[114:115], v[116:117], v[114:115]
	v_fmamk_f32 v158, v162, 0x2d800000, v159
	v_rsq_f32_e32 v154, v150
	v_rsq_f32_e32 v162, v157
	v_rsq_f32_e32 v150, v169
	v_add_u32_e32 v157, 0xb0, v168
	v_mad_i64_i32 v[168:169], s[22:23], v168, s62, v[148:149]
	v_pk_mul_f32 v[120:121], v[114:115], v[126:127]
	v_lshlrev_b64 v[114:115], 1, v[174:175]
	v_lshl_add_u64 v[126:127], v[168:169], 0, v[114:115]
	v_cvt_pk_bf16_f32 v116, v122, v123
	v_cvt_pk_bf16_f32 v117, v124, v125
	v_pk_mul_f32 v[106:107], v[106:107], v[172:173] op_sel_hi:[1,0]
	v_cvt_pk_bf16_f32 v118, v118, v119
	v_cvt_pk_bf16_f32 v119, v120, v121
	global_store_dwordx4 v[126:127], v[116:119], off sc1
	v_pk_mul_f32 v[108:109], v[108:109], v[172:173] op_sel_hi:[1,0]
	v_pk_mul_f32 v[110:111], v[110:111], v[172:173] op_sel_hi:[1,0]
	v_pk_mul_f32 v[116:117], v[106:107], s[10:11] op_sel_hi:[1,0]
	v_pk_mul_f32 v[120:121], v[108:109], s[10:11] op_sel_hi:[1,0]
	v_exp_f32_e32 v116, v116
	v_exp_f32_e32 v117, v117
	v_exp_f32_e32 v120, v120
	v_exp_f32_e32 v121, v121
	v_pk_mul_f32 v[106:107], v[106:107], v[110:111]
	v_pk_add_f32 v[116:117], v[116:117], 1.0 op_sel_hi:[1,0]
	v_pk_mul_f32 v[110:111], v[112:113], v[172:173] op_sel_hi:[1,0]
	v_rcp_f32_e32 v116, v116
	v_rcp_f32_e32 v117, v117
	v_pk_add_f32 v[112:113], v[120:121], 1.0 op_sel_hi:[1,0]
	v_pk_mul_f32 v[98:99], v[98:99], v[172:173] op_sel_hi:[1,0]
; __device__ __forceinline__ unsigned cvt_pk_bf16(float lo, float hi) { unsigned r; asm volatile("v_cvt_pk_bf16_f32 %0, %1, %2" : "=v"(r) : "v"(lo), "v"(hi)); return r; }
; __device__ __forceinline__ unsigned cvt_pk_bf16(float lo, float hi) { unsigned r; asm volatile("v_cvt_pk_bf16_f32 %0, %1, %2" : "=v"(r) : "v"(lo), "v"(hi)); return r; }
;     __device__ __forceinline__ void operator()(const f32x4 (&acc)[2][2][4][2], const Unit& u, int wr, int wc, int fr, int fq) const {
;     ...
;                         const f32x2 r2 = {rs[ai][m], rs[ai][m]};
;                         const f32x2 g = (f32x2){acc[ai][0][m][n][i], acc[ai][0][m][n][i + 1]} * r2, up = (f32x2){acc[ai][1][m][n][i], acc[ai][1][m][n][i + 1]} * r2;
;                         const f32x2 t = g * (f32x2){-1.4426950408889634f, -1.4426950408889634f};
;                         const f32x2 d = (f32x2){__builtin_amdgcn_exp2f(t.x), __builtin_amdgcn_exp2f(t.y)} + (f32x2){1.0f, 1.0f};
;                         const f32x2 o2 = (g * up) * (f32x2){__builtin_amdgcn_rcpf(d.x), __builtin_amdgcn_rcpf(d.y)};
;                         a[4 * n + i] = o2.x; a[4 * n + i + 1] = o2.y; }
;                 u32x4 w; w.x = cvt_pk_bf16(a[0], a[1]); w.y = cvt_pk_bf16(a[2], a[3]); w.z = cvt_pk_bf16(a[4], a[5]); w.w = cvt_pk_bf16(a[6], a[7]);
;                 *(u32x4*)rowp = w; }
	v_rcp_f32_e32 v112, v112
	v_rcp_f32_e32 v113, v113
	v_pk_mul_f32 v[106:107], v[106:107], v[116:117]
	v_pk_mul_f32 v[116:117], v[98:99], s[10:11] op_sel_hi:[1,0]
	v_pk_mul_f32 v[108:109], v[108:109], v[110:111]
	v_exp_f32_e32 v116, v116
	v_exp_f32_e32 v117, v117
	v_pk_mul_f32 v[100:101], v[100:101], v[172:173] op_sel_hi:[1,0]
	v_pk_mul_f32 v[108:109], v[108:109], v[112:113]
	v_pk_mul_f32 v[112:113], v[100:101], s[10:11] op_sel_hi:[1,0]
	v_pk_mul_f32 v[102:103], v[102:103], v[172:173] op_sel_hi:[1,0]
	v_exp_f32_e32 v112, v112
	v_exp_f32_e32 v113, v113
	v_pk_add_f32 v[110:111], v[116:117], 1.0 op_sel_hi:[1,0]
	v_pk_mul_f32 v[98:99], v[98:99], v[102:103]
	v_rcp_f32_e32 v102, v110
	v_rcp_f32_e32 v103, v111
	v_pk_add_f32 v[110:111], v[112:113], 1.0 op_sel_hi:[1,0]
	v_mad_i64_i32 v[118:119], s[22:23], v166, s62, v[148:149]
	v_rcp_f32_e32 v110, v110
	v_rcp_f32_e32 v111, v111
	v_pk_mul_f32 v[102:103], v[98:99], v[102:103]
	v_pk_mul_f32 v[98:99], v[104:105], v[172:173] op_sel_hi:[1,0]
	v_pk_mul_f32 v[90:91], v[90:91], v[162:163] op_sel_hi:[1,0]
	v_pk_mul_f32 v[98:99], v[100:101], v[98:99]
	v_pk_mul_f32 v[92:93], v[92:93], v[162:163] op_sel_hi:[1,0]
	v_pk_mul_f32 v[104:105], v[98:99], v[110:111]
	v_lshl_add_u64 v[110:111], v[118:119], 0, v[114:115]
	v_cvt_pk_bf16_f32 v98, v106, v107
	v_cvt_pk_bf16_f32 v99, v108, v109
	v_cvt_pk_bf16_f32 v100, v102, v103
	v_cvt_pk_bf16_f32 v101, v104, v105
	global_store_dwordx4 v[110:111], v[98:101], off sc1
	v_pk_mul_f32 v[102:103], v[92:93], s[10:11] op_sel_hi:[1,0]
	v_pk_mul_f32 v[94:95], v[94:95], v[162:163] op_sel_hi:[1,0]
	v_pk_mul_f32 v[98:99], v[90:91], s[10:11] op_sel_hi:[1,0]
	v_exp_f32_e32 v102, v102
	v_exp_f32_e32 v98, v98
	v_exp_f32_e32 v99, v99
	v_exp_f32_e32 v103, v103
	v_pk_mul_f32 v[90:91], v[90:91], v[94:95]
	v_pk_mul_f32 v[94:95], v[96:97], v[162:163] op_sel_hi:[1,0]
	v_pk_add_f32 v[98:99], v[98:99], 1.0 op_sel_hi:[1,0]
	v_pk_add_f32 v[96:97], v[102:103], 1.0 op_sel_hi:[1,0]
	v_rcp_f32_e32 v98, v98
	v_rcp_f32_e32 v99, v99
	v_rcp_f32_e32 v96, v96
	v_rcp_f32_e32 v97, v97
	v_pk_mul_f32 v[82:83], v[82:83], v[162:163] op_sel_hi:[1,0]
	v_pk_mul_f32 v[90:91], v[90:91], v[98:99]
	v_pk_mul_f32 v[98:99], v[82:83], s[10:11] op_sel_hi:[1,0]
	v_pk_mul_f32 v[92:93], v[92:93], v[94:95]
	v_exp_f32_e32 v98, v98
	v_exp_f32_e32 v99, v99
	v_pk_mul_f32 v[84:85], v[84:85], v[162:163] op_sel_hi:[1,0]
	v_pk_mul_f32 v[92:93], v[92:93], v[96:97]
	v_pk_mul_f32 v[96:97], v[84:85], s[10:11] op_sel_hi:[1,0]
	v_pk_mul_f32 v[86:87], v[86:87], v[162:163] op_sel_hi:[1,0]
	v_exp_f32_e32 v96, v96
	v_exp_f32_e32 v97, v97
	v_pk_add_f32 v[94:95], v[98:99], 1.0 op_sel_hi:[1,0]
	v_pk_mul_f32 v[82:83], v[82:83], v[86:87]
	v_rcp_f32_e32 v86, v94
	v_rcp_f32_e32 v87, v95
	v_pk_add_f32 v[94:95], v[96:97], 1.0 op_sel_hi:[1,0]
	v_rsq_f32_e32 v158, v158
	v_rcp_f32_e32 v94, v94
	v_rcp_f32_e32 v95, v95
	v_pk_mul_f32 v[86:87], v[82:83], v[86:87]
	v_pk_mul_f32 v[82:83], v[88:89], v[162:163] op_sel_hi:[1,0]
	v_mad_i64_i32 v[100:101], s[22:23], v160, s62, v[148:149]
	v_pk_mul_f32 v[82:83], v[84:85], v[82:83]
	v_pk_mul_f32 v[74:75], v[74:75], v[158:159] op_sel_hi:[1,0]
	v_pk_mul_f32 v[88:89], v[82:83], v[94:95]
	v_lshl_add_u64 v[94:95], v[100:101], 0, v[114:115]
	v_cvt_pk_bf16_f32 v82, v90, v91
	v_cvt_pk_bf16_f32 v83, v92, v93
	v_cvt_pk_bf16_f32 v84, v86, v87
	v_cvt_pk_bf16_f32 v85, v88, v89
	global_store_dwordx4 v[94:95], v[82:85], off sc1
	v_pk_mul_f32 v[76:77], v[76:77], v[158:159] op_sel_hi:[1,0]
	v_pk_mul_f32 v[78:79], v[78:79], v[158:159] op_sel_hi:[1,0]
	v_pk_mul_f32 v[82:83], v[74:75], s[10:11] op_sel_hi:[1,0]
	v_pk_mul_f32 v[86:87], v[76:77], s[10:11] op_sel_hi:[1,0]
	v_exp_f32_e32 v82, v82
	v_exp_f32_e32 v83, v83
	v_exp_f32_e32 v86, v86
	v_exp_f32_e32 v87, v87
	v_pk_mul_f32 v[74:75], v[74:75], v[78:79]
	v_pk_add_f32 v[82:83], v[82:83], 1.0 op_sel_hi:[1,0]
	v_pk_mul_f32 v[78:79], v[80:81], v[158:159] op_sel_hi:[1,0]
	v_rcp_f32_e32 v82, v82
	v_rcp_f32_e32 v83, v83
	v_pk_add_f32 v[80:81], v[86:87], 1.0 op_sel_hi:[1,0]
	v_pk_mul_f32 v[62:63], v[62:63], v[158:159] op_sel_hi:[1,0]
	v_rcp_f32_e32 v80, v80
	v_rcp_f32_e32 v81, v81
	v_pk_mul_f32 v[74:75], v[74:75], v[82:83]
	v_pk_mul_f32 v[82:83], v[62:63], s[10:11] op_sel_hi:[1,0]
	v_pk_mul_f32 v[76:77], v[76:77], v[78:79]
	v_exp_f32_e32 v82, v82
	v_exp_f32_e32 v83, v83
	v_pk_mul_f32 v[64:65], v[64:65], v[158:159] op_sel_hi:[1,0]
	v_pk_mul_f32 v[76:77], v[76:77], v[80:81]
	v_pk_mul_f32 v[80:81], v[64:65], s[10:11] op_sel_hi:[1,0]
	v_pk_mul_f32 v[70:71], v[70:71], v[158:159] op_sel_hi:[1,0]
	v_exp_f32_e32 v80, v80
	v_exp_f32_e32 v81, v81
	v_pk_add_f32 v[78:79], v[82:83], 1.0 op_sel_hi:[1,0]
	v_pk_mul_f32 v[62:63], v[62:63], v[70:71]
	v_rcp_f32_e32 v70, v78
	v_rcp_f32_e32 v71, v79
	v_pk_add_f32 v[78:79], v[80:81], 1.0 op_sel_hi:[1,0]
	v_mad_i64_i32 v[84:85], s[22:23], v156, s62, v[148:149]
	v_rcp_f32_e32 v78, v78
	v_rcp_f32_e32 v79, v79
	v_pk_mul_f32 v[70:71], v[62:63], v[70:71]
	v_pk_mul_f32 v[62:63], v[72:73], v[158:159] op_sel_hi:[1,0]
	v_pk_mul_f32 v[58:59], v[58:59], v[154:155] op_sel_hi:[1,0]
	v_pk_mul_f32 v[62:63], v[64:65], v[62:63]
	v_pk_mul_f32 v[60:61], v[60:61], v[154:155] op_sel_hi:[1,0]
	v_pk_mul_f32 v[72:73], v[62:63], v[78:79]
	v_lshl_add_u64 v[78:79], v[84:85], 0, v[114:115]
	v_cvt_pk_bf16_f32 v62, v74, v75
	v_cvt_pk_bf16_f32 v63, v76, v77
	v_cvt_pk_bf16_f32 v64, v70, v71
	v_cvt_pk_bf16_f32 v65, v72, v73
	global_store_dwordx4 v[78:79], v[62:65], off sc1
	v_pk_mul_f32 v[70:71], v[60:61], s[10:11] op_sel_hi:[1,0]
	v_pk_mul_f32 v[66:67], v[66:67], v[154:155] op_sel_hi:[1,0]
	v_pk_mul_f32 v[62:63], v[58:59], s[10:11] op_sel_hi:[1,0]
	v_exp_f32_e32 v70, v70
	v_exp_f32_e32 v62, v62
; __device__ __forceinline__ unsigned cvt_pk_bf16(float lo, float hi) { unsigned r; asm volatile("v_cvt_pk_bf16_f32 %0, %1, %2" : "=v"(r) : "v"(lo), "v"(hi)); return r; }
; __device__ __forceinline__ unsigned cvt_pk_bf16(float lo, float hi) { unsigned r; asm volatile("v_cvt_pk_bf16_f32 %0, %1, %2" : "=v"(r) : "v"(lo), "v"(hi)); return r; }
;     __device__ __forceinline__ void operator()(const f32x4 (&acc)[2][2][4][2], const Unit& u, int wr, int wc, int fr, int fq) const {
;     ...
;                         const f32x2 r2 = {rs[ai][m], rs[ai][m]};
;                         const f32x2 g = (f32x2){acc[ai][0][m][n][i], acc[ai][0][m][n][i + 1]} * r2, up = (f32x2){acc[ai][1][m][n][i], acc[ai][1][m][n][i + 1]} * r2;
;                         const f32x2 t = g * (f32x2){-1.4426950408889634f, -1.4426950408889634f};
;                         const f32x2 d = (f32x2){__builtin_amdgcn_exp2f(t.x), __builtin_amdgcn_exp2f(t.y)} + (f32x2){1.0f, 1.0f};
;                         const f32x2 o2 = (g * up) * (f32x2){__builtin_amdgcn_rcpf(d.x), __builtin_amdgcn_rcpf(d.y)};
;                         a[4 * n + i] = o2.x; a[4 * n + i + 1] = o2.y; }
;                 u32x4 w; w.x = cvt_pk_bf16(a[0], a[1]); w.y = cvt_pk_bf16(a[2], a[3]); w.z = cvt_pk_bf16(a[4], a[5]); w.w = cvt_pk_bf16(a[6], a[7]);
;                 *(u32x4*)rowp = w; }
	v_exp_f32_e32 v63, v63
	v_exp_f32_e32 v71, v71
	v_pk_mul_f32 v[58:59], v[58:59], v[66:67]
	v_pk_mul_f32 v[50:51], v[50:51], v[154:155] op_sel_hi:[1,0]
	v_pk_add_f32 v[62:63], v[62:63], 1.0 op_sel_hi:[1,0]
	v_pk_add_f32 v[66:67], v[70:71], 1.0 op_sel_hi:[1,0]
	v_rcp_f32_e32 v62, v62
	v_rcp_f32_e32 v63, v63
	v_rcp_f32_e32 v66, v66
	v_rcp_f32_e32 v67, v67
	v_pk_mul_f32 v[52:53], v[52:53], v[154:155] op_sel_hi:[1,0]
	v_pk_mul_f32 v[58:59], v[58:59], v[62:63]
	v_pk_mul_f32 v[62:63], v[68:69], v[154:155] op_sel_hi:[1,0]
	v_pk_mul_f32 v[68:69], v[50:51], s[10:11] op_sel_hi:[1,0]
	v_pk_mul_f32 v[60:61], v[60:61], v[62:63]
	v_exp_f32_e32 v68, v68
	v_exp_f32_e32 v69, v69
	v_pk_mul_f32 v[60:61], v[60:61], v[66:67]
	v_pk_mul_f32 v[66:67], v[52:53], s[10:11] op_sel_hi:[1,0]
	v_pk_mul_f32 v[54:55], v[54:55], v[154:155] op_sel_hi:[1,0]
	v_exp_f32_e32 v66, v66
	v_exp_f32_e32 v67, v67
	v_pk_add_f32 v[62:63], v[68:69], 1.0 op_sel_hi:[1,0]
	v_pk_mul_f32 v[50:51], v[50:51], v[54:55]
	v_rcp_f32_e32 v54, v62
	v_rcp_f32_e32 v55, v63
	v_fmamk_f32 v152, v152, 0x2d800000, v159
	v_pk_add_f32 v[62:63], v[66:67], 1.0 op_sel_hi:[1,0]
	v_rsq_f32_e32 v152, v152
	v_rcp_f32_e32 v62, v62
	v_rcp_f32_e32 v63, v63
	v_pk_mul_f32 v[54:55], v[50:51], v[54:55]
	v_pk_mul_f32 v[50:51], v[56:57], v[154:155] op_sel_hi:[1,0]
	v_mad_i64_i32 v[64:65], s[22:23], v165, s62, v[148:149]
	v_pk_mul_f32 v[50:51], v[52:53], v[50:51]
	v_pk_mul_f32 v[42:43], v[42:43], v[152:153] op_sel_hi:[1,0]
	v_pk_mul_f32 v[56:57], v[50:51], v[62:63]
	v_lshl_add_u64 v[62:63], v[64:65], 0, v[114:115]
	v_cvt_pk_bf16_f32 v50, v58, v59
	v_cvt_pk_bf16_f32 v51, v60, v61
	v_cvt_pk_bf16_f32 v52, v54, v55
	v_cvt_pk_bf16_f32 v53, v56, v57
	global_store_dwordx4 v[62:63], v[50:53], off sc1
	v_pk_mul_f32 v[44:45], v[44:45], v[152:153] op_sel_hi:[1,0]
	v_pk_mul_f32 v[46:47], v[46:47], v[152:153] op_sel_hi:[1,0]
	v_pk_mul_f32 v[50:51], v[42:43], s[10:11] op_sel_hi:[1,0]
	v_pk_mul_f32 v[54:55], v[44:45], s[10:11] op_sel_hi:[1,0]
	v_exp_f32_e32 v50, v50
	v_exp_f32_e32 v51, v51
	v_exp_f32_e32 v54, v54
	v_exp_f32_e32 v55, v55
	v_pk_mul_f32 v[42:43], v[42:43], v[46:47]
	v_pk_add_f32 v[50:51], v[50:51], 1.0 op_sel_hi:[1,0]
	v_pk_mul_f32 v[46:47], v[48:49], v[152:153] op_sel_hi:[1,0]
	v_rcp_f32_e32 v50, v50
	v_rcp_f32_e32 v51, v51
	v_pk_add_f32 v[48:49], v[54:55], 1.0 op_sel_hi:[1,0]
	v_pk_mul_f32 v[34:35], v[34:35], v[152:153] op_sel_hi:[1,0]
	v_rcp_f32_e32 v48, v48
	v_rcp_f32_e32 v49, v49
	v_pk_mul_f32 v[42:43], v[42:43], v[50:51]
	v_pk_mul_f32 v[50:51], v[34:35], s[10:11] op_sel_hi:[1,0]
	v_pk_mul_f32 v[44:45], v[44:45], v[46:47]
	v_exp_f32_e32 v50, v50
	v_exp_f32_e32 v51, v51
	v_pk_mul_f32 v[36:37], v[36:37], v[152:153] op_sel_hi:[1,0]
	v_pk_mul_f32 v[44:45], v[44:45], v[48:49]
	v_pk_mul_f32 v[48:49], v[36:37], s[10:11] op_sel_hi:[1,0]
	v_pk_mul_f32 v[38:39], v[38:39], v[152:153] op_sel_hi:[1,0]
	v_exp_f32_e32 v48, v48
	v_exp_f32_e32 v49, v49
	v_pk_add_f32 v[46:47], v[50:51], 1.0 op_sel_hi:[1,0]
	v_pk_mul_f32 v[34:35], v[34:35], v[38:39]
	v_rcp_f32_e32 v38, v46
	v_rcp_f32_e32 v39, v47
	v_pk_add_f32 v[46:47], v[48:49], 1.0 op_sel_hi:[1,0]
	v_mad_i64_i32 v[52:53], s[22:23], v163, s62, v[148:149]
	v_rcp_f32_e32 v46, v46
	v_rcp_f32_e32 v47, v47
	v_pk_mul_f32 v[38:39], v[34:35], v[38:39]
	v_pk_mul_f32 v[34:35], v[40:41], v[152:153] op_sel_hi:[1,0]
	v_pk_mul_f32 v[26:27], v[26:27], v[150:151] op_sel_hi:[1,0]
	v_pk_mul_f32 v[34:35], v[36:37], v[34:35]
	v_pk_mul_f32 v[28:29], v[28:29], v[150:151] op_sel_hi:[1,0]
	v_pk_mul_f32 v[40:41], v[34:35], v[46:47]
	v_lshl_add_u64 v[46:47], v[52:53], 0, v[114:115]
	v_cvt_pk_bf16_f32 v34, v42, v43
	v_cvt_pk_bf16_f32 v35, v44, v45
	v_cvt_pk_bf16_f32 v36, v38, v39
	v_cvt_pk_bf16_f32 v37, v40, v41
	global_store_dwordx4 v[46:47], v[34:37], off sc1
	v_pk_mul_f32 v[38:39], v[28:29], s[10:11] op_sel_hi:[1,0]
	v_pk_mul_f32 v[30:31], v[30:31], v[150:151] op_sel_hi:[1,0]
	v_pk_mul_f32 v[34:35], v[26:27], s[10:11] op_sel_hi:[1,0]
	v_exp_f32_e32 v38, v38
	v_exp_f32_e32 v34, v34
	v_exp_f32_e32 v35, v35
	v_exp_f32_e32 v39, v39
	v_pk_mul_f32 v[26:27], v[26:27], v[30:31]
	v_pk_mul_f32 v[30:31], v[32:33], v[150:151] op_sel_hi:[1,0]
	v_pk_add_f32 v[34:35], v[34:35], 1.0 op_sel_hi:[1,0]
	v_pk_add_f32 v[32:33], v[38:39], 1.0 op_sel_hi:[1,0]
	v_rcp_f32_e32 v34, v34
	v_rcp_f32_e32 v35, v35
	v_rcp_f32_e32 v32, v32
	v_rcp_f32_e32 v33, v33
	v_pk_mul_f32 v[18:19], v[18:19], v[150:151] op_sel_hi:[1,0]
	v_pk_mul_f32 v[26:27], v[26:27], v[34:35]
	v_pk_mul_f32 v[34:35], v[18:19], s[10:11] op_sel_hi:[1,0]
	v_pk_mul_f32 v[28:29], v[28:29], v[30:31]
	v_exp_f32_e32 v34, v34
	v_exp_f32_e32 v35, v35
; __device__ __forceinline__ unsigned cvt_pk_bf16(float lo, float hi) { unsigned r; asm volatile("v_cvt_pk_bf16_f32 %0, %1, %2" : "=v"(r) : "v"(lo), "v"(hi)); return r; }
; __device__ __forceinline__ unsigned cvt_pk_bf16(float lo, float hi) { unsigned r; asm volatile("v_cvt_pk_bf16_f32 %0, %1, %2" : "=v"(r) : "v"(lo), "v"(hi)); return r; }
; #define PG8_BAR __builtin_amdgcn_s_barrier()
;     __device__ __forceinline__ void operator()(const f32x4 (&acc)[2][2][4][2], const Unit& u, int wr, int wc, int fr, int fq) const {
;     ...
;                         const f32x2 r2 = {rs[ai][m], rs[ai][m]};
;                         const f32x2 g = (f32x2){acc[ai][0][m][n][i], acc[ai][0][m][n][i + 1]} * r2, up = (f32x2){acc[ai][1][m][n][i], acc[ai][1][m][n][i + 1]} * r2;
;                         const f32x2 t = g * (f32x2){-1.4426950408889634f, -1.4426950408889634f};
;                         const f32x2 d = (f32x2){__builtin_amdgcn_exp2f(t.x), __builtin_amdgcn_exp2f(t.y)} + (f32x2){1.0f, 1.0f};
;                         const f32x2 o2 = (g * up) * (f32x2){__builtin_amdgcn_rcpf(d.x), __builtin_amdgcn_rcpf(d.y)};
;                         a[4 * n + i] = o2.x; a[4 * n + i + 1] = o2.y; }
;                 u32x4 w; w.x = cvt_pk_bf16(a[0], a[1]); w.y = cvt_pk_bf16(a[2], a[3]); w.z = cvt_pk_bf16(a[4], a[5]); w.w = cvt_pk_bf16(a[6], a[7]);
;                 *(u32x4*)rowp = w; }
; template <class Epi, class Sched, bool ALIGN_EPI = false, bool SP2 = false>
; __device__ __forceinline__ void gemm_phase(PG8_LAS unsigned char* lds, const Gemm g, const Sched& S, const Epi& E) {
;     ...
; #pragma unroll
;         for (int a = 0; a < 2; ++a)
; #pragma unroll
;             for (int b = 0; b < 2; ++b)
; #pragma unroll
;                 for (int m = 0; m < 4; ++m)
; #pragma unroll
;                     for (int n = 0; n < 2; ++n) { d64x2 z_; asm volatile("v_mov_b64 %0, 0\n\tv_mov_b64 %1, 0" : "=v"(z_.x), "=v"(z_.y)); acc[a][b][m][n] = __builtin_bit_cast(f32x4, z_); }
;         cur = nxt; cA = nA; cB = nB; ++ui;
;         if constexpr (ALIGN_EPI) { if (wr == 1) PG8_BAR; }
	v_pk_mul_f32 v[20:21], v[20:21], v[150:151] op_sel_hi:[1,0]
	v_pk_mul_f32 v[28:29], v[28:29], v[32:33]
	v_pk_mul_f32 v[32:33], v[20:21], s[10:11] op_sel_hi:[1,0]
	v_pk_mul_f32 v[22:23], v[22:23], v[150:151] op_sel_hi:[1,0]
	v_exp_f32_e32 v32, v32
	v_exp_f32_e32 v33, v33
	v_pk_add_f32 v[30:31], v[34:35], 1.0 op_sel_hi:[1,0]
	v_pk_mul_f32 v[18:19], v[18:19], v[22:23]
	v_rcp_f32_e32 v22, v30
	v_rcp_f32_e32 v23, v31
	v_fmamk_f32 v146, v146, 0x2d800000, v159
	v_pk_add_f32 v[30:31], v[32:33], 1.0 op_sel_hi:[1,0]
	v_rsq_f32_e32 v146, v146
	v_rcp_f32_e32 v30, v30
	v_rcp_f32_e32 v31, v31
	v_pk_mul_f32 v[22:23], v[18:19], v[22:23]
	v_pk_mul_f32 v[18:19], v[24:25], v[150:151] op_sel_hi:[1,0]
	v_mad_i64_i32 v[36:37], s[22:23], v161, s62, v[148:149]
	v_pk_mul_f32 v[18:19], v[20:21], v[18:19]
	v_pk_mul_f32 v[10:11], v[10:11], v[146:147] op_sel_hi:[1,0]
	v_pk_mul_f32 v[24:25], v[18:19], v[30:31]
	v_lshl_add_u64 v[30:31], v[36:37], 0, v[114:115]
	v_cvt_pk_bf16_f32 v18, v26, v27
	v_cvt_pk_bf16_f32 v19, v28, v29
	v_cvt_pk_bf16_f32 v20, v22, v23
	v_cvt_pk_bf16_f32 v21, v24, v25
	global_store_dwordx4 v[30:31], v[18:21], off sc1
	v_pk_mul_f32 v[12:13], v[12:13], v[146:147] op_sel_hi:[1,0]
	v_pk_mul_f32 v[14:15], v[14:15], v[146:147] op_sel_hi:[1,0]
	v_pk_mul_f32 v[18:19], v[10:11], s[10:11] op_sel_hi:[1,0]
	v_pk_mul_f32 v[22:23], v[12:13], s[10:11] op_sel_hi:[1,0]
	v_exp_f32_e32 v18, v18
	v_exp_f32_e32 v19, v19
	v_exp_f32_e32 v22, v22
	v_exp_f32_e32 v23, v23
	v_pk_mul_f32 v[10:11], v[10:11], v[14:15]
	v_pk_add_f32 v[18:19], v[18:19], 1.0 op_sel_hi:[1,0]
	v_pk_mul_f32 v[14:15], v[16:17], v[146:147] op_sel_hi:[1,0]
	v_rcp_f32_e32 v18, v18
	v_rcp_f32_e32 v19, v19
	v_pk_add_f32 v[16:17], v[22:23], 1.0 op_sel_hi:[1,0]
	v_pk_mul_f32 v[2:3], v[2:3], v[146:147] op_sel_hi:[1,0]
	v_rcp_f32_e32 v16, v16
	v_rcp_f32_e32 v17, v17
	v_pk_mul_f32 v[10:11], v[10:11], v[18:19]
	v_pk_mul_f32 v[18:19], v[2:3], s[10:11] op_sel_hi:[1,0]
	v_pk_mul_f32 v[12:13], v[12:13], v[14:15]
	v_exp_f32_e32 v18, v18
	v_exp_f32_e32 v19, v19
	v_pk_mul_f32 v[4:5], v[4:5], v[146:147] op_sel_hi:[1,0]
	v_pk_mul_f32 v[12:13], v[12:13], v[16:17]
	v_pk_mul_f32 v[16:17], v[4:5], s[10:11] op_sel_hi:[1,0]
	v_pk_mul_f32 v[6:7], v[6:7], v[146:147] op_sel_hi:[1,0]
	v_exp_f32_e32 v16, v16
	v_exp_f32_e32 v17, v17
	v_pk_add_f32 v[14:15], v[18:19], 1.0 op_sel_hi:[1,0]
	v_pk_mul_f32 v[2:3], v[2:3], v[6:7]
	v_rcp_f32_e32 v6, v14
	v_rcp_f32_e32 v7, v15
	v_pk_add_f32 v[14:15], v[16:17], 1.0 op_sel_hi:[1,0]
	v_mad_i64_i32 v[20:21], s[22:23], v157, s62, v[148:149]
	v_rcp_f32_e32 v14, v14
	v_rcp_f32_e32 v15, v15
	v_pk_mul_f32 v[6:7], v[2:3], v[6:7]
	v_pk_mul_f32 v[2:3], v[8:9], v[146:147] op_sel_hi:[1,0]
	s_nop 0
	v_pk_mul_f32 v[2:3], v[4:5], v[2:3]
	s_nop 0
	v_pk_mul_f32 v[8:9], v[2:3], v[14:15]
	v_lshl_add_u64 v[14:15], v[20:21], 0, v[114:115]
	v_cvt_pk_bf16_f32 v2, v10, v11
	v_cvt_pk_bf16_f32 v3, v12, v13
	v_cvt_pk_bf16_f32 v4, v6, v7
	v_cvt_pk_bf16_f32 v5, v8, v9
	global_store_dwordx4 v[14:15], v[2:5], off sc1
	s_cbranch_vccnz .LBB0_1122
	s_andn2_b64 vcc, exec, s[2:3]
	v_mov_b64 v[122:123], 0
	v_mov_b64 v[124:125], 0
	v_mov_b64 v[114:115], 0
	v_mov_b64 v[116:117], 0
	v_mov_b64 v[106:107], 0
	v_mov_b64 v[108:109], 0
	v_mov_b64 v[98:99], 0
	v_mov_b64 v[100:101], 0
	v_mov_b64 v[90:91], 0
	v_mov_b64 v[92:93], 0
	v_mov_b64 v[82:83], 0
	v_mov_b64 v[84:85], 0
	v_mov_b64 v[74:75], 0
	v_mov_b64 v[76:77], 0
	v_mov_b64 v[62:63], 0
	v_mov_b64 v[64:65], 0
	v_mov_b64 v[126:127], 0
	v_mov_b64 v[128:129], 0
	v_mov_b64 v[118:119], 0
	v_mov_b64 v[120:121], 0
	v_mov_b64 v[110:111], 0
	v_mov_b64 v[112:113], 0
	v_mov_b64 v[102:103], 0
	v_mov_b64 v[104:105], 0
	v_mov_b64 v[94:95], 0
	v_mov_b64 v[96:97], 0
	v_mov_b64 v[86:87], 0
	v_mov_b64 v[88:89], 0
	v_mov_b64 v[78:79], 0
	v_mov_b64 v[80:81], 0
	v_mov_b64 v[70:71], 0
	v_mov_b64 v[72:73], 0
	v_mov_b64 v[58:59], 0
	v_mov_b64 v[60:61], 0
	v_mov_b64 v[50:51], 0
	v_mov_b64 v[52:53], 0
	v_mov_b64 v[42:43], 0
	v_mov_b64 v[44:45], 0
	v_mov_b64 v[34:35], 0
	v_mov_b64 v[36:37], 0
	v_mov_b64 v[26:27], 0
	v_mov_b64 v[28:29], 0
	v_mov_b64 v[18:19], 0
	v_mov_b64 v[20:21], 0
	v_mov_b64 v[10:11], 0
	v_mov_b64 v[12:13], 0
	v_mov_b64 v[2:3], 0
	v_mov_b64 v[4:5], 0
	v_mov_b64 v[66:67], 0
	v_mov_b64 v[68:69], 0
	v_mov_b64 v[54:55], 0
	v_mov_b64 v[56:57], 0
	v_mov_b64 v[46:47], 0
	v_mov_b64 v[48:49], 0
	v_mov_b64 v[38:39], 0
	v_mov_b64 v[40:41], 0
	v_mov_b64 v[30:31], 0
	v_mov_b64 v[32:33], 0
	v_mov_b64 v[22:23], 0
	v_mov_b64 v[24:25], 0
	v_mov_b64 v[14:15], 0
	v_mov_b64 v[16:17], 0
	v_mov_b64 v[6:7], 0
	v_mov_b64 v[8:9], 0
	s_cbranch_vccnz .LBB0_1121
	s_barrier
	s_branch .LBB0_1121

; __device__ __forceinline__ unsigned cvt_pk_bf16(float lo, float hi) { unsigned r; asm volatile("v_cvt_pk_bf16_f32 %0, %1, %2" : "=v"(r) : "v"(lo), "v"(hi)); return r; }
; __device__ __forceinline__ unsigned cvt_pk_bf16(float lo, float hi) { unsigned r; asm volatile("v_cvt_pk_bf16_f32 %0, %1, %2" : "=v"(r) : "v"(lo), "v"(hi)); return r; }
;     __device__ __forceinline__ void operator()(const f32x4 (&acc)[2][2][4][2], const Unit& u, int wr, int wc, int fr, int fq) const {
;     ...
;                 for (int bj = 0; bj < 2; ++bj) { const size_t off = (size_t)(row0 + ai * HALF + m * 16) * ldc + col0 + bj * HALF;
;                     if (BASE_F32) { const float* bp = (const float*)base + off; b0[m][bj] = *(const f32x4*)bp; b1[m][bj] = *(const f32x4*)(bp + 4); }
;                     else { const u32x4 r = *(const u32x4*)((const bf16_t*)base + off);
;                         b0[m][bj] = (f32x4){__uint_as_float(r.x << 16), __uint_as_float(r.x & 0xffff0000u), __uint_as_float(r.y << 16), __uint_as_float(r.y & 0xffff0000u)};
;                         b1[m][bj] = (f32x4){__uint_as_float(r.z << 16), __uint_as_float(r.z & 0xffff0000u), __uint_as_float(r.w << 16), __uint_as_float(r.w & 0xffff0000u)}; } }
; #pragma unroll
;             for (int m = 0; m < 4; ++m) { const int row = row0 + ai * HALF + m * 16; const size_t off = (size_t)row * ldc + col0; f32x2 q2 = {0.f, 0.f};
; #pragma unroll
;                 for (int bj = 0; bj < 2; ++bj) { const f32x4 v0 = acc[ai][bj][m][0] + b0[m][bj], v1 = acc[ai][bj][m][1] + b1[m][bj];
;                     { const f32x2 e0 = {v0[0], v0[1]}, e1 = {v0[2], v0[3]}, e2 = {v1[0], v1[1]}, e3 = {v1[2], v1[3]}; q2 = e0 * e0 + q2; q2 = e1 * e1 + q2; q2 = e2 * e2 + q2; q2 = e3 * e3 + q2; }
;                     u32x4 w; w.x = cvt_pk_bf16(v0[0], v0[1]); w.y = cvt_pk_bf16(v0[2], v0[3]); w.z = cvt_pk_bf16(v1[0], v1[1]); w.w = cvt_pk_bf16(v1[2], v1[3]);
;                     *(u32x4*)(out + off + bj * HALF) = w; }
;                 float q = q2.x + q2.y; q += __shfl_xor(q, 16); q += __shfl_xor(q, 32);
;                 if (fq == 0) atomicAdd(ssq + row, (ssq_t)(q * SSQ_FIX + 0.5f)); }
.Lepi_rest_1248:
	v_and_b32_e32 v200, 64, v186
	v_xor_b32_e32 v187, 16, v186
	v_add_u32_e32 v200, 64, v200
	v_xor_b32_e32 v201, 32, v186
	v_cmp_lt_i32_e32 vcc, v187, v200
	v_lshl_add_u64 v[198:199], s[96:97], 0, v[198:199]
	v_lshl_add_u64 v[196:197], v[198:199], 0, v[196:197]
	v_cndmask_b32_e32 v187, v186, v187, vcc
	v_cmp_lt_i32_e32 vcc, v201, v200
	v_lshlrev_b32_e32 v187, 2, v187
	s_waitcnt vmcnt(0)
	v_lshlrev_b32_e32 v198, 16, v188
	v_and_b32_e32 v199, 0xffff0000, v188
	v_lshlrev_b32_e32 v188, 16, v189
	v_and_b32_e32 v189, 0xffff0000, v189
	v_cndmask_b32_e32 v206, v186, v201, vcc
	v_lshlrev_b32_e32 v200, 16, v190
	v_and_b32_e32 v201, 0xffff0000, v190
	v_lshlrev_b32_e32 v190, 16, v191
	v_and_b32_e32 v191, 0xffff0000, v191
	v_pk_add_f32 v[116:117], v[116:117], v[188:189]
	v_pk_add_f32 v[188:189], v[114:115], v[198:199]
	v_pk_add_f32 v[120:121], v[120:121], v[190:191]
	v_pk_mul_f32 v[190:191], v[116:117], v[116:117]
	v_pk_add_f32 v[118:119], v[118:119], v[200:201]
	v_cvt_pk_bf16_f32 v114, v188, v189
	v_cvt_pk_bf16_f32 v115, v116, v117
	v_pk_fma_f32 v[116:117], v[188:189], v[188:189], v[190:191]
	v_lshlrev_b32_e32 v202, 16, v192
	v_and_b32_e32 v203, 0xffff0000, v192
	v_pk_fma_f32 v[116:117], v[118:119], v[118:119], v[116:117]
	v_lshlrev_b32_e32 v192, 16, v193
	v_and_b32_e32 v193, 0xffff0000, v193
	v_pk_add_f32 v[122:123], v[122:123], v[202:203]
	v_pk_fma_f32 v[116:117], v[120:121], v[120:121], v[116:117]
	v_lshlrev_b32_e32 v204, 16, v194
	v_and_b32_e32 v205, 0xffff0000, v194
	v_pk_add_f32 v[124:125], v[124:125], v[192:193]
	v_pk_fma_f32 v[116:117], v[122:123], v[122:123], v[116:117]
	v_lshlrev_b32_e32 v194, 16, v195
	v_and_b32_e32 v195, 0xffff0000, v195
	v_pk_add_f32 v[126:127], v[126:127], v[204:205]
	v_pk_fma_f32 v[116:117], v[124:125], v[124:125], v[116:117]
	v_pk_add_f32 v[128:129], v[128:129], v[194:195]
	v_pk_fma_f32 v[116:117], v[126:127], v[126:127], v[116:117]
	s_nop 0
	v_pk_fma_f32 v[116:117], v[128:129], v[128:129], v[116:117]
	s_nop 0
	v_add_f32_e32 v188, v116, v117
	ds_bpermute_b32 v189, v187, v188
	v_cvt_pk_bf16_f32 v116, v118, v119
	v_cvt_pk_bf16_f32 v117, v120, v121
	global_store_dwordx4 v[196:197], v[114:117], off sc1
	v_cvt_pk_bf16_f32 v118, v122, v123
	v_cvt_pk_bf16_f32 v119, v124, v125
	v_cvt_pk_bf16_f32 v120, v126, v127
	v_cvt_pk_bf16_f32 v121, v128, v129
	global_store_dwordx4 v[196:197], v[118:121], off offset:256 sc1
	s_waitcnt lgkmcnt(0)
	v_add_f32_e32 v115, v188, v189
	v_lshlrev_b32_e32 v114, 2, v206
	ds_bpermute_b32 v116, v114, v115
	s_and_saveexec_b64 s[16:17], s[0:1]
	s_cbranch_execz .LBB0_1250
	s_waitcnt lgkmcnt(0)
	v_add_f32_e32 v115, v115, v116
	v_fma_f32 v115, v115, s43, 0.5
	v_trunc_f32_e32 v115, v115
	v_mul_f32_e32 v116, 0x2f800000, v115
	v_floor_f32_e32 v117, v116
	v_fmac_f32_e32 v115, 0xcf800000, v117
	v_cvt_u32_f32_e32 v116, v115
	v_cvt_u32_f32_e32 v117, v117
	v_lshl_add_u64 v[118:119], v[176:177], 3, s[8:9]
	global_atomic_add_x2 v[118:119], v[116:117], off
.LBB0_1250:
	s_or_b64 exec, exec, s[16:17]
	v_lshlrev_b32_e32 v120, 16, v151
	v_and_b32_e32 v121, 0xffff0000, v151
	v_lshlrev_b32_e32 v118, 16, v150
	v_and_b32_e32 v119, 0xffff0000, v150
	v_lshlrev_b32_e32 v122, 16, v152
	v_and_b32_e32 v123, 0xffff0000, v152
	v_lshlrev_b32_e32 v124, 16, v153
	v_and_b32_e32 v125, 0xffff0000, v153
	v_pk_add_f32 v[108:109], v[108:109], v[120:121]
	v_pk_add_f32 v[106:107], v[106:107], v[118:119]
	v_pk_add_f32 v[118:119], v[100:101], v[124:125]
	v_pk_add_f32 v[100:101], v[98:99], v[122:123]
	v_pk_mul_f32 v[98:99], v[108:109], v[108:109]
	v_lshlrev_b32_e32 v126, 16, v146
	v_pk_fma_f32 v[98:99], v[106:107], v[106:107], v[98:99]
	v_and_b32_e32 v127, 0xffff0000, v146
	v_pk_fma_f32 v[98:99], v[100:101], v[100:101], v[98:99]
	v_lshlrev_b32_e32 v128, 16, v147
	v_and_b32_e32 v129, 0xffff0000, v147
	v_pk_fma_f32 v[120:121], v[118:119], v[118:119], v[98:99]
	v_cvt_pk_bf16_f32 v98, v106, v107
	v_cvt_pk_bf16_f32 v99, v108, v109
	v_pk_add_f32 v[108:109], v[110:111], v[126:127]
	v_lshlrev_b32_e32 v146, 16, v148
	v_and_b32_e32 v147, 0xffff0000, v148
	v_pk_add_f32 v[106:107], v[112:113], v[128:129]
	v_pk_fma_f32 v[110:111], v[108:109], v[108:109], v[120:121]
	v_lshlrev_b32_e32 v148, 16, v149
	v_and_b32_e32 v149, 0xffff0000, v149
	v_pk_add_f32 v[102:103], v[102:103], v[146:147]
	v_pk_fma_f32 v[110:111], v[106:107], v[106:107], v[110:111]
	v_pk_add_f32 v[104:105], v[104:105], v[148:149]
	v_pk_fma_f32 v[110:111], v[102:103], v[102:103], v[110:111]
	s_waitcnt lgkmcnt(0)
	v_lshlrev_b64 v[116:117], 12, v[182:183]
	v_pk_fma_f32 v[110:111], v[104:105], v[104:105], v[110:111]
	v_cvt_pk_bf16_f32 v100, v100, v101
	v_cvt_pk_bf16_f32 v101, v118, v119
	s_nop 0
	v_add_f32_e32 v112, v110, v111
	ds_bpermute_b32 v113, v187, v112
	v_lshl_add_u64 v[110:111], v[116:117], 1, s[96:97]
	v_lshl_add_u64 v[110:111], v[172:173], 1, v[110:111]
	global_store_dwordx4 v[110:111], v[98:101], off sc1
	s_waitcnt lgkmcnt(0)
	s_nop 0
	v_add_f32_e32 v98, v112, v113
	ds_bpermute_b32 v99, v114, v98
	v_cvt_pk_bf16_f32 v100, v108, v109
	v_cvt_pk_bf16_f32 v101, v106, v107
	v_cvt_pk_bf16_f32 v102, v102, v103
	v_cvt_pk_bf16_f32 v103, v104, v105
	global_store_dwordx4 v[110:111], v[100:103], off offset:256 sc1
	s_and_saveexec_b64 s[16:17], s[0:1]
	s_cbranch_execz .LBB0_1252
	s_waitcnt lgkmcnt(0)
	v_add_f32_e32 v98, v98, v99
	v_fma_f32 v98, v98, s43, 0.5
	v_trunc_f32_e32 v98, v98
	v_mul_f32_e32 v99, 0x2f800000, v98
	v_floor_f32_e32 v99, v99
	v_fmac_f32_e32 v98, 0xcf800000, v99
	v_cvt_u32_f32_e32 v98, v98
	v_cvt_u32_f32_e32 v99, v99
	v_lshl_add_u64 v[100:101], v[182:183], 3, s[8:9]
	global_atomic_add_x2 v[100:101], v[98:99], off
; __device__ __forceinline__ unsigned cvt_pk_bf16(float lo, float hi) { unsigned r; asm volatile("v_cvt_pk_bf16_f32 %0, %1, %2" : "=v"(r) : "v"(lo), "v"(hi)); return r; }
; __device__ __forceinline__ unsigned cvt_pk_bf16(float lo, float hi) { unsigned r; asm volatile("v_cvt_pk_bf16_f32 %0, %1, %2" : "=v"(r) : "v"(lo), "v"(hi)); return r; }
;     __device__ __forceinline__ void operator()(const f32x4 (&acc)[2][2][4][2], const Unit& u, int wr, int wc, int fr, int fq) const {
;     ...
;                 for (int bj = 0; bj < 2; ++bj) { const size_t off = (size_t)(row0 + ai * HALF + m * 16) * ldc + col0 + bj * HALF;
;                     if (BASE_F32) { const float* bp = (const float*)base + off; b0[m][bj] = *(const f32x4*)bp; b1[m][bj] = *(const f32x4*)(bp + 4); }
;                     else { const u32x4 r = *(const u32x4*)((const bf16_t*)base + off);
;                         b0[m][bj] = (f32x4){__uint_as_float(r.x << 16), __uint_as_float(r.x & 0xffff0000u), __uint_as_float(r.y << 16), __uint_as_float(r.y & 0xffff0000u)};
;                         b1[m][bj] = (f32x4){__uint_as_float(r.z << 16), __uint_as_float(r.z & 0xffff0000u), __uint_as_float(r.w << 16), __uint_as_float(r.w & 0xffff0000u)}; } }
; #pragma unroll
;             for (int m = 0; m < 4; ++m) { const int row = row0 + ai * HALF + m * 16; const size_t off = (size_t)row * ldc + col0; f32x2 q2 = {0.f, 0.f};
; #pragma unroll
;                 for (int bj = 0; bj < 2; ++bj) { const f32x4 v0 = acc[ai][bj][m][0] + b0[m][bj], v1 = acc[ai][bj][m][1] + b1[m][bj];
;                     { const f32x2 e0 = {v0[0], v0[1]}, e1 = {v0[2], v0[3]}, e2 = {v1[0], v1[1]}, e3 = {v1[2], v1[3]}; q2 = e0 * e0 + q2; q2 = e1 * e1 + q2; q2 = e2 * e2 + q2; q2 = e3 * e3 + q2; }
;                     u32x4 w; w.x = cvt_pk_bf16(v0[0], v0[1]); w.y = cvt_pk_bf16(v0[2], v0[3]); w.z = cvt_pk_bf16(v1[0], v1[1]); w.w = cvt_pk_bf16(v1[2], v1[3]);
;                     *(u32x4*)(out + off + bj * HALF) = w; }
;                 float q = q2.x + q2.y; q += __shfl_xor(q, 16); q += __shfl_xor(q, 32);
;                 if (fq == 0) atomicAdd(ssq + row, (ssq_t)(q * SSQ_FIX + 0.5f)); }
.LBB0_1252:
	s_or_b64 exec, exec, s[16:17]
	v_lshlrev_b32_e32 v102, 16, v143
	v_and_b32_e32 v103, 0xffff0000, v143
	v_lshlrev_b32_e32 v100, 16, v142
	v_and_b32_e32 v101, 0xffff0000, v142
	v_lshlrev_b32_e32 v104, 16, v144
	v_and_b32_e32 v105, 0xffff0000, v144
	v_lshlrev_b32_e32 v106, 16, v145
	v_and_b32_e32 v107, 0xffff0000, v145
	v_pk_add_f32 v[92:93], v[92:93], v[102:103]
	v_pk_add_f32 v[90:91], v[90:91], v[100:101]
	v_pk_add_f32 v[100:101], v[84:85], v[106:107]
	v_pk_add_f32 v[84:85], v[82:83], v[104:105]
	v_pk_mul_f32 v[82:83], v[92:93], v[92:93]
	v_lshlrev_b32_e32 v108, 16, v138
	v_pk_fma_f32 v[82:83], v[90:91], v[90:91], v[82:83]
	v_and_b32_e32 v109, 0xffff0000, v138
	v_pk_fma_f32 v[82:83], v[84:85], v[84:85], v[82:83]
	v_lshlrev_b32_e32 v110, 16, v139
	v_and_b32_e32 v111, 0xffff0000, v139
	v_pk_fma_f32 v[102:103], v[100:101], v[100:101], v[82:83]
	v_cvt_pk_bf16_f32 v82, v90, v91
	v_cvt_pk_bf16_f32 v83, v92, v93
	v_pk_add_f32 v[92:93], v[94:95], v[108:109]
	v_lshlrev_b32_e32 v112, 16, v140
	v_and_b32_e32 v113, 0xffff0000, v140
	v_pk_add_f32 v[90:91], v[96:97], v[110:111]
	v_pk_fma_f32 v[94:95], v[92:93], v[92:93], v[102:103]
	v_lshlrev_b32_e32 v116, 16, v141
	v_and_b32_e32 v117, 0xffff0000, v141
	v_pk_add_f32 v[86:87], v[86:87], v[112:113]
	v_pk_fma_f32 v[94:95], v[90:91], v[90:91], v[94:95]
	v_pk_add_f32 v[88:89], v[88:89], v[116:117]
	v_pk_fma_f32 v[94:95], v[86:87], v[86:87], v[94:95]
	s_waitcnt lgkmcnt(0)
	v_lshlrev_b64 v[98:99], 12, v[180:181]
	v_pk_fma_f32 v[94:95], v[88:89], v[88:89], v[94:95]
	v_cvt_pk_bf16_f32 v84, v84, v85
	v_cvt_pk_bf16_f32 v85, v100, v101
	s_nop 0
	v_add_f32_e32 v96, v94, v95
	ds_bpermute_b32 v97, v187, v96
	v_lshl_add_u64 v[94:95], v[98:99], 1, s[96:97]
	v_lshl_add_u64 v[94:95], v[172:173], 1, v[94:95]
	global_store_dwordx4 v[94:95], v[82:85], off sc1
	s_waitcnt lgkmcnt(0)
	s_nop 0
	v_add_f32_e32 v82, v96, v97
	ds_bpermute_b32 v83, v114, v82
	v_cvt_pk_bf16_f32 v84, v92, v93
	v_cvt_pk_bf16_f32 v85, v90, v91
	v_cvt_pk_bf16_f32 v86, v86, v87
	v_cvt_pk_bf16_f32 v87, v88, v89
	global_store_dwordx4 v[94:95], v[84:87], off offset:256 sc1
	s_and_saveexec_b64 s[16:17], s[0:1]
	s_cbranch_execz .LBB0_1254
	s_waitcnt lgkmcnt(0)
	v_add_f32_e32 v82, v82, v83
	v_fma_f32 v82, v82, s43, 0.5
	v_trunc_f32_e32 v82, v82
	v_mul_f32_e32 v83, 0x2f800000, v82
	v_floor_f32_e32 v83, v83
	v_fmac_f32_e32 v82, 0xcf800000, v83
	v_cvt_u32_f32_e32 v82, v82
	v_cvt_u32_f32_e32 v83, v83
	v_lshl_add_u64 v[84:85], v[180:181], 3, s[8:9]
	global_atomic_add_x2 v[84:85], v[82:83], off
.LBB0_1254:
	s_or_b64 exec, exec, s[16:17]
	v_lshlrev_b32_e32 v86, 16, v135
	v_and_b32_e32 v87, 0xffff0000, v135
	v_lshlrev_b32_e32 v84, 16, v134
	v_and_b32_e32 v85, 0xffff0000, v134
	v_lshlrev_b32_e32 v88, 16, v136
	v_and_b32_e32 v89, 0xffff0000, v136
	v_lshlrev_b32_e32 v90, 16, v137
	v_and_b32_e32 v91, 0xffff0000, v137
	v_pk_add_f32 v[76:77], v[76:77], v[86:87]
	v_pk_add_f32 v[74:75], v[74:75], v[84:85]
	v_pk_add_f32 v[84:85], v[68:69], v[90:91]
	v_pk_add_f32 v[68:69], v[66:67], v[88:89]
	v_pk_mul_f32 v[66:67], v[76:77], v[76:77]
	v_lshlrev_b32_e32 v92, 16, v130
	v_pk_fma_f32 v[66:67], v[74:75], v[74:75], v[66:67]
	v_and_b32_e32 v93, 0xffff0000, v130
	v_pk_fma_f32 v[66:67], v[68:69], v[68:69], v[66:67]
	v_lshlrev_b32_e32 v94, 16, v131
	v_and_b32_e32 v95, 0xffff0000, v131
	v_pk_fma_f32 v[86:87], v[84:85], v[84:85], v[66:67]
	v_cvt_pk_bf16_f32 v66, v74, v75
	v_cvt_pk_bf16_f32 v67, v76, v77
	v_pk_add_f32 v[76:77], v[78:79], v[92:93]
	v_lshlrev_b32_e32 v96, 16, v132
	v_and_b32_e32 v97, 0xffff0000, v132
	v_pk_add_f32 v[74:75], v[80:81], v[94:95]
	v_pk_fma_f32 v[78:79], v[76:77], v[76:77], v[86:87]
	v_lshlrev_b32_e32 v98, 16, v133
	v_and_b32_e32 v99, 0xffff0000, v133
	v_pk_add_f32 v[70:71], v[70:71], v[96:97]
	v_pk_fma_f32 v[78:79], v[74:75], v[74:75], v[78:79]
	v_pk_add_f32 v[72:73], v[72:73], v[98:99]
	v_pk_fma_f32 v[78:79], v[70:71], v[70:71], v[78:79]
	s_waitcnt lgkmcnt(0)
	v_lshlrev_b64 v[82:83], 12, v[178:179]
	v_pk_fma_f32 v[78:79], v[72:73], v[72:73], v[78:79]
	v_cvt_pk_bf16_f32 v68, v68, v69
	v_cvt_pk_bf16_f32 v69, v84, v85
	s_nop 0
	v_add_f32_e32 v80, v78, v79
	ds_bpermute_b32 v81, v187, v80
	v_lshl_add_u64 v[78:79], v[82:83], 1, s[96:97]
	v_lshl_add_u64 v[78:79], v[172:173], 1, v[78:79]
	global_store_dwordx4 v[78:79], v[66:69], off sc1
	s_waitcnt lgkmcnt(0)
	s_nop 0
	v_add_f32_e32 v66, v80, v81
	ds_bpermute_b32 v67, v114, v66
	v_cvt_pk_bf16_f32 v68, v76, v77
	v_cvt_pk_bf16_f32 v69, v74, v75
	v_cvt_pk_bf16_f32 v70, v70, v71
	v_cvt_pk_bf16_f32 v71, v72, v73
	global_store_dwordx4 v[78:79], v[68:71], off offset:256 sc1
	s_and_saveexec_b64 s[16:17], s[0:1]
	s_cbranch_execz .LBB0_1256
	s_waitcnt lgkmcnt(0)
	v_add_f32_e32 v66, v66, v67
	v_fma_f32 v66, v66, s43, 0.5
	v_trunc_f32_e32 v66, v66
	v_mul_f32_e32 v67, 0x2f800000, v66
	v_floor_f32_e32 v67, v67
	v_fmac_f32_e32 v66, 0xcf800000, v67
	v_cvt_u32_f32_e32 v66, v66
	v_cvt_u32_f32_e32 v67, v67
	v_lshl_add_u64 v[68:69], v[178:179], 3, s[8:9]
	global_atomic_add_x2 v[68:69], v[66:67], off
; __device__ __forceinline__ unsigned cvt_pk_bf16(float lo, float hi) { unsigned r; asm volatile("v_cvt_pk_bf16_f32 %0, %1, %2" : "=v"(r) : "v"(lo), "v"(hi)); return r; }
; __device__ __forceinline__ unsigned cvt_pk_bf16(float lo, float hi) { unsigned r; asm volatile("v_cvt_pk_bf16_f32 %0, %1, %2" : "=v"(r) : "v"(lo), "v"(hi)); return r; }
;     __device__ __forceinline__ void operator()(const f32x4 (&acc)[2][2][4][2], const Unit& u, int wr, int wc, int fr, int fq) const {
;     ...
;                 for (int bj = 0; bj < 2; ++bj) { const size_t off = (size_t)(row0 + ai * HALF + m * 16) * ldc + col0 + bj * HALF;
;                     if (BASE_F32) { const float* bp = (const float*)base + off; b0[m][bj] = *(const f32x4*)bp; b1[m][bj] = *(const f32x4*)(bp + 4); }
;                     else { const u32x4 r = *(const u32x4*)((const bf16_t*)base + off);
;                         b0[m][bj] = (f32x4){__uint_as_float(r.x << 16), __uint_as_float(r.x & 0xffff0000u), __uint_as_float(r.y << 16), __uint_as_float(r.y & 0xffff0000u)};
;                         b1[m][bj] = (f32x4){__uint_as_float(r.z << 16), __uint_as_float(r.z & 0xffff0000u), __uint_as_float(r.w << 16), __uint_as_float(r.w & 0xffff0000u)}; } }
; #pragma unroll
;             for (int m = 0; m < 4; ++m) { const int row = row0 + ai * HALF + m * 16; const size_t off = (size_t)row * ldc + col0; f32x2 q2 = {0.f, 0.f};
; #pragma unroll
;                 for (int bj = 0; bj < 2; ++bj) { const f32x4 v0 = acc[ai][bj][m][0] + b0[m][bj], v1 = acc[ai][bj][m][1] + b1[m][bj];
;                     { const f32x2 e0 = {v0[0], v0[1]}, e1 = {v0[2], v0[3]}, e2 = {v1[0], v1[1]}, e3 = {v1[2], v1[3]}; q2 = e0 * e0 + q2; q2 = e1 * e1 + q2; q2 = e2 * e2 + q2; q2 = e3 * e3 + q2; }
;                     u32x4 w; w.x = cvt_pk_bf16(v0[0], v0[1]); w.y = cvt_pk_bf16(v0[2], v0[3]); w.z = cvt_pk_bf16(v1[0], v1[1]); w.w = cvt_pk_bf16(v1[2], v1[3]);
;                     *(u32x4*)(out + off + bj * HALF) = w; }
;                 float q = q2.x + q2.y; q += __shfl_xor(q, 16); q += __shfl_xor(q, 32);
;                 if (fq == 0) atomicAdd(ssq + row, (ssq_t)(q * SSQ_FIX + 0.5f)); }
.LBB0_1256:
	s_or_b64 exec, exec, s[16:17]
	v_add_u32_e32 v96, 0x80, v176
	v_ashrrev_i32_e32 v97, 31, v96
	v_lshlrev_b64 v[106:107], 13, v[96:97]
	s_waitcnt lgkmcnt(0)
	v_lshl_add_u64 v[66:67], v[174:175], 0, v[106:107]
	global_load_dwordx4 v[98:101], v[66:67], off
	global_load_dwordx4 v[102:105], v[66:67], off offset:256
	v_add_u32_e32 v94, 0x90, v176
	v_add_u32_e32 v92, 0xa0, v176
	v_add_u32_e32 v90, 0xb0, v176
	v_ashrrev_i32_e32 v95, 31, v94
	v_ashrrev_i32_e32 v93, 31, v92
	v_ashrrev_i32_e32 v91, 31, v90
	v_lshlrev_b64 v[66:67], 13, v[94:95]
	v_lshlrev_b64 v[68:69], 13, v[92:93]
	v_lshlrev_b64 v[70:71], 13, v[90:91]
	v_lshl_add_u64 v[66:67], v[174:175], 0, v[66:67]
	v_lshl_add_u64 v[68:69], v[174:175], 0, v[68:69]
	v_lshl_add_u64 v[108:109], v[174:175], 0, v[70:71]
	global_load_dwordx4 v[86:89], v[66:67], off
	global_load_dwordx4 v[82:85], v[66:67], off offset:256
	global_load_dwordx4 v[78:81], v[68:69], off
	global_load_dwordx4 v[74:77], v[68:69], off offset:256
	global_load_dwordx4 v[70:73], v[108:109], off
	s_nop 0
	global_load_dwordx4 v[66:69], v[108:109], off offset:256
	s_waitcnt vmcnt(7)
	v_lshlrev_b32_e32 v108, 16, v98
	v_and_b32_e32 v109, 0xffff0000, v98
	v_lshlrev_b32_e32 v98, 16, v99
	v_and_b32_e32 v99, 0xffff0000, v99
	s_waitcnt vmcnt(6)
	v_lshlrev_b32_e32 v112, 16, v102
	v_and_b32_e32 v113, 0xffff0000, v102
	v_lshlrev_b32_e32 v102, 16, v103
	v_and_b32_e32 v103, 0xffff0000, v103
	v_pk_add_f32 v[60:61], v[60:61], v[98:99]
	v_lshlrev_b32_e32 v110, 16, v100
	v_and_b32_e32 v111, 0xffff0000, v100
	v_lshlrev_b32_e32 v100, 16, v101
	v_and_b32_e32 v101, 0xffff0000, v101
	v_lshlrev_b32_e32 v116, 16, v104
	v_and_b32_e32 v117, 0xffff0000, v104
	v_lshlrev_b32_e32 v104, 16, v105
	v_and_b32_e32 v105, 0xffff0000, v105
	v_pk_add_f32 v[58:59], v[58:59], v[108:109]
	v_pk_add_f32 v[64:65], v[64:65], v[102:103]
	v_pk_mul_f32 v[102:103], v[60:61], v[60:61]
	v_pk_add_f32 v[56:57], v[56:57], v[100:101]
	v_pk_add_f32 v[98:99], v[54:55], v[110:111]
	v_pk_add_f32 v[100:101], v[52:53], v[104:105]
	v_cvt_pk_bf16_f32 v52, v58, v59
	v_pk_fma_f32 v[58:59], v[58:59], v[58:59], v[102:103]
	v_pk_add_f32 v[62:63], v[62:63], v[112:113]
	v_pk_fma_f32 v[58:59], v[98:99], v[98:99], v[58:59]
	v_cvt_pk_bf16_f32 v53, v60, v61
	v_cvt_pk_bf16_f32 v54, v98, v99
	v_cvt_pk_bf16_f32 v55, v56, v57
	s_nop 0
	v_pk_fma_f32 v[56:57], v[56:57], v[56:57], v[58:59]
	v_pk_add_f32 v[58:59], v[50:51], v[116:117]
	v_pk_fma_f32 v[50:51], v[62:63], v[62:63], v[56:57]
	s_nop 0
	v_pk_fma_f32 v[50:51], v[64:65], v[64:65], v[50:51]
	s_nop 0
	v_pk_fma_f32 v[50:51], v[58:59], v[58:59], v[50:51]
	s_nop 0
	v_pk_fma_f32 v[50:51], v[100:101], v[100:101], v[50:51]
	s_nop 0
	v_add_f32_e32 v60, v50, v51
	ds_bpermute_b32 v61, v187, v60
	v_lshl_add_u64 v[50:51], s[96:97], 0, v[106:107]
	v_lshl_add_u64 v[56:57], v[172:173], 1, v[50:51]
	global_store_dwordx4 v[56:57], v[52:55], off sc1
	s_waitcnt lgkmcnt(0)
	v_add_f32_e32 v50, v60, v61
	ds_bpermute_b32 v51, v114, v50
	v_cvt_pk_bf16_f32 v52, v62, v63
	v_cvt_pk_bf16_f32 v53, v64, v65
	v_cvt_pk_bf16_f32 v54, v58, v59
	v_cvt_pk_bf16_f32 v55, v100, v101
	global_store_dwordx4 v[56:57], v[52:55], off offset:256 sc1
	s_and_saveexec_b64 s[16:17], s[0:1]
	s_cbranch_execz .LBB0_1258
	s_waitcnt lgkmcnt(0)
	v_add_f32_e32 v50, v50, v51
	v_fma_f32 v50, v50, s43, 0.5
	v_trunc_f32_e32 v50, v50
	v_mul_f32_e32 v51, 0x2f800000, v50
	v_floor_f32_e32 v51, v51
	v_fmac_f32_e32 v50, 0xcf800000, v51
	v_cvt_u32_f32_e32 v50, v50
	v_cvt_u32_f32_e32 v51, v51
	v_lshl_add_u64 v[52:53], v[96:97], 3, s[8:9]
	global_atomic_add_x2 v[52:53], v[50:51], off
.LBB0_1258:
	s_or_b64 exec, exec, s[16:17]
	s_waitcnt vmcnt(7)
	v_lshlrev_b32_e32 v54, 16, v87
	v_and_b32_e32 v55, 0xffff0000, v87
	v_lshlrev_b32_e32 v52, 16, v86
	v_and_b32_e32 v53, 0xffff0000, v86
	v_lshlrev_b32_e32 v56, 16, v88
	v_and_b32_e32 v57, 0xffff0000, v88
	v_lshlrev_b32_e32 v58, 16, v89
	v_and_b32_e32 v59, 0xffff0000, v89
	v_pk_add_f32 v[44:45], v[44:45], v[54:55]
	v_pk_add_f32 v[42:43], v[42:43], v[52:53]
	v_pk_add_f32 v[52:53], v[36:37], v[58:59]
	v_pk_add_f32 v[36:37], v[34:35], v[56:57]
	v_pk_mul_f32 v[34:35], v[44:45], v[44:45]
	s_waitcnt vmcnt(6)
	v_lshlrev_b32_e32 v60, 16, v82
	v_pk_fma_f32 v[34:35], v[42:43], v[42:43], v[34:35]
	v_and_b32_e32 v61, 0xffff0000, v82
	v_pk_fma_f32 v[34:35], v[36:37], v[36:37], v[34:35]
	v_lshlrev_b32_e32 v62, 16, v83
	v_and_b32_e32 v63, 0xffff0000, v83
	v_pk_fma_f32 v[54:55], v[52:53], v[52:53], v[34:35]
	v_cvt_pk_bf16_f32 v34, v42, v43
	v_cvt_pk_bf16_f32 v35, v44, v45
	v_pk_add_f32 v[44:45], v[46:47], v[60:61]
	v_lshlrev_b32_e32 v64, 16, v84
	v_and_b32_e32 v65, 0xffff0000, v84
	v_pk_add_f32 v[42:43], v[48:49], v[62:63]
	v_pk_fma_f32 v[46:47], v[44:45], v[44:45], v[54:55]
	v_lshlrev_b32_e32 v82, 16, v85
	v_and_b32_e32 v83, 0xffff0000, v85
	v_pk_add_f32 v[38:39], v[38:39], v[64:65]
	v_pk_fma_f32 v[46:47], v[42:43], v[42:43], v[46:47]
	v_pk_add_f32 v[40:41], v[40:41], v[82:83]
	v_pk_fma_f32 v[46:47], v[38:39], v[38:39], v[46:47]
	s_waitcnt lgkmcnt(0)
	v_lshlrev_b64 v[50:51], 12, v[94:95]
	v_pk_fma_f32 v[46:47], v[40:41], v[40:41], v[46:47]
	v_cvt_pk_bf16_f32 v36, v36, v37
	v_cvt_pk_bf16_f32 v37, v52, v53
	s_nop 0
	v_add_f32_e32 v48, v46, v47
	ds_bpermute_b32 v49, v187, v48
	v_lshl_add_u64 v[46:47], v[50:51], 1, s[96:97]
	v_lshl_add_u64 v[46:47], v[172:173], 1, v[46:47]
	global_store_dwordx4 v[46:47], v[34:37], off sc1
	s_waitcnt lgkmcnt(0)
	s_nop 0
	v_add_f32_e32 v34, v48, v49
	ds_bpermute_b32 v35, v114, v34
	v_cvt_pk_bf16_f32 v36, v44, v45
	v_cvt_pk_bf16_f32 v37, v42, v43
	v_cvt_pk_bf16_f32 v38, v38, v39
	v_cvt_pk_bf16_f32 v39, v40, v41
	global_store_dwordx4 v[46:47], v[36:39], off offset:256 sc1
	s_and_saveexec_b64 s[16:17], s[0:1]
	s_cbranch_execz .LBB0_1260
	s_waitcnt lgkmcnt(0)
	v_add_f32_e32 v34, v34, v35
	v_fma_f32 v34, v34, s43, 0.5
	v_trunc_f32_e32 v34, v34
	v_mul_f32_e32 v35, 0x2f800000, v34
	v_floor_f32_e32 v35, v35
	v_fmac_f32_e32 v34, 0xcf800000, v35
	v_cvt_u32_f32_e32 v34, v34
	v_cvt_u32_f32_e32 v35, v35
	v_lshl_add_u64 v[36:37], v[94:95], 3, s[8:9]
	global_atomic_add_x2 v[36:37], v[34:35], off
; __device__ __forceinline__ unsigned cvt_pk_bf16(float lo, float hi) { unsigned r; asm volatile("v_cvt_pk_bf16_f32 %0, %1, %2" : "=v"(r) : "v"(lo), "v"(hi)); return r; }
; __device__ __forceinline__ unsigned cvt_pk_bf16(float lo, float hi) { unsigned r; asm volatile("v_cvt_pk_bf16_f32 %0, %1, %2" : "=v"(r) : "v"(lo), "v"(hi)); return r; }
;     __device__ __forceinline__ void operator()(const f32x4 (&acc)[2][2][4][2], const Unit& u, int wr, int wc, int fr, int fq) const {
;     ...
;                 for (int bj = 0; bj < 2; ++bj) { const size_t off = (size_t)(row0 + ai * HALF + m * 16) * ldc + col0 + bj * HALF;
;                     if (BASE_F32) { const float* bp = (const float*)base + off; b0[m][bj] = *(const f32x4*)bp; b1[m][bj] = *(const f32x4*)(bp + 4); }
;                     else { const u32x4 r = *(const u32x4*)((const bf16_t*)base + off);
;                         b0[m][bj] = (f32x4){__uint_as_float(r.x << 16), __uint_as_float(r.x & 0xffff0000u), __uint_as_float(r.y << 16), __uint_as_float(r.y & 0xffff0000u)};
;                         b1[m][bj] = (f32x4){__uint_as_float(r.z << 16), __uint_as_float(r.z & 0xffff0000u), __uint_as_float(r.w << 16), __uint_as_float(r.w & 0xffff0000u)}; } }
; #pragma unroll
;             for (int m = 0; m < 4; ++m) { const int row = row0 + ai * HALF + m * 16; const size_t off = (size_t)row * ldc + col0; f32x2 q2 = {0.f, 0.f};
; #pragma unroll
;                 for (int bj = 0; bj < 2; ++bj) { const f32x4 v0 = acc[ai][bj][m][0] + b0[m][bj], v1 = acc[ai][bj][m][1] + b1[m][bj];
;                     { const f32x2 e0 = {v0[0], v0[1]}, e1 = {v0[2], v0[3]}, e2 = {v1[0], v1[1]}, e3 = {v1[2], v1[3]}; q2 = e0 * e0 + q2; q2 = e1 * e1 + q2; q2 = e2 * e2 + q2; q2 = e3 * e3 + q2; }
;                     u32x4 w; w.x = cvt_pk_bf16(v0[0], v0[1]); w.y = cvt_pk_bf16(v0[2], v0[3]); w.z = cvt_pk_bf16(v1[0], v1[1]); w.w = cvt_pk_bf16(v1[2], v1[3]);
;                     *(u32x4*)(out + off + bj * HALF) = w; }
;                 float q = q2.x + q2.y; q += __shfl_xor(q, 16); q += __shfl_xor(q, 32);
;                 if (fq == 0) atomicAdd(ssq + row, (ssq_t)(q * SSQ_FIX + 0.5f)); }
.LBB0_1260:
	s_or_b64 exec, exec, s[16:17]
	s_waitcnt vmcnt(7)
	v_lshlrev_b32_e32 v38, 16, v79
	v_and_b32_e32 v39, 0xffff0000, v79
	v_lshlrev_b32_e32 v36, 16, v78
	v_and_b32_e32 v37, 0xffff0000, v78
	v_lshlrev_b32_e32 v40, 16, v80
	v_and_b32_e32 v41, 0xffff0000, v80
	v_lshlrev_b32_e32 v42, 16, v81
	v_and_b32_e32 v43, 0xffff0000, v81
	v_pk_add_f32 v[28:29], v[28:29], v[38:39]
	v_pk_add_f32 v[26:27], v[26:27], v[36:37]
	v_pk_add_f32 v[36:37], v[20:21], v[42:43]
	v_pk_add_f32 v[20:21], v[18:19], v[40:41]
	v_pk_mul_f32 v[18:19], v[28:29], v[28:29]
	s_waitcnt vmcnt(6)
	v_lshlrev_b32_e32 v44, 16, v74
	v_pk_fma_f32 v[18:19], v[26:27], v[26:27], v[18:19]
	v_and_b32_e32 v45, 0xffff0000, v74
	v_pk_fma_f32 v[18:19], v[20:21], v[20:21], v[18:19]
	v_lshlrev_b32_e32 v46, 16, v75
	v_and_b32_e32 v47, 0xffff0000, v75
	v_pk_fma_f32 v[38:39], v[36:37], v[36:37], v[18:19]
	v_cvt_pk_bf16_f32 v18, v26, v27
	v_cvt_pk_bf16_f32 v19, v28, v29
	v_pk_add_f32 v[28:29], v[30:31], v[44:45]
	v_lshlrev_b32_e32 v48, 16, v76
	v_and_b32_e32 v49, 0xffff0000, v76
	v_pk_add_f32 v[26:27], v[32:33], v[46:47]
	v_pk_fma_f32 v[30:31], v[28:29], v[28:29], v[38:39]
	v_lshlrev_b32_e32 v50, 16, v77
	v_and_b32_e32 v51, 0xffff0000, v77
	v_pk_add_f32 v[22:23], v[22:23], v[48:49]
	v_pk_fma_f32 v[30:31], v[26:27], v[26:27], v[30:31]
	v_pk_add_f32 v[24:25], v[24:25], v[50:51]
	v_pk_fma_f32 v[30:31], v[22:23], v[22:23], v[30:31]
	s_waitcnt lgkmcnt(0)
	v_lshlrev_b64 v[34:35], 12, v[92:93]
	v_pk_fma_f32 v[30:31], v[24:25], v[24:25], v[30:31]
	v_cvt_pk_bf16_f32 v20, v20, v21
	v_cvt_pk_bf16_f32 v21, v36, v37
	s_nop 0
	v_add_f32_e32 v32, v30, v31
	ds_bpermute_b32 v33, v187, v32
	v_lshl_add_u64 v[30:31], v[34:35], 1, s[96:97]
	v_lshl_add_u64 v[30:31], v[172:173], 1, v[30:31]
	global_store_dwordx4 v[30:31], v[18:21], off sc1
	s_waitcnt lgkmcnt(0)
	s_nop 0
	v_add_f32_e32 v18, v32, v33
	ds_bpermute_b32 v19, v114, v18
	v_cvt_pk_bf16_f32 v20, v28, v29
	v_cvt_pk_bf16_f32 v21, v26, v27
	v_cvt_pk_bf16_f32 v22, v22, v23
	v_cvt_pk_bf16_f32 v23, v24, v25
	global_store_dwordx4 v[30:31], v[20:23], off offset:256 sc1
	s_and_saveexec_b64 s[16:17], s[0:1]
	s_cbranch_execz .LBB0_1262
	s_waitcnt lgkmcnt(0)
	v_add_f32_e32 v18, v18, v19
	v_fma_f32 v18, v18, s43, 0.5
	v_trunc_f32_e32 v18, v18
	v_mul_f32_e32 v19, 0x2f800000, v18
	v_floor_f32_e32 v19, v19
	v_fmac_f32_e32 v18, 0xcf800000, v19
	v_cvt_u32_f32_e32 v18, v18
	v_cvt_u32_f32_e32 v19, v19
	v_lshl_add_u64 v[20:21], v[92:93], 3, s[8:9]
	global_atomic_add_x2 v[20:21], v[18:19], off
.LBB0_1262:
	s_or_b64 exec, exec, s[16:17]
	s_waitcnt vmcnt(7)
	v_lshlrev_b32_e32 v22, 16, v71
	v_and_b32_e32 v23, 0xffff0000, v71
	v_lshlrev_b32_e32 v20, 16, v70
	v_and_b32_e32 v21, 0xffff0000, v70
	v_lshlrev_b32_e32 v24, 16, v72
	v_and_b32_e32 v25, 0xffff0000, v72
	v_lshlrev_b32_e32 v26, 16, v73
	v_and_b32_e32 v27, 0xffff0000, v73
	v_pk_add_f32 v[8:9], v[8:9], v[22:23]
	v_pk_add_f32 v[6:7], v[6:7], v[20:21]
	v_pk_add_f32 v[20:21], v[4:5], v[26:27]
	v_pk_add_f32 v[4:5], v[2:3], v[24:25]
	v_pk_mul_f32 v[2:3], v[8:9], v[8:9]
	s_waitcnt vmcnt(6)
	v_lshlrev_b32_e32 v28, 16, v66
	v_pk_fma_f32 v[2:3], v[6:7], v[6:7], v[2:3]
	v_and_b32_e32 v29, 0xffff0000, v66
	v_pk_fma_f32 v[2:3], v[4:5], v[4:5], v[2:3]
	v_lshlrev_b32_e32 v30, 16, v67
	v_and_b32_e32 v31, 0xffff0000, v67
	v_lshlrev_b32_e32 v32, 16, v68
	v_and_b32_e32 v33, 0xffff0000, v68
	v_pk_fma_f32 v[22:23], v[20:21], v[20:21], v[2:3]
	v_cvt_pk_bf16_f32 v2, v6, v7
	v_cvt_pk_bf16_f32 v3, v8, v9
	v_pk_add_f32 v[8:9], v[10:11], v[28:29]
	v_pk_add_f32 v[6:7], v[12:13], v[30:31]
	v_pk_add_f32 v[12:13], v[14:15], v[32:33]
	v_pk_fma_f32 v[14:15], v[8:9], v[8:9], v[22:23]
	v_lshlrev_b32_e32 v34, 16, v69
	v_and_b32_e32 v35, 0xffff0000, v69
	v_pk_fma_f32 v[14:15], v[6:7], v[6:7], v[14:15]
	v_pk_add_f32 v[10:11], v[16:17], v[34:35]
	v_pk_fma_f32 v[14:15], v[12:13], v[12:13], v[14:15]
	s_waitcnt lgkmcnt(0)
	v_lshlrev_b64 v[18:19], 12, v[90:91]
	v_pk_fma_f32 v[14:15], v[10:11], v[10:11], v[14:15]
	v_cvt_pk_bf16_f32 v4, v4, v5
	v_cvt_pk_bf16_f32 v5, v20, v21
	s_nop 0
	v_add_f32_e32 v16, v14, v15
	ds_bpermute_b32 v17, v187, v16
	v_lshl_add_u64 v[14:15], v[18:19], 1, s[96:97]
	v_lshl_add_u64 v[14:15], v[172:173], 1, v[14:15]
	global_store_dwordx4 v[14:15], v[2:5], off sc1
	s_waitcnt lgkmcnt(0)
	s_nop 0
	v_add_f32_e32 v2, v16, v17
	ds_bpermute_b32 v3, v114, v2
	v_cvt_pk_bf16_f32 v4, v8, v9
	v_cvt_pk_bf16_f32 v5, v6, v7
	v_cvt_pk_bf16_f32 v6, v12, v13
	v_cvt_pk_bf16_f32 v7, v10, v11
	global_store_dwordx4 v[14:15], v[4:7], off offset:256 sc1
	s_and_saveexec_b64 s[16:17], s[0:1]
	s_cbranch_execz .LBB0_1264
	s_waitcnt lgkmcnt(0)
	v_add_f32_e32 v2, v2, v3
	v_fma_f32 v2, v2, s43, 0.5
	v_trunc_f32_e32 v2, v2
	v_mul_f32_e32 v3, 0x2f800000, v2
	v_floor_f32_e32 v3, v3
	v_fmac_f32_e32 v2, 0xcf800000, v3
	v_cvt_u32_f32_e32 v2, v2
	v_cvt_u32_f32_e32 v3, v3
	v_lshl_add_u64 v[4:5], v[90:91], 3, s[8:9]
	global_atomic_add_x2 v[4:5], v[2:3], off

; __device__ __forceinline__ unsigned cvt_pk_bf16(float lo, float hi) { unsigned r; asm volatile("v_cvt_pk_bf16_f32 %0, %1, %2" : "=v"(r) : "v"(lo), "v"(hi)); return r; }
; __device__ __forceinline__ unsigned cvt_pk_bf16(float lo, float hi) { unsigned r; asm volatile("v_cvt_pk_bf16_f32 %0, %1, %2" : "=v"(r) : "v"(lo), "v"(hi)); return r; }
; __device__ __forceinline__ float ssq_rstd(const ssq_t* ssq, int row) { return __builtin_amdgcn_rsqf((float)ssq[row] * (SSQ_UNFIX * RMS_INV_D) + RMS_EPS); }
;     __device__ __forceinline__ void operator()(const f32x4 (&acc)[2][2][4][2], const Unit& u, int wr, int wc, int fr, int fq) const {
;     ...
;             for (int m = 0; m < 4; ++m) rs[ai][m] = SCALE ? ssq_rstd(ssq, row0 + ai * HALF + m * 16) : 1.0f;
; #pragma unroll
;         for (int ai = 0; ai < 2; ++ai)
; #pragma unroll
;             for (int m = 0; m < 4; ++m) { const int row = row0 + ai * HALF + m * 16; bf16_t* rowp = O + (size_t)row * ldc + col0;
; #pragma unroll
;                 for (int bj = 0; bj < 2; ++bj) { const f32x2 r2 = {rs[ai][m], rs[ai][m]}; const f32x4 a0 = acc[ai][bj][m][0], a1 = acc[ai][bj][m][1];
;                     const f32x2 p0 = (f32x2){a0[0], a0[1]} * r2, p1 = (f32x2){a0[2], a0[3]} * r2, p2 = (f32x2){a1[0], a1[1]} * r2, p3 = (f32x2){a1[2], a1[3]} * r2;
;                     u32x4 w; w.x = cvt_pk_bf16(p0.x, p0.y); w.y = cvt_pk_bf16(p1.x, p1.y); w.z = cvt_pk_bf16(p2.x, p2.y); w.w = cvt_pk_bf16(p3.x, p3.y);
;                     *(u32x4*)(rowp + bj * HALF) = w; } }
.Lepi_rest_1335:
	v_add_u32_e32 v157, 0x80, v150
	v_add_u32_e32 v159, 0x90, v150
	v_add_u32_e32 v163, 0xa0, v150
	s_andn2_b64 vcc, exec, s[0:1]
	s_mov_b64 s[0:1], -1
	s_waitcnt vmcnt(0)
	v_ffbh_u32_e32 v146, v171
	v_min_u32_e32 v146, 32, v146
	v_ffbh_u32_e32 v160, v167
	v_lshlrev_b64 v[170:171], v146, v[170:171]
	v_min_u32_e32 v160, 32, v160
	v_ffbh_u32_e32 v165, v169
	v_ffbh_u32_e32 v180, v179
	v_min_u32_e32 v170, 1, v170
	v_lshlrev_b64 v[166:167], v160, v[166:167]
	v_min_u32_e32 v165, 32, v165
	v_min_u32_e32 v180, 32, v180
	v_or_b32_e32 v170, v171, v170
	v_min_u32_e32 v166, 1, v166
	v_lshlrev_b64 v[168:169], v165, v[168:169]
	v_lshlrev_b64 v[178:179], v180, v[178:179]
	v_cvt_f32_u32_e32 v170, v170
	v_or_b32_e32 v166, v167, v166
	v_min_u32_e32 v168, 1, v168
	v_min_u32_e32 v171, 1, v178
	v_cvt_f32_u32_e32 v166, v166
	v_ffbh_u32_e32 v151, v173
	v_or_b32_e32 v167, v169, v168
	v_or_b32_e32 v168, v179, v171
	v_min_u32_e32 v151, 32, v151
	v_ffbh_u32_e32 v181, v149
	v_sub_u32_e32 v146, 32, v146
	v_cvt_f32_u32_e32 v167, v167
	v_cvt_f32_u32_e32 v168, v168
	v_lshlrev_b64 v[172:173], v151, v[172:173]
	v_min_u32_e32 v181, 32, v181
	v_sub_u32_e32 v160, 32, v160
	v_ldexp_f32 v146, v170, v146
	v_min_u32_e32 v172, 1, v172
	v_lshlrev_b64 v[148:149], v181, v[148:149]
	v_fmamk_f32 v146, v146, 0x2d800000, v161
	v_ldexp_f32 v160, v166, v160
	v_ffbh_u32_e32 v152, v175
	v_ffbh_u32_e32 v154, v177
	v_sub_u32_e32 v165, 32, v165
	v_sub_u32_e32 v180, 32, v180
	v_or_b32_e32 v172, v173, v172
	v_min_u32_e32 v148, 1, v148
	v_rsq_f32_e32 v166, v146
	v_fmamk_f32 v146, v160, 0x2d800000, v161
	v_min_u32_e32 v152, 32, v152
	v_min_u32_e32 v154, 32, v154
	v_cvt_f32_u32_e32 v169, v172
	v_ldexp_f32 v165, v167, v165
	v_ldexp_f32 v167, v168, v180
	v_rsq_f32_e32 v168, v146
	v_or_b32_e32 v146, v149, v148
	v_lshlrev_b64 v[174:175], v152, v[174:175]
	v_lshlrev_b64 v[176:177], v154, v[176:177]
	v_cvt_f32_u32_e32 v146, v146
	v_min_u32_e32 v174, 1, v174
	v_min_u32_e32 v176, 1, v176
	v_sub_u32_e32 v151, 32, v151
	v_or_b32_e32 v173, v175, v174
	v_or_b32_e32 v174, v177, v176
	v_cvt_f32_u32_e32 v172, v174
	v_ldexp_f32 v151, v169, v151
	v_sub_u32_e32 v148, 32, v181
	v_lshl_or_b32 v174, s62, 8, v153
	v_fmamk_f32 v151, v151, 0x2d800000, v161
	v_fmamk_f32 v165, v165, 0x2d800000, v161
	v_ldexp_f32 v146, v146, v148
	v_ashrrev_i32_e32 v175, 31, v174
	v_mov_b64_e32 v[148:149], s[38:39]
	v_fmamk_f32 v167, v167, 0x2d800000, v161
	v_rsq_f32_e32 v160, v151
	v_rsq_f32_e32 v170, v165
	v_add_u32_e32 v165, 0xb0, v150
	v_mad_i64_i32 v[176:177], s[20:21], v150, s53, v[148:149]
	v_lshlrev_b64 v[150:151], 1, v[174:175]
	v_lshl_add_u64 v[174:175], v[176:177], 0, v[150:151]
	v_pk_mul_f32 v[118:119], v[118:119], v[166:167] op_sel_hi:[1,0]
	v_pk_mul_f32 v[120:121], v[120:121], v[166:167] op_sel_hi:[1,0]
	v_pk_mul_f32 v[176:177], v[114:115], v[166:167] op_sel_hi:[1,0]
	v_cvt_pk_bf16_f32 v114, v118, v119
	v_cvt_pk_bf16_f32 v115, v120, v121
	v_sub_u32_e32 v154, 32, v154
	v_pk_mul_f32 v[178:179], v[116:117], v[166:167] op_sel_hi:[1,0]
	v_cvt_pk_bf16_f32 v116, v176, v177
	v_ldexp_f32 v154, v172, v154
	v_cvt_pk_bf16_f32 v117, v178, v179
	global_store_dwordx4 v[174:175], v[114:117], off sc1
	v_fmamk_f32 v169, v154, 0x2d800000, v161
	v_pk_mul_f32 v[118:119], v[122:123], v[166:167] op_sel_hi:[1,0]
	v_pk_mul_f32 v[114:115], v[126:127], v[166:167] op_sel_hi:[1,0]
	v_pk_mul_f32 v[116:117], v[128:129], v[166:167] op_sel_hi:[1,0]
	v_cvt_pk_bf16_f32 v114, v114, v115
	v_pk_mul_f32 v[120:121], v[124:125], v[166:167] op_sel_hi:[1,0]
	v_cvt_pk_bf16_f32 v115, v116, v117
	v_cvt_pk_bf16_f32 v116, v118, v119
	v_cvt_f32_u32_e32 v171, v173
	v_cvt_pk_bf16_f32 v117, v120, v121
	global_store_dwordx4 v[174:175], v[114:117], off offset:256 sc1
	v_pk_mul_f32 v[102:103], v[102:103], v[168:169] op_sel_hi:[1,0]
	v_pk_mul_f32 v[104:105], v[104:105], v[168:169] op_sel_hi:[1,0]
	v_mad_i64_i32 v[114:115], s[20:21], v162, s53, v[148:149]
	v_lshl_add_u64 v[114:115], v[114:115], 0, v[150:151]
	v_pk_mul_f32 v[116:117], v[98:99], v[168:169] op_sel_hi:[1,0]
	v_cvt_pk_bf16_f32 v98, v102, v103
	v_cvt_pk_bf16_f32 v99, v104, v105
	v_pk_mul_f32 v[118:119], v[100:101], v[168:169] op_sel_hi:[1,0]
	v_cvt_pk_bf16_f32 v100, v116, v117
	v_pk_mul_f32 v[102:103], v[106:107], v[168:169] op_sel_hi:[1,0]
	v_cvt_pk_bf16_f32 v101, v118, v119
	global_store_dwordx4 v[114:115], v[98:101], off sc1
	v_pk_mul_f32 v[104:105], v[108:109], v[168:169] op_sel_hi:[1,0]
	v_rsq_f32_e32 v172, v167
	v_pk_mul_f32 v[98:99], v[110:111], v[168:169] op_sel_hi:[1,0]
	v_pk_mul_f32 v[100:101], v[112:113], v[168:169] op_sel_hi:[1,0]
	v_cvt_pk_bf16_f32 v98, v98, v99
	v_pk_mul_f32 v[86:87], v[86:87], v[170:171] op_sel_hi:[1,0]
	v_cvt_pk_bf16_f32 v99, v100, v101
	v_cvt_pk_bf16_f32 v100, v102, v103
	v_cvt_pk_bf16_f32 v101, v104, v105
	global_store_dwordx4 v[114:115], v[98:101], off offset:256 sc1
	v_pk_mul_f32 v[88:89], v[88:89], v[170:171] op_sel_hi:[1,0]
	v_pk_mul_f32 v[102:103], v[84:85], v[170:171] op_sel_hi:[1,0]
	v_mad_i64_i32 v[98:99], s[20:21], v158, s53, v[148:149]
	v_lshl_add_u64 v[98:99], v[98:99], 0, v[150:151]
	v_pk_mul_f32 v[100:101], v[82:83], v[170:171] op_sel_hi:[1,0]
	v_cvt_pk_bf16_f32 v82, v86, v87
	v_cvt_pk_bf16_f32 v83, v88, v89
	v_pk_mul_f32 v[86:87], v[90:91], v[170:171] op_sel_hi:[1,0]
	v_cvt_pk_bf16_f32 v84, v100, v101
	v_cvt_pk_bf16_f32 v85, v102, v103
	global_store_dwordx4 v[98:99], v[82:85], off sc1
	v_pk_mul_f32 v[88:89], v[92:93], v[170:171] op_sel_hi:[1,0]
	v_pk_mul_f32 v[70:71], v[70:71], v[172:173] op_sel_hi:[1,0]
	v_pk_mul_f32 v[82:83], v[94:95], v[170:171] op_sel_hi:[1,0]
	v_pk_mul_f32 v[84:85], v[96:97], v[170:171] op_sel_hi:[1,0]
	v_cvt_pk_bf16_f32 v82, v82, v83
; __device__ __forceinline__ unsigned cvt_pk_bf16(float lo, float hi) { unsigned r; asm volatile("v_cvt_pk_bf16_f32 %0, %1, %2" : "=v"(r) : "v"(lo), "v"(hi)); return r; }
; __device__ __forceinline__ unsigned cvt_pk_bf16(float lo, float hi) { unsigned r; asm volatile("v_cvt_pk_bf16_f32 %0, %1, %2" : "=v"(r) : "v"(lo), "v"(hi)); return r; }
; #define PG8_BAR __builtin_amdgcn_s_barrier()
;     __device__ __forceinline__ void operator()(const f32x4 (&acc)[2][2][4][2], const Unit& u, int wr, int wc, int fr, int fq) const {
;     ...
;             for (int m = 0; m < 4; ++m) { const int row = row0 + ai * HALF + m * 16; bf16_t* rowp = O + (size_t)row * ldc + col0;
; #pragma unroll
;                 for (int bj = 0; bj < 2; ++bj) { const f32x2 r2 = {rs[ai][m], rs[ai][m]}; const f32x4 a0 = acc[ai][bj][m][0], a1 = acc[ai][bj][m][1];
;                     const f32x2 p0 = (f32x2){a0[0], a0[1]} * r2, p1 = (f32x2){a0[2], a0[3]} * r2, p2 = (f32x2){a1[0], a1[1]} * r2, p3 = (f32x2){a1[2], a1[3]} * r2;
;                     u32x4 w; w.x = cvt_pk_bf16(p0.x, p0.y); w.y = cvt_pk_bf16(p1.x, p1.y); w.z = cvt_pk_bf16(p2.x, p2.y); w.w = cvt_pk_bf16(p3.x, p3.y);
;                     *(u32x4*)(rowp + bj * HALF) = w; } }
; template <class Epi, class Sched, bool ALIGN_EPI = false, bool SP2 = false>
; __device__ __forceinline__ void gemm_phase(PG8_LAS unsigned char* lds, const Gemm g, const Sched& S, const Epi& E) {
;     ...
; #pragma unroll
;         for (int a = 0; a < 2; ++a)
; #pragma unroll
;             for (int b = 0; b < 2; ++b)
; #pragma unroll
;                 for (int m = 0; m < 4; ++m)
; #pragma unroll
;                     for (int n = 0; n < 2; ++n) { d64x2 z_; asm volatile("v_mov_b64 %0, 0\n\tv_mov_b64 %1, 0" : "=v"(z_.x), "=v"(z_.y)); acc[a][b][m][n] = __builtin_bit_cast(f32x4, z_); }
;         cur = nxt; cA = nA; cB = nB; ++ui;
;         if constexpr (ALIGN_EPI) { if (wr == 1) PG8_BAR; }
	v_pk_mul_f32 v[72:73], v[72:73], v[172:173] op_sel_hi:[1,0]
	v_cvt_pk_bf16_f32 v83, v84, v85
	v_cvt_pk_bf16_f32 v84, v86, v87
	v_cvt_pk_bf16_f32 v85, v88, v89
	global_store_dwordx4 v[98:99], v[82:85], off offset:256 sc1
	v_sub_u32_e32 v152, 32, v152
	v_pk_mul_f32 v[86:87], v[68:69], v[172:173] op_sel_hi:[1,0]
	v_mad_i64_i32 v[82:83], s[20:21], v156, s53, v[148:149]
	v_lshl_add_u64 v[82:83], v[82:83], 0, v[150:151]
	v_pk_mul_f32 v[84:85], v[66:67], v[172:173] op_sel_hi:[1,0]
	v_cvt_pk_bf16_f32 v66, v70, v71
	v_cvt_pk_bf16_f32 v67, v72, v73
	v_ldexp_f32 v152, v171, v152
	v_cvt_pk_bf16_f32 v68, v84, v85
	v_cvt_pk_bf16_f32 v69, v86, v87
	global_store_dwordx4 v[82:83], v[66:69], off sc1
	v_fmamk_f32 v152, v152, 0x2d800000, v161
	v_pk_mul_f32 v[70:71], v[74:75], v[172:173] op_sel_hi:[1,0]
	v_pk_mul_f32 v[66:67], v[78:79], v[172:173] op_sel_hi:[1,0]
	v_pk_mul_f32 v[68:69], v[80:81], v[172:173] op_sel_hi:[1,0]
	v_cvt_pk_bf16_f32 v66, v66, v67
	v_pk_mul_f32 v[72:73], v[76:77], v[172:173] op_sel_hi:[1,0]
	v_cvt_pk_bf16_f32 v67, v68, v69
	v_cvt_pk_bf16_f32 v68, v70, v71
	v_rsq_f32_e32 v154, v152
	v_cvt_pk_bf16_f32 v69, v72, v73
	global_store_dwordx4 v[82:83], v[66:69], off offset:256 sc1
	v_pk_mul_f32 v[54:55], v[54:55], v[160:161] op_sel_hi:[1,0]
	v_pk_mul_f32 v[56:57], v[56:57], v[160:161] op_sel_hi:[1,0]
	v_mad_i64_i32 v[66:67], s[20:21], v157, s53, v[148:149]
	v_lshl_add_u64 v[66:67], v[66:67], 0, v[150:151]
	v_pk_mul_f32 v[68:69], v[50:51], v[160:161] op_sel_hi:[1,0]
	v_cvt_pk_bf16_f32 v50, v54, v55
	v_cvt_pk_bf16_f32 v51, v56, v57
	v_pk_mul_f32 v[70:71], v[52:53], v[160:161] op_sel_hi:[1,0]
	v_cvt_pk_bf16_f32 v52, v68, v69
	v_pk_mul_f32 v[54:55], v[58:59], v[160:161] op_sel_hi:[1,0]
	v_cvt_pk_bf16_f32 v53, v70, v71
	global_store_dwordx4 v[66:67], v[50:53], off sc1
	v_pk_mul_f32 v[56:57], v[60:61], v[160:161] op_sel_hi:[1,0]
	v_rsq_f32_e32 v152, v169
	v_pk_mul_f32 v[50:51], v[62:63], v[160:161] op_sel_hi:[1,0]
	v_pk_mul_f32 v[52:53], v[64:65], v[160:161] op_sel_hi:[1,0]
	v_cvt_pk_bf16_f32 v50, v50, v51
	v_pk_mul_f32 v[38:39], v[38:39], v[154:155] op_sel_hi:[1,0]
	v_cvt_pk_bf16_f32 v51, v52, v53
	v_cvt_pk_bf16_f32 v52, v54, v55
	v_cvt_pk_bf16_f32 v53, v56, v57
	global_store_dwordx4 v[66:67], v[50:53], off offset:256 sc1
	v_pk_mul_f32 v[40:41], v[40:41], v[154:155] op_sel_hi:[1,0]
	v_pk_mul_f32 v[54:55], v[36:37], v[154:155] op_sel_hi:[1,0]
	v_mad_i64_i32 v[50:51], s[20:21], v159, s53, v[148:149]
	v_lshl_add_u64 v[50:51], v[50:51], 0, v[150:151]
	v_pk_mul_f32 v[52:53], v[34:35], v[154:155] op_sel_hi:[1,0]
	v_cvt_pk_bf16_f32 v34, v38, v39
	v_cvt_pk_bf16_f32 v35, v40, v41
	v_fmamk_f32 v146, v146, 0x2d800000, v161
	v_cvt_pk_bf16_f32 v36, v52, v53
	v_cvt_pk_bf16_f32 v37, v54, v55
	global_store_dwordx4 v[50:51], v[34:37], off sc1
	v_pk_mul_f32 v[38:39], v[42:43], v[154:155] op_sel_hi:[1,0]
	v_pk_mul_f32 v[40:41], v[44:45], v[154:155] op_sel_hi:[1,0]
	v_pk_mul_f32 v[34:35], v[46:47], v[154:155] op_sel_hi:[1,0]
	v_pk_mul_f32 v[36:37], v[48:49], v[154:155] op_sel_hi:[1,0]
	v_cvt_pk_bf16_f32 v34, v34, v35
	v_rsq_f32_e32 v146, v146
	v_cvt_pk_bf16_f32 v35, v36, v37
	v_cvt_pk_bf16_f32 v36, v38, v39
	v_cvt_pk_bf16_f32 v37, v40, v41
	global_store_dwordx4 v[50:51], v[34:37], off offset:256 sc1
	v_pk_mul_f32 v[22:23], v[22:23], v[152:153] op_sel_hi:[1,0]
	v_pk_mul_f32 v[24:25], v[24:25], v[152:153] op_sel_hi:[1,0]
	v_mad_i64_i32 v[34:35], s[20:21], v163, s53, v[148:149]
	v_lshl_add_u64 v[34:35], v[34:35], 0, v[150:151]
	v_pk_mul_f32 v[36:37], v[18:19], v[152:153] op_sel_hi:[1,0]
	v_cvt_pk_bf16_f32 v18, v22, v23
	v_cvt_pk_bf16_f32 v19, v24, v25
	v_pk_mul_f32 v[38:39], v[20:21], v[152:153] op_sel_hi:[1,0]
	v_cvt_pk_bf16_f32 v20, v36, v37
	v_pk_mul_f32 v[22:23], v[26:27], v[152:153] op_sel_hi:[1,0]
	v_cvt_pk_bf16_f32 v21, v38, v39
	global_store_dwordx4 v[34:35], v[18:21], off sc1
	v_pk_mul_f32 v[24:25], v[28:29], v[152:153] op_sel_hi:[1,0]
	v_pk_mul_f32 v[6:7], v[6:7], v[146:147] op_sel_hi:[1,0]
	v_pk_mul_f32 v[18:19], v[30:31], v[152:153] op_sel_hi:[1,0]
	v_pk_mul_f32 v[20:21], v[32:33], v[152:153] op_sel_hi:[1,0]
	v_cvt_pk_bf16_f32 v18, v18, v19
	v_pk_mul_f32 v[8:9], v[8:9], v[146:147] op_sel_hi:[1,0]
	v_cvt_pk_bf16_f32 v19, v20, v21
	v_cvt_pk_bf16_f32 v20, v22, v23
	v_cvt_pk_bf16_f32 v21, v24, v25
	global_store_dwordx4 v[34:35], v[18:21], off offset:256 sc1
	v_pk_mul_f32 v[22:23], v[4:5], v[146:147] op_sel_hi:[1,0]
	s_nop 0
	v_mad_i64_i32 v[18:19], s[20:21], v165, s53, v[148:149]
	v_lshl_add_u64 v[18:19], v[18:19], 0, v[150:151]
	v_pk_mul_f32 v[20:21], v[2:3], v[146:147] op_sel_hi:[1,0]
	v_cvt_pk_bf16_f32 v2, v6, v7
	v_cvt_pk_bf16_f32 v3, v8, v9
	v_pk_mul_f32 v[6:7], v[14:15], v[146:147] op_sel_hi:[1,0]
	v_cvt_pk_bf16_f32 v4, v20, v21
	v_cvt_pk_bf16_f32 v5, v22, v23
	global_store_dwordx4 v[18:19], v[2:5], off sc1
	v_pk_mul_f32 v[8:9], v[16:17], v[146:147] op_sel_hi:[1,0]
	s_nop 0
	v_pk_mul_f32 v[2:3], v[10:11], v[146:147] op_sel_hi:[1,0]
	v_pk_mul_f32 v[4:5], v[12:13], v[146:147] op_sel_hi:[1,0]
	v_cvt_pk_bf16_f32 v2, v2, v3
	s_nop 0
	v_cvt_pk_bf16_f32 v3, v4, v5
	v_cvt_pk_bf16_f32 v4, v6, v7
	v_cvt_pk_bf16_f32 v5, v8, v9
	global_store_dwordx4 v[18:19], v[2:5], off offset:256 sc1
	s_cbranch_vccnz .LBB0_1328
	s_andn2_b64 vcc, exec, s[2:3]
	v_mov_b64 v[118:119], 0
	v_mov_b64 v[120:121], 0
	v_mov_b64 v[114:115], 0
	v_mov_b64 v[116:117], 0
	v_mov_b64 v[102:103], 0
	v_mov_b64 v[104:105], 0
	v_mov_b64 v[98:99], 0
	v_mov_b64 v[100:101], 0
	v_mov_b64 v[86:87], 0
	v_mov_b64 v[88:89], 0
	v_mov_b64 v[82:83], 0
	v_mov_b64 v[84:85], 0
	v_mov_b64 v[70:71], 0
	v_mov_b64 v[72:73], 0
	v_mov_b64 v[66:67], 0
	v_mov_b64 v[68:69], 0
	v_mov_b64 v[126:127], 0
	v_mov_b64 v[128:129], 0
	v_mov_b64 v[122:123], 0
	v_mov_b64 v[124:125], 0
	v_mov_b64 v[110:111], 0
	v_mov_b64 v[112:113], 0
	v_mov_b64 v[106:107], 0
	v_mov_b64 v[108:109], 0
	v_mov_b64 v[94:95], 0
	v_mov_b64 v[96:97], 0
	v_mov_b64 v[90:91], 0
	v_mov_b64 v[92:93], 0
	v_mov_b64 v[78:79], 0
	v_mov_b64 v[80:81], 0
	v_mov_b64 v[74:75], 0
	v_mov_b64 v[76:77], 0
	v_mov_b64 v[54:55], 0
	v_mov_b64 v[56:57], 0
	v_mov_b64 v[50:51], 0
	v_mov_b64 v[52:53], 0
	v_mov_b64 v[38:39], 0
	v_mov_b64 v[40:41], 0
	v_mov_b64 v[34:35], 0
	v_mov_b64 v[36:37], 0
	v_mov_b64 v[22:23], 0
	v_mov_b64 v[24:25], 0
	v_mov_b64 v[18:19], 0
	v_mov_b64 v[20:21], 0
	v_mov_b64 v[6:7], 0
	v_mov_b64 v[8:9], 0
	v_mov_b64 v[2:3], 0
	v_mov_b64 v[4:5], 0
	v_mov_b64 v[62:63], 0
	v_mov_b64 v[64:65], 0
	v_mov_b64 v[58:59], 0
	v_mov_b64 v[60:61], 0
	v_mov_b64 v[46:47], 0
	v_mov_b64 v[48:49], 0
	v_mov_b64 v[42:43], 0
	v_mov_b64 v[44:45], 0
	v_mov_b64 v[30:31], 0
	v_mov_b64 v[32:33], 0
	v_mov_b64 v[26:27], 0
	v_mov_b64 v[28:29], 0
	v_mov_b64 v[10:11], 0
	v_mov_b64 v[12:13], 0
	v_mov_b64 v[14:15], 0
	v_mov_b64 v[16:17], 0
	s_cbranch_vccnz .LBB0_1327
	s_barrier
	s_branch .LBB0_1327

; __device__ __forceinline__ unsigned cvt_pk_bf16(float lo, float hi) { unsigned r; asm volatile("v_cvt_pk_bf16_f32 %0, %1, %2" : "=v"(r) : "v"(lo), "v"(hi)); return r; }
; __device__ __forceinline__ unsigned cvt_pk_bf16(float lo, float hi) { unsigned r; asm volatile("v_cvt_pk_bf16_f32 %0, %1, %2" : "=v"(r) : "v"(lo), "v"(hi)); return r; }
;     __device__ __forceinline__ void operator()(const f32x4 (&acc)[2][2][4][2], const Unit& u, int wr, int wc, int fr, int fq) const {
;     ...
;                 for (int bj = 0; bj < 2; ++bj) { const size_t off = (size_t)(row0 + ai * HALF + m * 16) * ldc + col0 + bj * HALF;
;                     if (BASE_F32) { const float* bp = (const float*)base + off; b0[m][bj] = *(const f32x4*)bp; b1[m][bj] = *(const f32x4*)(bp + 4); }
;                     else { const u32x4 r = *(const u32x4*)((const bf16_t*)base + off);
;                         b0[m][bj] = (f32x4){__uint_as_float(r.x << 16), __uint_as_float(r.x & 0xffff0000u), __uint_as_float(r.y << 16), __uint_as_float(r.y & 0xffff0000u)};
;                         b1[m][bj] = (f32x4){__uint_as_float(r.z << 16), __uint_as_float(r.z & 0xffff0000u), __uint_as_float(r.w << 16), __uint_as_float(r.w & 0xffff0000u)}; } }
; #pragma unroll
;             for (int m = 0; m < 4; ++m) { const int row = row0 + ai * HALF + m * 16; const size_t off = (size_t)row * ldc + col0; f32x2 q2 = {0.f, 0.f};
; #pragma unroll
;                 for (int bj = 0; bj < 2; ++bj) { const f32x4 v0 = acc[ai][bj][m][0] + b0[m][bj], v1 = acc[ai][bj][m][1] + b1[m][bj];
;                     { const f32x2 e0 = {v0[0], v0[1]}, e1 = {v0[2], v0[3]}, e2 = {v1[0], v1[1]}, e3 = {v1[2], v1[3]}; q2 = e0 * e0 + q2; q2 = e1 * e1 + q2; q2 = e2 * e2 + q2; q2 = e3 * e3 + q2; }
;                     u32x4 w; w.x = cvt_pk_bf16(v0[0], v0[1]); w.y = cvt_pk_bf16(v0[2], v0[3]); w.z = cvt_pk_bf16(v1[0], v1[1]); w.w = cvt_pk_bf16(v1[2], v1[3]);
;                     *(u32x4*)(out + off + bj * HALF) = w; }
;                 float q = q2.x + q2.y; q += __shfl_xor(q, 16); q += __shfl_xor(q, 32);
;                 if (fq == 0) atomicAdd(ssq + row, (ssq_t)(q * SSQ_FIX + 0.5f)); }
.Lepi_rest_1598:
	v_and_b32_e32 v200, 64, v186
	v_xor_b32_e32 v187, 16, v186
	v_add_u32_e32 v200, 64, v200
	v_xor_b32_e32 v201, 32, v186
	v_cmp_lt_i32_e32 vcc, v187, v200
	v_lshl_add_u64 v[198:199], s[96:97], 0, v[198:199]
	v_lshl_add_u64 v[196:197], v[198:199], 0, v[196:197]
	v_cndmask_b32_e32 v187, v186, v187, vcc
	v_cmp_lt_i32_e32 vcc, v201, v200
	v_lshlrev_b32_e32 v187, 2, v187
	s_waitcnt vmcnt(0)
	v_lshlrev_b32_e32 v198, 16, v188
	v_and_b32_e32 v199, 0xffff0000, v188
	v_lshlrev_b32_e32 v188, 16, v189
	v_and_b32_e32 v189, 0xffff0000, v189
	v_cndmask_b32_e32 v206, v186, v201, vcc
	v_lshlrev_b32_e32 v200, 16, v190
	v_and_b32_e32 v201, 0xffff0000, v190
	v_lshlrev_b32_e32 v190, 16, v191
	v_and_b32_e32 v191, 0xffff0000, v191
	v_pk_add_f32 v[116:117], v[116:117], v[188:189]
	v_pk_add_f32 v[188:189], v[114:115], v[198:199]
	v_pk_add_f32 v[120:121], v[120:121], v[190:191]
	v_pk_mul_f32 v[190:191], v[116:117], v[116:117]
	v_pk_add_f32 v[118:119], v[118:119], v[200:201]
	v_cvt_pk_bf16_f32 v114, v188, v189
	v_cvt_pk_bf16_f32 v115, v116, v117
	v_pk_fma_f32 v[116:117], v[188:189], v[188:189], v[190:191]
	v_lshlrev_b32_e32 v202, 16, v192
	v_and_b32_e32 v203, 0xffff0000, v192
	v_pk_fma_f32 v[116:117], v[118:119], v[118:119], v[116:117]
	v_lshlrev_b32_e32 v192, 16, v193
	v_and_b32_e32 v193, 0xffff0000, v193
	v_pk_add_f32 v[122:123], v[122:123], v[202:203]
	v_pk_fma_f32 v[116:117], v[120:121], v[120:121], v[116:117]
	v_lshlrev_b32_e32 v204, 16, v194
	v_and_b32_e32 v205, 0xffff0000, v194
	v_pk_add_f32 v[124:125], v[124:125], v[192:193]
	v_pk_fma_f32 v[116:117], v[122:123], v[122:123], v[116:117]
	v_lshlrev_b32_e32 v194, 16, v195
	v_and_b32_e32 v195, 0xffff0000, v195
	v_pk_add_f32 v[126:127], v[126:127], v[204:205]
	v_pk_fma_f32 v[116:117], v[124:125], v[124:125], v[116:117]
	v_pk_add_f32 v[128:129], v[128:129], v[194:195]
	v_pk_fma_f32 v[116:117], v[126:127], v[126:127], v[116:117]
	s_nop 0
	v_pk_fma_f32 v[116:117], v[128:129], v[128:129], v[116:117]
	s_nop 0
	v_add_f32_e32 v188, v116, v117
	ds_bpermute_b32 v189, v187, v188
	v_cvt_pk_bf16_f32 v116, v118, v119
	v_cvt_pk_bf16_f32 v117, v120, v121
	global_store_dwordx4 v[196:197], v[114:117], off sc1
	v_cvt_pk_bf16_f32 v118, v122, v123
	v_cvt_pk_bf16_f32 v119, v124, v125
	v_cvt_pk_bf16_f32 v120, v126, v127
	v_cvt_pk_bf16_f32 v121, v128, v129
	global_store_dwordx4 v[196:197], v[118:121], off offset:256 sc1
	s_waitcnt lgkmcnt(0)
	v_add_f32_e32 v115, v188, v189
	v_lshlrev_b32_e32 v114, 2, v206
	ds_bpermute_b32 v116, v114, v115
	s_and_saveexec_b64 s[20:21], s[0:1]
	s_cbranch_execz .LBB0_1600
	s_waitcnt lgkmcnt(0)
	v_add_f32_e32 v115, v115, v116
	v_fma_f32 v115, v115, s50, 0.5
	v_trunc_f32_e32 v115, v115
	v_mul_f32_e32 v116, 0x2f800000, v115
	v_floor_f32_e32 v117, v116
	v_fmac_f32_e32 v115, 0xcf800000, v117
	v_cvt_u32_f32_e32 v116, v115
	v_cvt_u32_f32_e32 v117, v117
	v_lshl_add_u64 v[118:119], v[176:177], 3, s[6:7]
	global_atomic_add_x2 v[118:119], v[116:117], off
.LBB0_1600:
	s_or_b64 exec, exec, s[20:21]
	v_lshlrev_b32_e32 v120, 16, v151
	v_and_b32_e32 v121, 0xffff0000, v151
	v_lshlrev_b32_e32 v118, 16, v150
	v_and_b32_e32 v119, 0xffff0000, v150
	v_lshlrev_b32_e32 v122, 16, v152
	v_and_b32_e32 v123, 0xffff0000, v152
	v_lshlrev_b32_e32 v124, 16, v153
	v_and_b32_e32 v125, 0xffff0000, v153
	v_pk_add_f32 v[108:109], v[108:109], v[120:121]
	v_pk_add_f32 v[106:107], v[106:107], v[118:119]
	v_pk_add_f32 v[118:119], v[100:101], v[124:125]
	v_pk_add_f32 v[100:101], v[98:99], v[122:123]
	v_pk_mul_f32 v[98:99], v[108:109], v[108:109]
	v_lshlrev_b32_e32 v126, 16, v146
	v_pk_fma_f32 v[98:99], v[106:107], v[106:107], v[98:99]
	v_and_b32_e32 v127, 0xffff0000, v146
	v_pk_fma_f32 v[98:99], v[100:101], v[100:101], v[98:99]
	v_lshlrev_b32_e32 v128, 16, v147
	v_and_b32_e32 v129, 0xffff0000, v147
	v_pk_fma_f32 v[120:121], v[118:119], v[118:119], v[98:99]
	v_cvt_pk_bf16_f32 v98, v106, v107
	v_cvt_pk_bf16_f32 v99, v108, v109
	v_pk_add_f32 v[108:109], v[110:111], v[126:127]
	v_lshlrev_b32_e32 v146, 16, v148
	v_and_b32_e32 v147, 0xffff0000, v148
	v_pk_add_f32 v[106:107], v[112:113], v[128:129]
	v_pk_fma_f32 v[110:111], v[108:109], v[108:109], v[120:121]
	v_lshlrev_b32_e32 v148, 16, v149
	v_and_b32_e32 v149, 0xffff0000, v149
	v_pk_add_f32 v[102:103], v[102:103], v[146:147]
	v_pk_fma_f32 v[110:111], v[106:107], v[106:107], v[110:111]
	v_pk_add_f32 v[104:105], v[104:105], v[148:149]
	v_pk_fma_f32 v[110:111], v[102:103], v[102:103], v[110:111]
	s_waitcnt lgkmcnt(0)
	v_lshlrev_b64 v[116:117], 12, v[182:183]
	v_pk_fma_f32 v[110:111], v[104:105], v[104:105], v[110:111]
	v_cvt_pk_bf16_f32 v100, v100, v101
	v_cvt_pk_bf16_f32 v101, v118, v119
	s_nop 0
	v_add_f32_e32 v112, v110, v111
	ds_bpermute_b32 v113, v187, v112
	v_lshl_add_u64 v[110:111], v[116:117], 1, s[96:97]
	v_lshl_add_u64 v[110:111], v[172:173], 1, v[110:111]
	global_store_dwordx4 v[110:111], v[98:101], off sc1
	s_waitcnt lgkmcnt(0)
	s_nop 0
	v_add_f32_e32 v98, v112, v113
	ds_bpermute_b32 v99, v114, v98
	v_cvt_pk_bf16_f32 v100, v108, v109
	v_cvt_pk_bf16_f32 v101, v106, v107
	v_cvt_pk_bf16_f32 v102, v102, v103
	v_cvt_pk_bf16_f32 v103, v104, v105
	global_store_dwordx4 v[110:111], v[100:103], off offset:256 sc1
	s_and_saveexec_b64 s[20:21], s[0:1]
	s_cbranch_execz .LBB0_1602
	s_waitcnt lgkmcnt(0)
	v_add_f32_e32 v98, v98, v99
	v_fma_f32 v98, v98, s50, 0.5
	v_trunc_f32_e32 v98, v98
	v_mul_f32_e32 v99, 0x2f800000, v98
	v_floor_f32_e32 v99, v99
	v_fmac_f32_e32 v98, 0xcf800000, v99
	v_cvt_u32_f32_e32 v98, v98
	v_cvt_u32_f32_e32 v99, v99
	v_lshl_add_u64 v[100:101], v[182:183], 3, s[6:7]
	global_atomic_add_x2 v[100:101], v[98:99], off
; __device__ __forceinline__ unsigned cvt_pk_bf16(float lo, float hi) { unsigned r; asm volatile("v_cvt_pk_bf16_f32 %0, %1, %2" : "=v"(r) : "v"(lo), "v"(hi)); return r; }
; __device__ __forceinline__ unsigned cvt_pk_bf16(float lo, float hi) { unsigned r; asm volatile("v_cvt_pk_bf16_f32 %0, %1, %2" : "=v"(r) : "v"(lo), "v"(hi)); return r; }
;     __device__ __forceinline__ void operator()(const f32x4 (&acc)[2][2][4][2], const Unit& u, int wr, int wc, int fr, int fq) const {
;     ...
;                 for (int bj = 0; bj < 2; ++bj) { const size_t off = (size_t)(row0 + ai * HALF + m * 16) * ldc + col0 + bj * HALF;
;                     if (BASE_F32) { const float* bp = (const float*)base + off; b0[m][bj] = *(const f32x4*)bp; b1[m][bj] = *(const f32x4*)(bp + 4); }
;                     else { const u32x4 r = *(const u32x4*)((const bf16_t*)base + off);
;                         b0[m][bj] = (f32x4){__uint_as_float(r.x << 16), __uint_as_float(r.x & 0xffff0000u), __uint_as_float(r.y << 16), __uint_as_float(r.y & 0xffff0000u)};
;                         b1[m][bj] = (f32x4){__uint_as_float(r.z << 16), __uint_as_float(r.z & 0xffff0000u), __uint_as_float(r.w << 16), __uint_as_float(r.w & 0xffff0000u)}; } }
; #pragma unroll
;             for (int m = 0; m < 4; ++m) { const int row = row0 + ai * HALF + m * 16; const size_t off = (size_t)row * ldc + col0; f32x2 q2 = {0.f, 0.f};
; #pragma unroll
;                 for (int bj = 0; bj < 2; ++bj) { const f32x4 v0 = acc[ai][bj][m][0] + b0[m][bj], v1 = acc[ai][bj][m][1] + b1[m][bj];
;                     { const f32x2 e0 = {v0[0], v0[1]}, e1 = {v0[2], v0[3]}, e2 = {v1[0], v1[1]}, e3 = {v1[2], v1[3]}; q2 = e0 * e0 + q2; q2 = e1 * e1 + q2; q2 = e2 * e2 + q2; q2 = e3 * e3 + q2; }
;                     u32x4 w; w.x = cvt_pk_bf16(v0[0], v0[1]); w.y = cvt_pk_bf16(v0[2], v0[3]); w.z = cvt_pk_bf16(v1[0], v1[1]); w.w = cvt_pk_bf16(v1[2], v1[3]);
;                     *(u32x4*)(out + off + bj * HALF) = w; }
;                 float q = q2.x + q2.y; q += __shfl_xor(q, 16); q += __shfl_xor(q, 32);
;                 if (fq == 0) atomicAdd(ssq + row, (ssq_t)(q * SSQ_FIX + 0.5f)); }
.LBB0_1602:
	s_or_b64 exec, exec, s[20:21]
	v_lshlrev_b32_e32 v102, 16, v143
	v_and_b32_e32 v103, 0xffff0000, v143
	v_lshlrev_b32_e32 v100, 16, v142
	v_and_b32_e32 v101, 0xffff0000, v142
	v_lshlrev_b32_e32 v104, 16, v144
	v_and_b32_e32 v105, 0xffff0000, v144
	v_lshlrev_b32_e32 v106, 16, v145
	v_and_b32_e32 v107, 0xffff0000, v145
	v_pk_add_f32 v[92:93], v[92:93], v[102:103]
	v_pk_add_f32 v[90:91], v[90:91], v[100:101]
	v_pk_add_f32 v[100:101], v[84:85], v[106:107]
	v_pk_add_f32 v[84:85], v[82:83], v[104:105]
	v_pk_mul_f32 v[82:83], v[92:93], v[92:93]
	v_lshlrev_b32_e32 v108, 16, v138
	v_pk_fma_f32 v[82:83], v[90:91], v[90:91], v[82:83]
	v_and_b32_e32 v109, 0xffff0000, v138
	v_pk_fma_f32 v[82:83], v[84:85], v[84:85], v[82:83]
	v_lshlrev_b32_e32 v110, 16, v139
	v_and_b32_e32 v111, 0xffff0000, v139
	v_pk_fma_f32 v[102:103], v[100:101], v[100:101], v[82:83]
	v_cvt_pk_bf16_f32 v82, v90, v91
	v_cvt_pk_bf16_f32 v83, v92, v93
	v_pk_add_f32 v[92:93], v[94:95], v[108:109]
	v_lshlrev_b32_e32 v112, 16, v140
	v_and_b32_e32 v113, 0xffff0000, v140
	v_pk_add_f32 v[90:91], v[96:97], v[110:111]
	v_pk_fma_f32 v[94:95], v[92:93], v[92:93], v[102:103]
	v_lshlrev_b32_e32 v116, 16, v141
	v_and_b32_e32 v117, 0xffff0000, v141
	v_pk_add_f32 v[86:87], v[86:87], v[112:113]
	v_pk_fma_f32 v[94:95], v[90:91], v[90:91], v[94:95]
	v_pk_add_f32 v[88:89], v[88:89], v[116:117]
	v_pk_fma_f32 v[94:95], v[86:87], v[86:87], v[94:95]
	s_waitcnt lgkmcnt(0)
	v_lshlrev_b64 v[98:99], 12, v[180:181]
	v_pk_fma_f32 v[94:95], v[88:89], v[88:89], v[94:95]
	v_cvt_pk_bf16_f32 v84, v84, v85
	v_cvt_pk_bf16_f32 v85, v100, v101
	s_nop 0
	v_add_f32_e32 v96, v94, v95
	ds_bpermute_b32 v97, v187, v96
	v_lshl_add_u64 v[94:95], v[98:99], 1, s[96:97]
	v_lshl_add_u64 v[94:95], v[172:173], 1, v[94:95]
	global_store_dwordx4 v[94:95], v[82:85], off sc1
	s_waitcnt lgkmcnt(0)
	s_nop 0
	v_add_f32_e32 v82, v96, v97
	ds_bpermute_b32 v83, v114, v82
	v_cvt_pk_bf16_f32 v84, v92, v93
	v_cvt_pk_bf16_f32 v85, v90, v91
	v_cvt_pk_bf16_f32 v86, v86, v87
	v_cvt_pk_bf16_f32 v87, v88, v89
	global_store_dwordx4 v[94:95], v[84:87], off offset:256 sc1
	s_and_saveexec_b64 s[20:21], s[0:1]
	s_cbranch_execz .LBB0_1604
	s_waitcnt lgkmcnt(0)
	v_add_f32_e32 v82, v82, v83
	v_fma_f32 v82, v82, s50, 0.5
	v_trunc_f32_e32 v82, v82
	v_mul_f32_e32 v83, 0x2f800000, v82
	v_floor_f32_e32 v83, v83
	v_fmac_f32_e32 v82, 0xcf800000, v83
	v_cvt_u32_f32_e32 v82, v82
	v_cvt_u32_f32_e32 v83, v83
	v_lshl_add_u64 v[84:85], v[180:181], 3, s[6:7]
	global_atomic_add_x2 v[84:85], v[82:83], off
.LBB0_1604:
	s_or_b64 exec, exec, s[20:21]
	v_lshlrev_b32_e32 v86, 16, v135
	v_and_b32_e32 v87, 0xffff0000, v135
	v_lshlrev_b32_e32 v84, 16, v134
	v_and_b32_e32 v85, 0xffff0000, v134
	v_lshlrev_b32_e32 v88, 16, v136
	v_and_b32_e32 v89, 0xffff0000, v136
	v_lshlrev_b32_e32 v90, 16, v137
	v_and_b32_e32 v91, 0xffff0000, v137
	v_pk_add_f32 v[76:77], v[76:77], v[86:87]
	v_pk_add_f32 v[74:75], v[74:75], v[84:85]
	v_pk_add_f32 v[84:85], v[68:69], v[90:91]
	v_pk_add_f32 v[68:69], v[66:67], v[88:89]
	v_pk_mul_f32 v[66:67], v[76:77], v[76:77]
	v_lshlrev_b32_e32 v92, 16, v130
	v_pk_fma_f32 v[66:67], v[74:75], v[74:75], v[66:67]
	v_and_b32_e32 v93, 0xffff0000, v130
	v_pk_fma_f32 v[66:67], v[68:69], v[68:69], v[66:67]
	v_lshlrev_b32_e32 v94, 16, v131
	v_and_b32_e32 v95, 0xffff0000, v131
	v_pk_fma_f32 v[86:87], v[84:85], v[84:85], v[66:67]
	v_cvt_pk_bf16_f32 v66, v74, v75
	v_cvt_pk_bf16_f32 v67, v76, v77
	v_pk_add_f32 v[76:77], v[78:79], v[92:93]
	v_lshlrev_b32_e32 v96, 16, v132
	v_and_b32_e32 v97, 0xffff0000, v132
	v_pk_add_f32 v[74:75], v[80:81], v[94:95]
	v_pk_fma_f32 v[78:79], v[76:77], v[76:77], v[86:87]
	v_lshlrev_b32_e32 v98, 16, v133
	v_and_b32_e32 v99, 0xffff0000, v133
	v_pk_add_f32 v[70:71], v[70:71], v[96:97]
	v_pk_fma_f32 v[78:79], v[74:75], v[74:75], v[78:79]
	v_pk_add_f32 v[72:73], v[72:73], v[98:99]
	v_pk_fma_f32 v[78:79], v[70:71], v[70:71], v[78:79]
	s_waitcnt lgkmcnt(0)
	v_lshlrev_b64 v[82:83], 12, v[178:179]
	v_pk_fma_f32 v[78:79], v[72:73], v[72:73], v[78:79]
	v_cvt_pk_bf16_f32 v68, v68, v69
	v_cvt_pk_bf16_f32 v69, v84, v85
	s_nop 0
	v_add_f32_e32 v80, v78, v79
	ds_bpermute_b32 v81, v187, v80
	v_lshl_add_u64 v[78:79], v[82:83], 1, s[96:97]
	v_lshl_add_u64 v[78:79], v[172:173], 1, v[78:79]
	global_store_dwordx4 v[78:79], v[66:69], off sc1
	s_waitcnt lgkmcnt(0)
	s_nop 0
	v_add_f32_e32 v66, v80, v81
	ds_bpermute_b32 v67, v114, v66
	v_cvt_pk_bf16_f32 v68, v76, v77
	v_cvt_pk_bf16_f32 v69, v74, v75
	v_cvt_pk_bf16_f32 v70, v70, v71
	v_cvt_pk_bf16_f32 v71, v72, v73
	global_store_dwordx4 v[78:79], v[68:71], off offset:256 sc1
	s_and_saveexec_b64 s[20:21], s[0:1]
	s_cbranch_execz .LBB0_1606
	s_waitcnt lgkmcnt(0)
	v_add_f32_e32 v66, v66, v67
	v_fma_f32 v66, v66, s50, 0.5
	v_trunc_f32_e32 v66, v66
	v_mul_f32_e32 v67, 0x2f800000, v66
	v_floor_f32_e32 v67, v67
	v_fmac_f32_e32 v66, 0xcf800000, v67
	v_cvt_u32_f32_e32 v66, v66
	v_cvt_u32_f32_e32 v67, v67
	v_lshl_add_u64 v[68:69], v[178:179], 3, s[6:7]
	global_atomic_add_x2 v[68:69], v[66:67], off
; __device__ __forceinline__ unsigned cvt_pk_bf16(float lo, float hi) { unsigned r; asm volatile("v_cvt_pk_bf16_f32 %0, %1, %2" : "=v"(r) : "v"(lo), "v"(hi)); return r; }
; __device__ __forceinline__ unsigned cvt_pk_bf16(float lo, float hi) { unsigned r; asm volatile("v_cvt_pk_bf16_f32 %0, %1, %2" : "=v"(r) : "v"(lo), "v"(hi)); return r; }
;     __device__ __forceinline__ void operator()(const f32x4 (&acc)[2][2][4][2], const Unit& u, int wr, int wc, int fr, int fq) const {
;     ...
;                 for (int bj = 0; bj < 2; ++bj) { const size_t off = (size_t)(row0 + ai * HALF + m * 16) * ldc + col0 + bj * HALF;
;                     if (BASE_F32) { const float* bp = (const float*)base + off; b0[m][bj] = *(const f32x4*)bp; b1[m][bj] = *(const f32x4*)(bp + 4); }
;                     else { const u32x4 r = *(const u32x4*)((const bf16_t*)base + off);
;                         b0[m][bj] = (f32x4){__uint_as_float(r.x << 16), __uint_as_float(r.x & 0xffff0000u), __uint_as_float(r.y << 16), __uint_as_float(r.y & 0xffff0000u)};
;                         b1[m][bj] = (f32x4){__uint_as_float(r.z << 16), __uint_as_float(r.z & 0xffff0000u), __uint_as_float(r.w << 16), __uint_as_float(r.w & 0xffff0000u)}; } }
; #pragma unroll
;             for (int m = 0; m < 4; ++m) { const int row = row0 + ai * HALF + m * 16; const size_t off = (size_t)row * ldc + col0; f32x2 q2 = {0.f, 0.f};
; #pragma unroll
;                 for (int bj = 0; bj < 2; ++bj) { const f32x4 v0 = acc[ai][bj][m][0] + b0[m][bj], v1 = acc[ai][bj][m][1] + b1[m][bj];
;                     { const f32x2 e0 = {v0[0], v0[1]}, e1 = {v0[2], v0[3]}, e2 = {v1[0], v1[1]}, e3 = {v1[2], v1[3]}; q2 = e0 * e0 + q2; q2 = e1 * e1 + q2; q2 = e2 * e2 + q2; q2 = e3 * e3 + q2; }
;                     u32x4 w; w.x = cvt_pk_bf16(v0[0], v0[1]); w.y = cvt_pk_bf16(v0[2], v0[3]); w.z = cvt_pk_bf16(v1[0], v1[1]); w.w = cvt_pk_bf16(v1[2], v1[3]);
;                     *(u32x4*)(out + off + bj * HALF) = w; }
;                 float q = q2.x + q2.y; q += __shfl_xor(q, 16); q += __shfl_xor(q, 32);
;                 if (fq == 0) atomicAdd(ssq + row, (ssq_t)(q * SSQ_FIX + 0.5f)); }
.LBB0_1606:
	s_or_b64 exec, exec, s[20:21]
	v_add_u32_e32 v96, 0x80, v176
	v_ashrrev_i32_e32 v97, 31, v96
	v_lshlrev_b64 v[106:107], 13, v[96:97]
	s_waitcnt lgkmcnt(0)
	v_lshl_add_u64 v[66:67], v[174:175], 0, v[106:107]
	global_load_dwordx4 v[98:101], v[66:67], off
	global_load_dwordx4 v[102:105], v[66:67], off offset:256
	v_add_u32_e32 v94, 0x90, v176
	v_add_u32_e32 v92, 0xa0, v176
	v_add_u32_e32 v90, 0xb0, v176
	v_ashrrev_i32_e32 v95, 31, v94
	v_ashrrev_i32_e32 v93, 31, v92
	v_ashrrev_i32_e32 v91, 31, v90
	v_lshlrev_b64 v[66:67], 13, v[94:95]
	v_lshlrev_b64 v[68:69], 13, v[92:93]
	v_lshlrev_b64 v[70:71], 13, v[90:91]
	v_lshl_add_u64 v[66:67], v[174:175], 0, v[66:67]
	v_lshl_add_u64 v[68:69], v[174:175], 0, v[68:69]
	v_lshl_add_u64 v[108:109], v[174:175], 0, v[70:71]
	global_load_dwordx4 v[86:89], v[66:67], off
	global_load_dwordx4 v[82:85], v[66:67], off offset:256
	global_load_dwordx4 v[78:81], v[68:69], off
	global_load_dwordx4 v[74:77], v[68:69], off offset:256
	global_load_dwordx4 v[70:73], v[108:109], off
	s_nop 0
	global_load_dwordx4 v[66:69], v[108:109], off offset:256
	s_waitcnt vmcnt(7)
	v_lshlrev_b32_e32 v108, 16, v98
	v_and_b32_e32 v109, 0xffff0000, v98
	v_lshlrev_b32_e32 v98, 16, v99
	v_and_b32_e32 v99, 0xffff0000, v99
	s_waitcnt vmcnt(6)
	v_lshlrev_b32_e32 v112, 16, v102
	v_and_b32_e32 v113, 0xffff0000, v102
	v_lshlrev_b32_e32 v102, 16, v103
	v_and_b32_e32 v103, 0xffff0000, v103
	v_pk_add_f32 v[60:61], v[60:61], v[98:99]
	v_lshlrev_b32_e32 v110, 16, v100
	v_and_b32_e32 v111, 0xffff0000, v100
	v_lshlrev_b32_e32 v100, 16, v101
	v_and_b32_e32 v101, 0xffff0000, v101
	v_lshlrev_b32_e32 v116, 16, v104
	v_and_b32_e32 v117, 0xffff0000, v104
	v_lshlrev_b32_e32 v104, 16, v105
	v_and_b32_e32 v105, 0xffff0000, v105
	v_pk_add_f32 v[58:59], v[58:59], v[108:109]
	v_pk_add_f32 v[64:65], v[64:65], v[102:103]
	v_pk_mul_f32 v[102:103], v[60:61], v[60:61]
	v_pk_add_f32 v[56:57], v[56:57], v[100:101]
	v_pk_add_f32 v[98:99], v[54:55], v[110:111]
	v_pk_add_f32 v[100:101], v[52:53], v[104:105]
	v_cvt_pk_bf16_f32 v52, v58, v59
	v_pk_fma_f32 v[58:59], v[58:59], v[58:59], v[102:103]
	v_pk_add_f32 v[62:63], v[62:63], v[112:113]
	v_pk_fma_f32 v[58:59], v[98:99], v[98:99], v[58:59]
	v_cvt_pk_bf16_f32 v53, v60, v61
	v_cvt_pk_bf16_f32 v54, v98, v99
	v_cvt_pk_bf16_f32 v55, v56, v57
	s_nop 0
	v_pk_fma_f32 v[56:57], v[56:57], v[56:57], v[58:59]
	v_pk_add_f32 v[58:59], v[50:51], v[116:117]
	v_pk_fma_f32 v[50:51], v[62:63], v[62:63], v[56:57]
	s_nop 0
	v_pk_fma_f32 v[50:51], v[64:65], v[64:65], v[50:51]
	s_nop 0
	v_pk_fma_f32 v[50:51], v[58:59], v[58:59], v[50:51]
	s_nop 0
	v_pk_fma_f32 v[50:51], v[100:101], v[100:101], v[50:51]
	s_nop 0
	v_add_f32_e32 v60, v50, v51
	ds_bpermute_b32 v61, v187, v60
	v_lshl_add_u64 v[50:51], s[96:97], 0, v[106:107]
	v_lshl_add_u64 v[56:57], v[172:173], 1, v[50:51]
	global_store_dwordx4 v[56:57], v[52:55], off sc1
	s_waitcnt lgkmcnt(0)
	v_add_f32_e32 v50, v60, v61
	ds_bpermute_b32 v51, v114, v50
	v_cvt_pk_bf16_f32 v52, v62, v63
	v_cvt_pk_bf16_f32 v53, v64, v65
	v_cvt_pk_bf16_f32 v54, v58, v59
	v_cvt_pk_bf16_f32 v55, v100, v101
	global_store_dwordx4 v[56:57], v[52:55], off offset:256 sc1
	s_and_saveexec_b64 s[20:21], s[0:1]
	s_cbranch_execz .LBB0_1608
	s_waitcnt lgkmcnt(0)
	v_add_f32_e32 v50, v50, v51
	v_fma_f32 v50, v50, s50, 0.5
	v_trunc_f32_e32 v50, v50
	v_mul_f32_e32 v51, 0x2f800000, v50
	v_floor_f32_e32 v51, v51
	v_fmac_f32_e32 v50, 0xcf800000, v51
	v_cvt_u32_f32_e32 v50, v50
	v_cvt_u32_f32_e32 v51, v51
	v_lshl_add_u64 v[52:53], v[96:97], 3, s[6:7]
	global_atomic_add_x2 v[52:53], v[50:51], off
.LBB0_1608:
	s_or_b64 exec, exec, s[20:21]
	s_waitcnt vmcnt(7)
	v_lshlrev_b32_e32 v54, 16, v87
	v_and_b32_e32 v55, 0xffff0000, v87
	v_lshlrev_b32_e32 v52, 16, v86
	v_and_b32_e32 v53, 0xffff0000, v86
	v_lshlrev_b32_e32 v56, 16, v88
	v_and_b32_e32 v57, 0xffff0000, v88
	v_lshlrev_b32_e32 v58, 16, v89
	v_and_b32_e32 v59, 0xffff0000, v89
	v_pk_add_f32 v[44:45], v[44:45], v[54:55]
	v_pk_add_f32 v[42:43], v[42:43], v[52:53]
	v_pk_add_f32 v[52:53], v[36:37], v[58:59]
	v_pk_add_f32 v[36:37], v[34:35], v[56:57]
	v_pk_mul_f32 v[34:35], v[44:45], v[44:45]
	s_waitcnt vmcnt(6)
	v_lshlrev_b32_e32 v60, 16, v82
	v_pk_fma_f32 v[34:35], v[42:43], v[42:43], v[34:35]
	v_and_b32_e32 v61, 0xffff0000, v82
	v_pk_fma_f32 v[34:35], v[36:37], v[36:37], v[34:35]
	v_lshlrev_b32_e32 v62, 16, v83
	v_and_b32_e32 v63, 0xffff0000, v83
	v_pk_fma_f32 v[54:55], v[52:53], v[52:53], v[34:35]
	v_cvt_pk_bf16_f32 v34, v42, v43
	v_cvt_pk_bf16_f32 v35, v44, v45
	v_pk_add_f32 v[44:45], v[46:47], v[60:61]
	v_lshlrev_b32_e32 v64, 16, v84
	v_and_b32_e32 v65, 0xffff0000, v84
	v_pk_add_f32 v[42:43], v[48:49], v[62:63]
	v_pk_fma_f32 v[46:47], v[44:45], v[44:45], v[54:55]
	v_lshlrev_b32_e32 v82, 16, v85
	v_and_b32_e32 v83, 0xffff0000, v85
	v_pk_add_f32 v[38:39], v[38:39], v[64:65]
	v_pk_fma_f32 v[46:47], v[42:43], v[42:43], v[46:47]
	v_pk_add_f32 v[40:41], v[40:41], v[82:83]
	v_pk_fma_f32 v[46:47], v[38:39], v[38:39], v[46:47]
	s_waitcnt lgkmcnt(0)
	v_lshlrev_b64 v[50:51], 12, v[94:95]
	v_pk_fma_f32 v[46:47], v[40:41], v[40:41], v[46:47]
	v_cvt_pk_bf16_f32 v36, v36, v37
	v_cvt_pk_bf16_f32 v37, v52, v53
	s_nop 0
	v_add_f32_e32 v48, v46, v47
	ds_bpermute_b32 v49, v187, v48
	v_lshl_add_u64 v[46:47], v[50:51], 1, s[96:97]
	v_lshl_add_u64 v[46:47], v[172:173], 1, v[46:47]
	global_store_dwordx4 v[46:47], v[34:37], off sc1
	s_waitcnt lgkmcnt(0)
	s_nop 0
	v_add_f32_e32 v34, v48, v49
	ds_bpermute_b32 v35, v114, v34
	v_cvt_pk_bf16_f32 v36, v44, v45
	v_cvt_pk_bf16_f32 v37, v42, v43
	v_cvt_pk_bf16_f32 v38, v38, v39
	v_cvt_pk_bf16_f32 v39, v40, v41
	global_store_dwordx4 v[46:47], v[36:39], off offset:256 sc1
	s_and_saveexec_b64 s[20:21], s[0:1]
	s_cbranch_execz .LBB0_1610
	s_waitcnt lgkmcnt(0)
	v_add_f32_e32 v34, v34, v35
	v_fma_f32 v34, v34, s50, 0.5
	v_trunc_f32_e32 v34, v34
	v_mul_f32_e32 v35, 0x2f800000, v34
	v_floor_f32_e32 v35, v35
	v_fmac_f32_e32 v34, 0xcf800000, v35
	v_cvt_u32_f32_e32 v34, v34
	v_cvt_u32_f32_e32 v35, v35
	v_lshl_add_u64 v[36:37], v[94:95], 3, s[6:7]
	global_atomic_add_x2 v[36:37], v[34:35], off
; __device__ __forceinline__ unsigned cvt_pk_bf16(float lo, float hi) { unsigned r; asm volatile("v_cvt_pk_bf16_f32 %0, %1, %2" : "=v"(r) : "v"(lo), "v"(hi)); return r; }
; __device__ __forceinline__ unsigned cvt_pk_bf16(float lo, float hi) { unsigned r; asm volatile("v_cvt_pk_bf16_f32 %0, %1, %2" : "=v"(r) : "v"(lo), "v"(hi)); return r; }
;     __device__ __forceinline__ void operator()(const f32x4 (&acc)[2][2][4][2], const Unit& u, int wr, int wc, int fr, int fq) const {
;     ...
;                 for (int bj = 0; bj < 2; ++bj) { const size_t off = (size_t)(row0 + ai * HALF + m * 16) * ldc + col0 + bj * HALF;
;                     if (BASE_F32) { const float* bp = (const float*)base + off; b0[m][bj] = *(const f32x4*)bp; b1[m][bj] = *(const f32x4*)(bp + 4); }
;                     else { const u32x4 r = *(const u32x4*)((const bf16_t*)base + off);
;                         b0[m][bj] = (f32x4){__uint_as_float(r.x << 16), __uint_as_float(r.x & 0xffff0000u), __uint_as_float(r.y << 16), __uint_as_float(r.y & 0xffff0000u)};
;                         b1[m][bj] = (f32x4){__uint_as_float(r.z << 16), __uint_as_float(r.z & 0xffff0000u), __uint_as_float(r.w << 16), __uint_as_float(r.w & 0xffff0000u)}; } }
; #pragma unroll
;             for (int m = 0; m < 4; ++m) { const int row = row0 + ai * HALF + m * 16; const size_t off = (size_t)row * ldc + col0; f32x2 q2 = {0.f, 0.f};
; #pragma unroll
;                 for (int bj = 0; bj < 2; ++bj) { const f32x4 v0 = acc[ai][bj][m][0] + b0[m][bj], v1 = acc[ai][bj][m][1] + b1[m][bj];
;                     { const f32x2 e0 = {v0[0], v0[1]}, e1 = {v0[2], v0[3]}, e2 = {v1[0], v1[1]}, e3 = {v1[2], v1[3]}; q2 = e0 * e0 + q2; q2 = e1 * e1 + q2; q2 = e2 * e2 + q2; q2 = e3 * e3 + q2; }
;                     u32x4 w; w.x = cvt_pk_bf16(v0[0], v0[1]); w.y = cvt_pk_bf16(v0[2], v0[3]); w.z = cvt_pk_bf16(v1[0], v1[1]); w.w = cvt_pk_bf16(v1[2], v1[3]);
;                     *(u32x4*)(out + off + bj * HALF) = w; }
;                 float q = q2.x + q2.y; q += __shfl_xor(q, 16); q += __shfl_xor(q, 32);
;                 if (fq == 0) atomicAdd(ssq + row, (ssq_t)(q * SSQ_FIX + 0.5f)); }
.LBB0_1610:
	s_or_b64 exec, exec, s[20:21]
	s_waitcnt vmcnt(7)
	v_lshlrev_b32_e32 v38, 16, v79
	v_and_b32_e32 v39, 0xffff0000, v79
	v_lshlrev_b32_e32 v36, 16, v78
	v_and_b32_e32 v37, 0xffff0000, v78
	v_lshlrev_b32_e32 v40, 16, v80
	v_and_b32_e32 v41, 0xffff0000, v80
	v_lshlrev_b32_e32 v42, 16, v81
	v_and_b32_e32 v43, 0xffff0000, v81
	v_pk_add_f32 v[28:29], v[28:29], v[38:39]
	v_pk_add_f32 v[26:27], v[26:27], v[36:37]
	v_pk_add_f32 v[36:37], v[20:21], v[42:43]
	v_pk_add_f32 v[20:21], v[18:19], v[40:41]
	v_pk_mul_f32 v[18:19], v[28:29], v[28:29]
	s_waitcnt vmcnt(6)
	v_lshlrev_b32_e32 v44, 16, v74
	v_pk_fma_f32 v[18:19], v[26:27], v[26:27], v[18:19]
	v_and_b32_e32 v45, 0xffff0000, v74
	v_pk_fma_f32 v[18:19], v[20:21], v[20:21], v[18:19]
	v_lshlrev_b32_e32 v46, 16, v75
	v_and_b32_e32 v47, 0xffff0000, v75
	v_pk_fma_f32 v[38:39], v[36:37], v[36:37], v[18:19]
	v_cvt_pk_bf16_f32 v18, v26, v27
	v_cvt_pk_bf16_f32 v19, v28, v29
	v_pk_add_f32 v[28:29], v[30:31], v[44:45]
	v_lshlrev_b32_e32 v48, 16, v76
	v_and_b32_e32 v49, 0xffff0000, v76
	v_pk_add_f32 v[26:27], v[32:33], v[46:47]
	v_pk_fma_f32 v[30:31], v[28:29], v[28:29], v[38:39]
	v_lshlrev_b32_e32 v50, 16, v77
	v_and_b32_e32 v51, 0xffff0000, v77
	v_pk_add_f32 v[22:23], v[22:23], v[48:49]
	v_pk_fma_f32 v[30:31], v[26:27], v[26:27], v[30:31]
	v_pk_add_f32 v[24:25], v[24:25], v[50:51]
	v_pk_fma_f32 v[30:31], v[22:23], v[22:23], v[30:31]
	s_waitcnt lgkmcnt(0)
	v_lshlrev_b64 v[34:35], 12, v[92:93]
	v_pk_fma_f32 v[30:31], v[24:25], v[24:25], v[30:31]
	v_cvt_pk_bf16_f32 v20, v20, v21
	v_cvt_pk_bf16_f32 v21, v36, v37
	s_nop 0
	v_add_f32_e32 v32, v30, v31
	ds_bpermute_b32 v33, v187, v32
	v_lshl_add_u64 v[30:31], v[34:35], 1, s[96:97]
	v_lshl_add_u64 v[30:31], v[172:173], 1, v[30:31]
	global_store_dwordx4 v[30:31], v[18:21], off sc1
	s_waitcnt lgkmcnt(0)
	s_nop 0
	v_add_f32_e32 v18, v32, v33
	ds_bpermute_b32 v19, v114, v18
	v_cvt_pk_bf16_f32 v20, v28, v29
	v_cvt_pk_bf16_f32 v21, v26, v27
	v_cvt_pk_bf16_f32 v22, v22, v23
	v_cvt_pk_bf16_f32 v23, v24, v25
	global_store_dwordx4 v[30:31], v[20:23], off offset:256 sc1
	s_and_saveexec_b64 s[20:21], s[0:1]
	s_cbranch_execz .LBB0_1612
	s_waitcnt lgkmcnt(0)
	v_add_f32_e32 v18, v18, v19
	v_fma_f32 v18, v18, s50, 0.5
	v_trunc_f32_e32 v18, v18
	v_mul_f32_e32 v19, 0x2f800000, v18
	v_floor_f32_e32 v19, v19
	v_fmac_f32_e32 v18, 0xcf800000, v19
	v_cvt_u32_f32_e32 v18, v18
	v_cvt_u32_f32_e32 v19, v19
	v_lshl_add_u64 v[20:21], v[92:93], 3, s[6:7]
	global_atomic_add_x2 v[20:21], v[18:19], off
.LBB0_1612:
	s_or_b64 exec, exec, s[20:21]
	s_waitcnt vmcnt(7)
	v_lshlrev_b32_e32 v22, 16, v71
	v_and_b32_e32 v23, 0xffff0000, v71
	v_lshlrev_b32_e32 v20, 16, v70
	v_and_b32_e32 v21, 0xffff0000, v70
	v_lshlrev_b32_e32 v24, 16, v72
	v_and_b32_e32 v25, 0xffff0000, v72
	v_lshlrev_b32_e32 v26, 16, v73
	v_and_b32_e32 v27, 0xffff0000, v73
	v_pk_add_f32 v[8:9], v[8:9], v[22:23]
	v_pk_add_f32 v[6:7], v[6:7], v[20:21]
	v_pk_add_f32 v[20:21], v[4:5], v[26:27]
	v_pk_add_f32 v[4:5], v[2:3], v[24:25]
	v_pk_mul_f32 v[2:3], v[8:9], v[8:9]
	s_waitcnt vmcnt(6)
	v_lshlrev_b32_e32 v28, 16, v66
	v_pk_fma_f32 v[2:3], v[6:7], v[6:7], v[2:3]
	v_and_b32_e32 v29, 0xffff0000, v66
	v_pk_fma_f32 v[2:3], v[4:5], v[4:5], v[2:3]
	v_lshlrev_b32_e32 v30, 16, v67
	v_and_b32_e32 v31, 0xffff0000, v67
	v_lshlrev_b32_e32 v32, 16, v68
	v_and_b32_e32 v33, 0xffff0000, v68
	v_pk_fma_f32 v[22:23], v[20:21], v[20:21], v[2:3]
	v_cvt_pk_bf16_f32 v2, v6, v7
	v_cvt_pk_bf16_f32 v3, v8, v9
	v_pk_add_f32 v[8:9], v[10:11], v[28:29]
	v_pk_add_f32 v[6:7], v[12:13], v[30:31]
	v_pk_add_f32 v[12:13], v[14:15], v[32:33]
	v_pk_fma_f32 v[14:15], v[8:9], v[8:9], v[22:23]
	v_lshlrev_b32_e32 v34, 16, v69
	v_and_b32_e32 v35, 0xffff0000, v69
	v_pk_fma_f32 v[14:15], v[6:7], v[6:7], v[14:15]
	v_pk_add_f32 v[10:11], v[16:17], v[34:35]
	v_pk_fma_f32 v[14:15], v[12:13], v[12:13], v[14:15]
	s_waitcnt lgkmcnt(0)
	v_lshlrev_b64 v[18:19], 12, v[90:91]
	v_pk_fma_f32 v[14:15], v[10:11], v[10:11], v[14:15]
	v_cvt_pk_bf16_f32 v4, v4, v5
	v_cvt_pk_bf16_f32 v5, v20, v21
	s_nop 0
	v_add_f32_e32 v16, v14, v15
	ds_bpermute_b32 v17, v187, v16
	v_lshl_add_u64 v[14:15], v[18:19], 1, s[96:97]
	v_lshl_add_u64 v[14:15], v[172:173], 1, v[14:15]
	global_store_dwordx4 v[14:15], v[2:5], off sc1
	s_waitcnt lgkmcnt(0)
	s_nop 0
	v_add_f32_e32 v2, v16, v17
	ds_bpermute_b32 v3, v114, v2
	v_cvt_pk_bf16_f32 v4, v8, v9
	v_cvt_pk_bf16_f32 v5, v6, v7
	v_cvt_pk_bf16_f32 v6, v12, v13
	v_cvt_pk_bf16_f32 v7, v10, v11
	global_store_dwordx4 v[14:15], v[4:7], off offset:256 sc1
	s_and_saveexec_b64 s[20:21], s[0:1]
	s_cbranch_execz .LBB0_1614
	s_waitcnt lgkmcnt(0)
	v_add_f32_e32 v2, v2, v3
	v_fma_f32 v2, v2, s50, 0.5
	v_trunc_f32_e32 v2, v2
	v_mul_f32_e32 v3, 0x2f800000, v2
	v_floor_f32_e32 v3, v3
	v_fmac_f32_e32 v2, 0xcf800000, v3
	v_cvt_u32_f32_e32 v2, v2
	v_cvt_u32_f32_e32 v3, v3
	v_lshl_add_u64 v[4:5], v[90:91], 3, s[6:7]
	global_atomic_add_x2 v[4:5], v[2:3], off

; __device__ __forceinline__ unsigned cvt_pk_bf16(float lo, float hi) { unsigned r; asm volatile("v_cvt_pk_bf16_f32 %0, %1, %2" : "=v"(r) : "v"(lo), "v"(hi)); return r; }
; __device__ __forceinline__ unsigned cvt_pk_bf16(float lo, float hi) { unsigned r; asm volatile("v_cvt_pk_bf16_f32 %0, %1, %2" : "=v"(r) : "v"(lo), "v"(hi)); return r; }
; __device__ __forceinline__ float ssq_rstd(const ssq_t* ssq, int row) { return __builtin_amdgcn_rsqf((float)ssq[row] * (SSQ_UNFIX * RMS_INV_D) + RMS_EPS); }
;     __device__ __forceinline__ void operator()(const f32x4 (&acc)[2][2][4][2], const Unit& u, int wr, int wc, int fr, int fq) const {
;     ...
;             for (int m = 0; m < 4; ++m) rs[ai][m] = ssq_rstd(ssq, row0 + ai * HALF + m * 16);
; #pragma unroll
;         for (int ai = 0; ai < 2; ++ai)
; #pragma unroll
;             for (int m = 0; m < 4; ++m) { const int row = row0 + ai * HALF + m * 16; bf16_t* rowp = O + (size_t)row * ldc + col0; float a[8];
; #pragma unroll
;                 for (int n = 0; n < 2; ++n)
; #pragma unroll
;                     for (int i = 0; i < 4; i += 2) {
;                         const f32x2 r2 = {rs[ai][m], rs[ai][m]};
;                         const f32x2 g = (f32x2){acc[ai][0][m][n][i], acc[ai][0][m][n][i + 1]} * r2, up = (f32x2){acc[ai][1][m][n][i], acc[ai][1][m][n][i + 1]} * r2;
;                         const f32x2 t = g * (f32x2){-1.4426950408889634f, -1.4426950408889634f};
;                         const f32x2 d = (f32x2){__builtin_amdgcn_exp2f(t.x), __builtin_amdgcn_exp2f(t.y)} + (f32x2){1.0f, 1.0f};
;                         const f32x2 o2 = (g * up) * (f32x2){__builtin_amdgcn_rcpf(d.x), __builtin_amdgcn_rcpf(d.y)};
;                         a[4 * n + i] = o2.x; a[4 * n + i + 1] = o2.y; }
;                 u32x4 w; w.x = cvt_pk_bf16(a[0], a[1]); w.y = cvt_pk_bf16(a[2], a[3]); w.z = cvt_pk_bf16(a[4], a[5]); w.w = cvt_pk_bf16(a[6], a[7]);
;                 *(u32x4*)rowp = w; }
.Lepi_rest_1684:
	v_add_u32_e32 v165, 0x80, v168
	v_add_u32_e32 v163, 0x90, v168
	v_add_u32_e32 v161, 0xa0, v168
	s_andn2_b64 vcc, exec, s[0:1]
	s_mov_b64 s[0:1], -1
	s_waitcnt vmcnt(0)
	v_ffbh_u32_e32 v146, v173
	v_min_u32_e32 v146, 32, v146
	v_lshlrev_b64 v[172:173], v146, v[172:173]
	v_ffbh_u32_e32 v158, v171
	v_min_u32_e32 v158, 32, v158
	v_min_u32_e32 v169, 1, v172
	v_lshlrev_b64 v[170:171], v158, v[170:171]
	v_or_b32_e32 v169, v173, v169
	v_min_u32_e32 v170, 1, v170
	v_cvt_f32_u32_e32 v169, v169
	v_ffbh_u32_e32 v150, v175
	v_ffbh_u32_e32 v152, v177
	v_ffbh_u32_e32 v154, v179
	v_ffbh_u32_e32 v162, v181
	v_or_b32_e32 v170, v171, v170
	v_min_u32_e32 v150, 32, v150
	v_min_u32_e32 v152, 32, v152
	v_min_u32_e32 v154, 32, v154
	v_min_u32_e32 v162, 32, v162
	v_cvt_f32_u32_e32 v170, v170
	v_sub_u32_e32 v146, 32, v146
	v_lshlrev_b64 v[174:175], v150, v[174:175]
	v_lshlrev_b64 v[176:177], v152, v[176:177]
	v_lshlrev_b64 v[178:179], v154, v[178:179]
	v_lshlrev_b64 v[180:181], v162, v[180:181]
	v_min_u32_e32 v172, 1, v174
	v_min_u32_e32 v174, 1, v176
	v_min_u32_e32 v176, 1, v178
	v_min_u32_e32 v178, 1, v180
	v_ldexp_f32 v146, v169, v146
	v_sub_u32_e32 v158, 32, v158
	v_or_b32_e32 v171, v181, v178
	v_fmamk_f32 v146, v146, 0x2d800000, v159
	v_cvt_f32_u32_e32 v171, v171
	v_ldexp_f32 v158, v170, v158
	v_rsq_f32_e32 v170, v146
	v_or_b32_e32 v172, v175, v172
	v_or_b32_e32 v174, v177, v174
	v_or_b32_e32 v175, v179, v176
	v_pk_mul_f32 v[122:123], v[122:123], v[170:171] op_sel_hi:[1,0]
	v_pk_mul_f32 v[124:125], v[124:125], v[170:171] op_sel_hi:[1,0]
	v_pk_mul_f32 v[176:177], v[122:123], s[10:11] op_sel_hi:[1,0]
	v_pk_mul_f32 v[178:179], v[124:125], s[10:11] op_sel_hi:[1,0]
	v_exp_f32_e32 v176, v176
	v_exp_f32_e32 v177, v177
	v_exp_f32_e32 v178, v178
	v_exp_f32_e32 v179, v179
	v_ffbh_u32_e32 v157, v183
	v_pk_add_f32 v[176:177], v[176:177], 1.0 op_sel_hi:[1,0]
	v_min_u32_e32 v157, 32, v157
	v_pk_mul_f32 v[126:127], v[126:127], v[170:171] op_sel_hi:[1,0]
	v_rcp_f32_e32 v176, v176
	v_rcp_f32_e32 v177, v177
	v_lshlrev_b64 v[182:183], v157, v[182:183]
	v_pk_mul_f32 v[122:123], v[122:123], v[126:127]
	v_pk_mul_f32 v[126:127], v[128:129], v[170:171] op_sel_hi:[1,0]
	v_pk_add_f32 v[128:129], v[178:179], 1.0 op_sel_hi:[1,0]
	v_min_u32_e32 v173, 1, v182
	v_rcp_f32_e32 v128, v128
	v_rcp_f32_e32 v129, v129
	v_or_b32_e32 v173, v183, v173
	v_pk_mul_f32 v[114:115], v[114:115], v[170:171] op_sel_hi:[1,0]
	v_cvt_f32_u32_e32 v173, v173
	v_pk_mul_f32 v[122:123], v[122:123], v[176:177]
	v_pk_mul_f32 v[176:177], v[114:115], s[10:11] op_sel_hi:[1,0]
	v_pk_mul_f32 v[124:125], v[124:125], v[126:127]
	v_exp_f32_e32 v176, v176
	v_exp_f32_e32 v177, v177
	v_pk_mul_f32 v[116:117], v[116:117], v[170:171] op_sel_hi:[1,0]
	v_ffbh_u32_e32 v167, v149
	v_cvt_f32_u32_e32 v172, v172
	v_pk_mul_f32 v[124:125], v[124:125], v[128:129]
	v_pk_mul_f32 v[128:129], v[116:117], s[10:11] op_sel_hi:[1,0]
	v_min_u32_e32 v167, 32, v167
	v_sub_u32_e32 v157, 32, v157
	v_exp_f32_e32 v128, v128
	v_exp_f32_e32 v129, v129
	v_lshlrev_b64 v[148:149], v167, v[148:149]
	v_ldexp_f32 v157, v173, v157
	v_sub_u32_e32 v150, 32, v150
	v_min_u32_e32 v148, 1, v148
	v_fmamk_f32 v146, v157, 0x2d800000, v159
	v_pk_mul_f32 v[118:119], v[118:119], v[170:171] op_sel_hi:[1,0]
	v_pk_add_f32 v[126:127], v[176:177], 1.0 op_sel_hi:[1,0]
	v_cvt_f32_u32_e32 v174, v174
	v_cvt_f32_u32_e32 v175, v175
	v_ldexp_f32 v150, v172, v150
	v_rsq_f32_e32 v172, v146
	v_or_b32_e32 v146, v149, v148
	v_pk_mul_f32 v[114:115], v[114:115], v[118:119]
	v_rcp_f32_e32 v118, v126
	v_rcp_f32_e32 v119, v127
	v_cvt_f32_u32_e32 v146, v146
	v_pk_add_f32 v[126:127], v[128:129], 1.0 op_sel_hi:[1,0]
	v_sub_u32_e32 v152, 32, v152
	v_rcp_f32_e32 v126, v126
	v_rcp_f32_e32 v127, v127
	v_sub_u32_e32 v154, 32, v154
	v_sub_u32_e32 v162, 32, v162
	v_ldexp_f32 v152, v174, v152
	v_ldexp_f32 v154, v175, v154
	v_sub_u32_e32 v148, 32, v167
	v_lshl_or_b32 v174, s47, 7, v153
	v_pk_mul_f32 v[118:119], v[114:115], v[118:119]
	v_pk_mul_f32 v[114:115], v[120:121], v[170:171] op_sel_hi:[1,0]
	v_ldexp_f32 v162, v171, v162
	v_fmamk_f32 v150, v150, 0x2d800000, v159
	v_fmamk_f32 v169, v154, 0x2d800000, v159
	v_fmamk_f32 v157, v158, 0x2d800000, v159
	v_ldexp_f32 v146, v146, v148
	v_ashrrev_i32_e32 v175, 31, v174
	v_mov_b64_e32 v[148:149], s[38:39]
	v_pk_mul_f32 v[114:115], v[116:117], v[114:115]
	v_fmamk_f32 v158, v162, 0x2d800000, v159
	v_rsq_f32_e32 v154, v150
	v_rsq_f32_e32 v162, v157
	v_rsq_f32_e32 v150, v169
	v_add_u32_e32 v157, 0xb0, v168
	v_mad_i64_i32 v[168:169], s[22:23], v168, s46, v[148:149]
	v_pk_mul_f32 v[120:121], v[114:115], v[126:127]
	v_lshlrev_b64 v[114:115], 1, v[174:175]
	v_lshl_add_u64 v[126:127], v[168:169], 0, v[114:115]
	v_cvt_pk_bf16_f32 v116, v122, v123
	v_cvt_pk_bf16_f32 v117, v124, v125
	v_pk_mul_f32 v[106:107], v[106:107], v[172:173] op_sel_hi:[1,0]
	v_cvt_pk_bf16_f32 v118, v118, v119
	v_cvt_pk_bf16_f32 v119, v120, v121
	global_store_dwordx4 v[126:127], v[116:119], off sc1
	v_pk_mul_f32 v[108:109], v[108:109], v[172:173] op_sel_hi:[1,0]
	v_pk_mul_f32 v[110:111], v[110:111], v[172:173] op_sel_hi:[1,0]
	v_pk_mul_f32 v[116:117], v[106:107], s[10:11] op_sel_hi:[1,0]
	v_pk_mul_f32 v[120:121], v[108:109], s[10:11] op_sel_hi:[1,0]
	v_exp_f32_e32 v116, v116
	v_exp_f32_e32 v117, v117
	v_exp_f32_e32 v120, v120
	v_exp_f32_e32 v121, v121
	v_pk_mul_f32 v[106:107], v[106:107], v[110:111]
	v_pk_add_f32 v[116:117], v[116:117], 1.0 op_sel_hi:[1,0]
	v_pk_mul_f32 v[110:111], v[112:113], v[172:173] op_sel_hi:[1,0]
	v_rcp_f32_e32 v116, v116
	v_rcp_f32_e32 v117, v117
	v_pk_add_f32 v[112:113], v[120:121], 1.0 op_sel_hi:[1,0]
	v_pk_mul_f32 v[98:99], v[98:99], v[172:173] op_sel_hi:[1,0]
; __device__ __forceinline__ unsigned cvt_pk_bf16(float lo, float hi) { unsigned r; asm volatile("v_cvt_pk_bf16_f32 %0, %1, %2" : "=v"(r) : "v"(lo), "v"(hi)); return r; }
; __device__ __forceinline__ unsigned cvt_pk_bf16(float lo, float hi) { unsigned r; asm volatile("v_cvt_pk_bf16_f32 %0, %1, %2" : "=v"(r) : "v"(lo), "v"(hi)); return r; }
;     __device__ __forceinline__ void operator()(const f32x4 (&acc)[2][2][4][2], const Unit& u, int wr, int wc, int fr, int fq) const {
;     ...
;                         const f32x2 r2 = {rs[ai][m], rs[ai][m]};
;                         const f32x2 g = (f32x2){acc[ai][0][m][n][i], acc[ai][0][m][n][i + 1]} * r2, up = (f32x2){acc[ai][1][m][n][i], acc[ai][1][m][n][i + 1]} * r2;
;                         const f32x2 t = g * (f32x2){-1.4426950408889634f, -1.4426950408889634f};
;                         const f32x2 d = (f32x2){__builtin_amdgcn_exp2f(t.x), __builtin_amdgcn_exp2f(t.y)} + (f32x2){1.0f, 1.0f};
;                         const f32x2 o2 = (g * up) * (f32x2){__builtin_amdgcn_rcpf(d.x), __builtin_amdgcn_rcpf(d.y)};
;                         a[4 * n + i] = o2.x; a[4 * n + i + 1] = o2.y; }
;                 u32x4 w; w.x = cvt_pk_bf16(a[0], a[1]); w.y = cvt_pk_bf16(a[2], a[3]); w.z = cvt_pk_bf16(a[4], a[5]); w.w = cvt_pk_bf16(a[6], a[7]);
;                 *(u32x4*)rowp = w; }
	v_rcp_f32_e32 v112, v112
	v_rcp_f32_e32 v113, v113
	v_pk_mul_f32 v[106:107], v[106:107], v[116:117]
	v_pk_mul_f32 v[116:117], v[98:99], s[10:11] op_sel_hi:[1,0]
	v_pk_mul_f32 v[108:109], v[108:109], v[110:111]
	v_exp_f32_e32 v116, v116
	v_exp_f32_e32 v117, v117
	v_pk_mul_f32 v[100:101], v[100:101], v[172:173] op_sel_hi:[1,0]
	v_pk_mul_f32 v[108:109], v[108:109], v[112:113]
	v_pk_mul_f32 v[112:113], v[100:101], s[10:11] op_sel_hi:[1,0]
	v_pk_mul_f32 v[102:103], v[102:103], v[172:173] op_sel_hi:[1,0]
	v_exp_f32_e32 v112, v112
	v_exp_f32_e32 v113, v113
	v_pk_add_f32 v[110:111], v[116:117], 1.0 op_sel_hi:[1,0]
	v_pk_mul_f32 v[98:99], v[98:99], v[102:103]
	v_rcp_f32_e32 v102, v110
	v_rcp_f32_e32 v103, v111
	v_pk_add_f32 v[110:111], v[112:113], 1.0 op_sel_hi:[1,0]
	v_mad_i64_i32 v[118:119], s[22:23], v166, s46, v[148:149]
	v_rcp_f32_e32 v110, v110
	v_rcp_f32_e32 v111, v111
	v_pk_mul_f32 v[102:103], v[98:99], v[102:103]
	v_pk_mul_f32 v[98:99], v[104:105], v[172:173] op_sel_hi:[1,0]
	v_pk_mul_f32 v[90:91], v[90:91], v[162:163] op_sel_hi:[1,0]
	v_pk_mul_f32 v[98:99], v[100:101], v[98:99]
	v_pk_mul_f32 v[92:93], v[92:93], v[162:163] op_sel_hi:[1,0]
	v_pk_mul_f32 v[104:105], v[98:99], v[110:111]
	v_lshl_add_u64 v[110:111], v[118:119], 0, v[114:115]
	v_cvt_pk_bf16_f32 v98, v106, v107
	v_cvt_pk_bf16_f32 v99, v108, v109
	v_cvt_pk_bf16_f32 v100, v102, v103
	v_cvt_pk_bf16_f32 v101, v104, v105
	global_store_dwordx4 v[110:111], v[98:101], off sc1
	v_pk_mul_f32 v[102:103], v[92:93], s[10:11] op_sel_hi:[1,0]
	v_pk_mul_f32 v[94:95], v[94:95], v[162:163] op_sel_hi:[1,0]
	v_pk_mul_f32 v[98:99], v[90:91], s[10:11] op_sel_hi:[1,0]
	v_exp_f32_e32 v102, v102
	v_exp_f32_e32 v98, v98
	v_exp_f32_e32 v99, v99
	v_exp_f32_e32 v103, v103
	v_pk_mul_f32 v[90:91], v[90:91], v[94:95]
	v_pk_mul_f32 v[94:95], v[96:97], v[162:163] op_sel_hi:[1,0]
	v_pk_add_f32 v[98:99], v[98:99], 1.0 op_sel_hi:[1,0]
	v_pk_add_f32 v[96:97], v[102:103], 1.0 op_sel_hi:[1,0]
	v_rcp_f32_e32 v98, v98
	v_rcp_f32_e32 v99, v99
	v_rcp_f32_e32 v96, v96
	v_rcp_f32_e32 v97, v97
	v_pk_mul_f32 v[82:83], v[82:83], v[162:163] op_sel_hi:[1,0]
	v_pk_mul_f32 v[90:91], v[90:91], v[98:99]
	v_pk_mul_f32 v[98:99], v[82:83], s[10:11] op_sel_hi:[1,0]
	v_pk_mul_f32 v[92:93], v[92:93], v[94:95]
	v_exp_f32_e32 v98, v98
	v_exp_f32_e32 v99, v99
	v_pk_mul_f32 v[84:85], v[84:85], v[162:163] op_sel_hi:[1,0]
	v_pk_mul_f32 v[92:93], v[92:93], v[96:97]
	v_pk_mul_f32 v[96:97], v[84:85], s[10:11] op_sel_hi:[1,0]
	v_pk_mul_f32 v[86:87], v[86:87], v[162:163] op_sel_hi:[1,0]
	v_exp_f32_e32 v96, v96
	v_exp_f32_e32 v97, v97
	v_pk_add_f32 v[94:95], v[98:99], 1.0 op_sel_hi:[1,0]
	v_pk_mul_f32 v[82:83], v[82:83], v[86:87]
	v_rcp_f32_e32 v86, v94
	v_rcp_f32_e32 v87, v95
	v_pk_add_f32 v[94:95], v[96:97], 1.0 op_sel_hi:[1,0]
	v_rsq_f32_e32 v158, v158
	v_rcp_f32_e32 v94, v94
	v_rcp_f32_e32 v95, v95
	v_pk_mul_f32 v[86:87], v[82:83], v[86:87]
	v_pk_mul_f32 v[82:83], v[88:89], v[162:163] op_sel_hi:[1,0]
	v_mad_i64_i32 v[100:101], s[22:23], v160, s46, v[148:149]
	v_pk_mul_f32 v[82:83], v[84:85], v[82:83]
	v_pk_mul_f32 v[74:75], v[74:75], v[158:159] op_sel_hi:[1,0]
	v_pk_mul_f32 v[88:89], v[82:83], v[94:95]
	v_lshl_add_u64 v[94:95], v[100:101], 0, v[114:115]
	v_cvt_pk_bf16_f32 v82, v90, v91
	v_cvt_pk_bf16_f32 v83, v92, v93
	v_cvt_pk_bf16_f32 v84, v86, v87
	v_cvt_pk_bf16_f32 v85, v88, v89
	global_store_dwordx4 v[94:95], v[82:85], off sc1
	v_pk_mul_f32 v[76:77], v[76:77], v[158:159] op_sel_hi:[1,0]
	v_pk_mul_f32 v[78:79], v[78:79], v[158:159] op_sel_hi:[1,0]
	v_pk_mul_f32 v[82:83], v[74:75], s[10:11] op_sel_hi:[1,0]
	v_pk_mul_f32 v[86:87], v[76:77], s[10:11] op_sel_hi:[1,0]
	v_exp_f32_e32 v82, v82
	v_exp_f32_e32 v83, v83
	v_exp_f32_e32 v86, v86
	v_exp_f32_e32 v87, v87
	v_pk_mul_f32 v[74:75], v[74:75], v[78:79]
	v_pk_add_f32 v[82:83], v[82:83], 1.0 op_sel_hi:[1,0]
	v_pk_mul_f32 v[78:79], v[80:81], v[158:159] op_sel_hi:[1,0]
	v_rcp_f32_e32 v82, v82
	v_rcp_f32_e32 v83, v83
	v_pk_add_f32 v[80:81], v[86:87], 1.0 op_sel_hi:[1,0]
	v_pk_mul_f32 v[62:63], v[62:63], v[158:159] op_sel_hi:[1,0]
	v_rcp_f32_e32 v80, v80
	v_rcp_f32_e32 v81, v81
	v_pk_mul_f32 v[74:75], v[74:75], v[82:83]
	v_pk_mul_f32 v[82:83], v[62:63], s[10:11] op_sel_hi:[1,0]
	v_pk_mul_f32 v[76:77], v[76:77], v[78:79]
	v_exp_f32_e32 v82, v82
	v_exp_f32_e32 v83, v83
	v_pk_mul_f32 v[64:65], v[64:65], v[158:159] op_sel_hi:[1,0]
	v_pk_mul_f32 v[76:77], v[76:77], v[80:81]
	v_pk_mul_f32 v[80:81], v[64:65], s[10:11] op_sel_hi:[1,0]
	v_pk_mul_f32 v[70:71], v[70:71], v[158:159] op_sel_hi:[1,0]
	v_exp_f32_e32 v80, v80
	v_exp_f32_e32 v81, v81
	v_pk_add_f32 v[78:79], v[82:83], 1.0 op_sel_hi:[1,0]
	v_pk_mul_f32 v[62:63], v[62:63], v[70:71]
	v_rcp_f32_e32 v70, v78
	v_rcp_f32_e32 v71, v79
	v_pk_add_f32 v[78:79], v[80:81], 1.0 op_sel_hi:[1,0]
	v_mad_i64_i32 v[84:85], s[22:23], v156, s46, v[148:149]
	v_rcp_f32_e32 v78, v78
	v_rcp_f32_e32 v79, v79
	v_pk_mul_f32 v[70:71], v[62:63], v[70:71]
	v_pk_mul_f32 v[62:63], v[72:73], v[158:159] op_sel_hi:[1,0]
	v_pk_mul_f32 v[58:59], v[58:59], v[154:155] op_sel_hi:[1,0]
	v_pk_mul_f32 v[62:63], v[64:65], v[62:63]
	v_pk_mul_f32 v[60:61], v[60:61], v[154:155] op_sel_hi:[1,0]
	v_pk_mul_f32 v[72:73], v[62:63], v[78:79]
	v_lshl_add_u64 v[78:79], v[84:85], 0, v[114:115]
	v_cvt_pk_bf16_f32 v62, v74, v75
	v_cvt_pk_bf16_f32 v63, v76, v77
	v_cvt_pk_bf16_f32 v64, v70, v71
	v_cvt_pk_bf16_f32 v65, v72, v73
	global_store_dwordx4 v[78:79], v[62:65], off sc1
	v_pk_mul_f32 v[70:71], v[60:61], s[10:11] op_sel_hi:[1,0]
	v_pk_mul_f32 v[66:67], v[66:67], v[154:155] op_sel_hi:[1,0]
	v_pk_mul_f32 v[62:63], v[58:59], s[10:11] op_sel_hi:[1,0]
	v_exp_f32_e32 v70, v70
	v_exp_f32_e32 v62, v62
; __device__ __forceinline__ unsigned cvt_pk_bf16(float lo, float hi) { unsigned r; asm volatile("v_cvt_pk_bf16_f32 %0, %1, %2" : "=v"(r) : "v"(lo), "v"(hi)); return r; }
; __device__ __forceinline__ unsigned cvt_pk_bf16(float lo, float hi) { unsigned r; asm volatile("v_cvt_pk_bf16_f32 %0, %1, %2" : "=v"(r) : "v"(lo), "v"(hi)); return r; }
;     __device__ __forceinline__ void operator()(const f32x4 (&acc)[2][2][4][2], const Unit& u, int wr, int wc, int fr, int fq) const {
;     ...
;             for (int m = 0; m < 4; ++m) { const int row = row0 + ai * HALF + m * 16; bf16_t* rowp = O + (size_t)row * ldc + col0; float a[8];
; #pragma unroll
;                 for (int n = 0; n < 2; ++n)
; #pragma unroll
;                     for (int i = 0; i < 4; i += 2) {
;                         const f32x2 r2 = {rs[ai][m], rs[ai][m]};
;                         const f32x2 g = (f32x2){acc[ai][0][m][n][i], acc[ai][0][m][n][i + 1]} * r2, up = (f32x2){acc[ai][1][m][n][i], acc[ai][1][m][n][i + 1]} * r2;
;                         const f32x2 t = g * (f32x2){-1.4426950408889634f, -1.4426950408889634f};
;                         const f32x2 d = (f32x2){__builtin_amdgcn_exp2f(t.x), __builtin_amdgcn_exp2f(t.y)} + (f32x2){1.0f, 1.0f};
;                         const f32x2 o2 = (g * up) * (f32x2){__builtin_amdgcn_rcpf(d.x), __builtin_amdgcn_rcpf(d.y)};
;                         a[4 * n + i] = o2.x; a[4 * n + i + 1] = o2.y; }
;                 u32x4 w; w.x = cvt_pk_bf16(a[0], a[1]); w.y = cvt_pk_bf16(a[2], a[3]); w.z = cvt_pk_bf16(a[4], a[5]); w.w = cvt_pk_bf16(a[6], a[7]);
;                 *(u32x4*)rowp = w; }
	v_exp_f32_e32 v63, v63
	v_exp_f32_e32 v71, v71
	v_pk_mul_f32 v[58:59], v[58:59], v[66:67]
	v_pk_mul_f32 v[50:51], v[50:51], v[154:155] op_sel_hi:[1,0]
	v_pk_add_f32 v[62:63], v[62:63], 1.0 op_sel_hi:[1,0]
	v_pk_add_f32 v[66:67], v[70:71], 1.0 op_sel_hi:[1,0]
	v_rcp_f32_e32 v62, v62
	v_rcp_f32_e32 v63, v63
	v_rcp_f32_e32 v66, v66
	v_rcp_f32_e32 v67, v67
	v_pk_mul_f32 v[52:53], v[52:53], v[154:155] op_sel_hi:[1,0]
	v_pk_mul_f32 v[58:59], v[58:59], v[62:63]
	v_pk_mul_f32 v[62:63], v[68:69], v[154:155] op_sel_hi:[1,0]
	v_pk_mul_f32 v[68:69], v[50:51], s[10:11] op_sel_hi:[1,0]
	v_pk_mul_f32 v[60:61], v[60:61], v[62:63]
	v_exp_f32_e32 v68, v68
	v_exp_f32_e32 v69, v69
	v_pk_mul_f32 v[60:61], v[60:61], v[66:67]
	v_pk_mul_f32 v[66:67], v[52:53], s[10:11] op_sel_hi:[1,0]
	v_pk_mul_f32 v[54:55], v[54:55], v[154:155] op_sel_hi:[1,0]
	v_exp_f32_e32 v66, v66
	v_exp_f32_e32 v67, v67
	v_pk_add_f32 v[62:63], v[68:69], 1.0 op_sel_hi:[1,0]
	v_pk_mul_f32 v[50:51], v[50:51], v[54:55]
	v_rcp_f32_e32 v54, v62
	v_rcp_f32_e32 v55, v63
	v_fmamk_f32 v152, v152, 0x2d800000, v159
	v_pk_add_f32 v[62:63], v[66:67], 1.0 op_sel_hi:[1,0]
	v_rsq_f32_e32 v152, v152
	v_rcp_f32_e32 v62, v62
	v_rcp_f32_e32 v63, v63
	v_pk_mul_f32 v[54:55], v[50:51], v[54:55]
	v_pk_mul_f32 v[50:51], v[56:57], v[154:155] op_sel_hi:[1,0]
	v_mad_i64_i32 v[64:65], s[22:23], v165, s46, v[148:149]
	v_pk_mul_f32 v[50:51], v[52:53], v[50:51]
	v_pk_mul_f32 v[42:43], v[42:43], v[152:153] op_sel_hi:[1,0]
	v_pk_mul_f32 v[56:57], v[50:51], v[62:63]
	v_lshl_add_u64 v[62:63], v[64:65], 0, v[114:115]
	v_cvt_pk_bf16_f32 v50, v58, v59
	v_cvt_pk_bf16_f32 v51, v60, v61
	v_cvt_pk_bf16_f32 v52, v54, v55
	v_cvt_pk_bf16_f32 v53, v56, v57
	global_store_dwordx4 v[62:63], v[50:53], off sc1
	v_pk_mul_f32 v[44:45], v[44:45], v[152:153] op_sel_hi:[1,0]
	v_pk_mul_f32 v[46:47], v[46:47], v[152:153] op_sel_hi:[1,0]
	v_pk_mul_f32 v[50:51], v[42:43], s[10:11] op_sel_hi:[1,0]
	v_pk_mul_f32 v[54:55], v[44:45], s[10:11] op_sel_hi:[1,0]
	v_exp_f32_e32 v50, v50
	v_exp_f32_e32 v51, v51
	v_exp_f32_e32 v54, v54
	v_exp_f32_e32 v55, v55
	v_pk_mul_f32 v[42:43], v[42:43], v[46:47]
	v_pk_add_f32 v[50:51], v[50:51], 1.0 op_sel_hi:[1,0]
	v_pk_mul_f32 v[46:47], v[48:49], v[152:153] op_sel_hi:[1,0]
	v_rcp_f32_e32 v50, v50
	v_rcp_f32_e32 v51, v51
	v_pk_add_f32 v[48:49], v[54:55], 1.0 op_sel_hi:[1,0]
	v_pk_mul_f32 v[34:35], v[34:35], v[152:153] op_sel_hi:[1,0]
	v_rcp_f32_e32 v48, v48
	v_rcp_f32_e32 v49, v49
	v_pk_mul_f32 v[42:43], v[42:43], v[50:51]
	v_pk_mul_f32 v[50:51], v[34:35], s[10:11] op_sel_hi:[1,0]
	v_pk_mul_f32 v[44:45], v[44:45], v[46:47]
	v_exp_f32_e32 v50, v50
	v_exp_f32_e32 v51, v51
	v_pk_mul_f32 v[36:37], v[36:37], v[152:153] op_sel_hi:[1,0]
	v_pk_mul_f32 v[44:45], v[44:45], v[48:49]
	v_pk_mul_f32 v[48:49], v[36:37], s[10:11] op_sel_hi:[1,0]
	v_pk_mul_f32 v[38:39], v[38:39], v[152:153] op_sel_hi:[1,0]
	v_exp_f32_e32 v48, v48
	v_exp_f32_e32 v49, v49
	v_pk_add_f32 v[46:47], v[50:51], 1.0 op_sel_hi:[1,0]
	v_pk_mul_f32 v[34:35], v[34:35], v[38:39]
	v_rcp_f32_e32 v38, v46
	v_rcp_f32_e32 v39, v47
	v_pk_add_f32 v[46:47], v[48:49], 1.0 op_sel_hi:[1,0]
	v_mad_i64_i32 v[52:53], s[22:23], v163, s46, v[148:149]
	v_rcp_f32_e32 v46, v46
	v_rcp_f32_e32 v47, v47
	v_pk_mul_f32 v[38:39], v[34:35], v[38:39]
	v_pk_mul_f32 v[34:35], v[40:41], v[152:153] op_sel_hi:[1,0]
	v_pk_mul_f32 v[26:27], v[26:27], v[150:151] op_sel_hi:[1,0]
	v_pk_mul_f32 v[34:35], v[36:37], v[34:35]
	v_pk_mul_f32 v[28:29], v[28:29], v[150:151] op_sel_hi:[1,0]
	v_pk_mul_f32 v[40:41], v[34:35], v[46:47]
	v_lshl_add_u64 v[46:47], v[52:53], 0, v[114:115]
	v_cvt_pk_bf16_f32 v34, v42, v43
	v_cvt_pk_bf16_f32 v35, v44, v45
	v_cvt_pk_bf16_f32 v36, v38, v39
	v_cvt_pk_bf16_f32 v37, v40, v41
	global_store_dwordx4 v[46:47], v[34:37], off sc1
	v_pk_mul_f32 v[38:39], v[28:29], s[10:11] op_sel_hi:[1,0]
	v_pk_mul_f32 v[30:31], v[30:31], v[150:151] op_sel_hi:[1,0]
	v_pk_mul_f32 v[34:35], v[26:27], s[10:11] op_sel_hi:[1,0]
	v_exp_f32_e32 v38, v38
	v_exp_f32_e32 v34, v34
	v_exp_f32_e32 v35, v35
	v_exp_f32_e32 v39, v39
	v_pk_mul_f32 v[26:27], v[26:27], v[30:31]
	v_pk_mul_f32 v[30:31], v[32:33], v[150:151] op_sel_hi:[1,0]
	v_pk_add_f32 v[34:35], v[34:35], 1.0 op_sel_hi:[1,0]
	v_pk_add_f32 v[32:33], v[38:39], 1.0 op_sel_hi:[1,0]
	v_rcp_f32_e32 v34, v34
	v_rcp_f32_e32 v35, v35
	v_rcp_f32_e32 v32, v32
	v_rcp_f32_e32 v33, v33
	v_pk_mul_f32 v[18:19], v[18:19], v[150:151] op_sel_hi:[1,0]
	v_pk_mul_f32 v[26:27], v[26:27], v[34:35]
	v_pk_mul_f32 v[34:35], v[18:19], s[10:11] op_sel_hi:[1,0]
	v_pk_mul_f32 v[28:29], v[28:29], v[30:31]
	v_exp_f32_e32 v34, v34
	v_exp_f32_e32 v35, v35
; __device__ __forceinline__ unsigned cvt_pk_bf16(float lo, float hi) { unsigned r; asm volatile("v_cvt_pk_bf16_f32 %0, %1, %2" : "=v"(r) : "v"(lo), "v"(hi)); return r; }
; __device__ __forceinline__ unsigned cvt_pk_bf16(float lo, float hi) { unsigned r; asm volatile("v_cvt_pk_bf16_f32 %0, %1, %2" : "=v"(r) : "v"(lo), "v"(hi)); return r; }
; #define PG8_BAR __builtin_amdgcn_s_barrier()
;     __device__ __forceinline__ void operator()(const f32x4 (&acc)[2][2][4][2], const Unit& u, int wr, int wc, int fr, int fq) const {
;     ...
;             for (int m = 0; m < 4; ++m) { const int row = row0 + ai * HALF + m * 16; bf16_t* rowp = O + (size_t)row * ldc + col0; float a[8];
; #pragma unroll
;                 for (int n = 0; n < 2; ++n)
; #pragma unroll
;                     for (int i = 0; i < 4; i += 2) {
;                         const f32x2 r2 = {rs[ai][m], rs[ai][m]};
;                         const f32x2 g = (f32x2){acc[ai][0][m][n][i], acc[ai][0][m][n][i + 1]} * r2, up = (f32x2){acc[ai][1][m][n][i], acc[ai][1][m][n][i + 1]} * r2;
;                         const f32x2 t = g * (f32x2){-1.4426950408889634f, -1.4426950408889634f};
;                         const f32x2 d = (f32x2){__builtin_amdgcn_exp2f(t.x), __builtin_amdgcn_exp2f(t.y)} + (f32x2){1.0f, 1.0f};
;                         const f32x2 o2 = (g * up) * (f32x2){__builtin_amdgcn_rcpf(d.x), __builtin_amdgcn_rcpf(d.y)};
;                         a[4 * n + i] = o2.x; a[4 * n + i + 1] = o2.y; }
;                 u32x4 w; w.x = cvt_pk_bf16(a[0], a[1]); w.y = cvt_pk_bf16(a[2], a[3]); w.z = cvt_pk_bf16(a[4], a[5]); w.w = cvt_pk_bf16(a[6], a[7]);
;                 *(u32x4*)rowp = w; }
; template <class Epi, class Sched, bool ALIGN_EPI = false, bool SP2 = false>
; __device__ __forceinline__ void gemm_phase(PG8_LAS unsigned char* lds, const Gemm g, const Sched& S, const Epi& E) {
;     ...
; #pragma unroll
;         for (int a = 0; a < 2; ++a)
; #pragma unroll
;             for (int b = 0; b < 2; ++b)
; #pragma unroll
;                 for (int m = 0; m < 4; ++m)
; #pragma unroll
;                     for (int n = 0; n < 2; ++n) { d64x2 z_; asm volatile("v_mov_b64 %0, 0\n\tv_mov_b64 %1, 0" : "=v"(z_.x), "=v"(z_.y)); acc[a][b][m][n] = __builtin_bit_cast(f32x4, z_); }
;         cur = nxt; cA = nA; cB = nB; ++ui;
;         if constexpr (ALIGN_EPI) { if (wr == 1) PG8_BAR; }
	v_pk_mul_f32 v[20:21], v[20:21], v[150:151] op_sel_hi:[1,0]
	v_pk_mul_f32 v[28:29], v[28:29], v[32:33]
	v_pk_mul_f32 v[32:33], v[20:21], s[10:11] op_sel_hi:[1,0]
	v_pk_mul_f32 v[22:23], v[22:23], v[150:151] op_sel_hi:[1,0]
	v_exp_f32_e32 v32, v32
	v_exp_f32_e32 v33, v33
	v_pk_add_f32 v[30:31], v[34:35], 1.0 op_sel_hi:[1,0]
	v_pk_mul_f32 v[18:19], v[18:19], v[22:23]
	v_rcp_f32_e32 v22, v30
	v_rcp_f32_e32 v23, v31
	v_fmamk_f32 v146, v146, 0x2d800000, v159
	v_pk_add_f32 v[30:31], v[32:33], 1.0 op_sel_hi:[1,0]
	v_rsq_f32_e32 v146, v146
	v_rcp_f32_e32 v30, v30
	v_rcp_f32_e32 v31, v31
	v_pk_mul_f32 v[22:23], v[18:19], v[22:23]
	v_pk_mul_f32 v[18:19], v[24:25], v[150:151] op_sel_hi:[1,0]
	v_mad_i64_i32 v[36:37], s[22:23], v161, s46, v[148:149]
	v_pk_mul_f32 v[18:19], v[20:21], v[18:19]
	v_pk_mul_f32 v[10:11], v[10:11], v[146:147] op_sel_hi:[1,0]
	v_pk_mul_f32 v[24:25], v[18:19], v[30:31]
	v_lshl_add_u64 v[30:31], v[36:37], 0, v[114:115]
	v_cvt_pk_bf16_f32 v18, v26, v27
	v_cvt_pk_bf16_f32 v19, v28, v29
	v_cvt_pk_bf16_f32 v20, v22, v23
	v_cvt_pk_bf16_f32 v21, v24, v25
	global_store_dwordx4 v[30:31], v[18:21], off sc1
	v_pk_mul_f32 v[12:13], v[12:13], v[146:147] op_sel_hi:[1,0]
	v_pk_mul_f32 v[14:15], v[14:15], v[146:147] op_sel_hi:[1,0]
	v_pk_mul_f32 v[18:19], v[10:11], s[10:11] op_sel_hi:[1,0]
	v_pk_mul_f32 v[22:23], v[12:13], s[10:11] op_sel_hi:[1,0]
	v_exp_f32_e32 v18, v18
	v_exp_f32_e32 v19, v19
	v_exp_f32_e32 v22, v22
	v_exp_f32_e32 v23, v23
	v_pk_mul_f32 v[10:11], v[10:11], v[14:15]
	v_pk_add_f32 v[18:19], v[18:19], 1.0 op_sel_hi:[1,0]
	v_pk_mul_f32 v[14:15], v[16:17], v[146:147] op_sel_hi:[1,0]
	v_rcp_f32_e32 v18, v18
	v_rcp_f32_e32 v19, v19
	v_pk_add_f32 v[16:17], v[22:23], 1.0 op_sel_hi:[1,0]
	v_pk_mul_f32 v[2:3], v[2:3], v[146:147] op_sel_hi:[1,0]
	v_rcp_f32_e32 v16, v16
	v_rcp_f32_e32 v17, v17
	v_pk_mul_f32 v[10:11], v[10:11], v[18:19]
	v_pk_mul_f32 v[18:19], v[2:3], s[10:11] op_sel_hi:[1,0]
	v_pk_mul_f32 v[12:13], v[12:13], v[14:15]
	v_exp_f32_e32 v18, v18
	v_exp_f32_e32 v19, v19
	v_pk_mul_f32 v[4:5], v[4:5], v[146:147] op_sel_hi:[1,0]
	v_pk_mul_f32 v[12:13], v[12:13], v[16:17]
	v_pk_mul_f32 v[16:17], v[4:5], s[10:11] op_sel_hi:[1,0]
	v_pk_mul_f32 v[6:7], v[6:7], v[146:147] op_sel_hi:[1,0]
	v_exp_f32_e32 v16, v16
	v_exp_f32_e32 v17, v17
	v_pk_add_f32 v[14:15], v[18:19], 1.0 op_sel_hi:[1,0]
	v_pk_mul_f32 v[2:3], v[2:3], v[6:7]
	v_rcp_f32_e32 v6, v14
	v_rcp_f32_e32 v7, v15
	v_pk_add_f32 v[14:15], v[16:17], 1.0 op_sel_hi:[1,0]
	v_mad_i64_i32 v[20:21], s[22:23], v157, s46, v[148:149]
	v_rcp_f32_e32 v14, v14
	v_rcp_f32_e32 v15, v15
	v_pk_mul_f32 v[6:7], v[2:3], v[6:7]
	v_pk_mul_f32 v[2:3], v[8:9], v[146:147] op_sel_hi:[1,0]
	s_nop 0
	v_pk_mul_f32 v[2:3], v[4:5], v[2:3]
	s_nop 0
	v_pk_mul_f32 v[8:9], v[2:3], v[14:15]
	v_lshl_add_u64 v[14:15], v[20:21], 0, v[114:115]
	v_cvt_pk_bf16_f32 v2, v10, v11
	v_cvt_pk_bf16_f32 v3, v12, v13
	v_cvt_pk_bf16_f32 v4, v6, v7
	v_cvt_pk_bf16_f32 v5, v8, v9
	global_store_dwordx4 v[14:15], v[2:5], off sc1
	s_cbranch_vccnz .LBB0_1677
	s_andn2_b64 vcc, exec, s[2:3]
	v_mov_b64 v[122:123], 0
	v_mov_b64 v[124:125], 0
	v_mov_b64 v[114:115], 0
	v_mov_b64 v[116:117], 0
	v_mov_b64 v[106:107], 0
	v_mov_b64 v[108:109], 0
	v_mov_b64 v[98:99], 0
	v_mov_b64 v[100:101], 0
	v_mov_b64 v[90:91], 0
	v_mov_b64 v[92:93], 0
	v_mov_b64 v[82:83], 0
	v_mov_b64 v[84:85], 0
	v_mov_b64 v[74:75], 0
	v_mov_b64 v[76:77], 0
	v_mov_b64 v[62:63], 0
	v_mov_b64 v[64:65], 0
	v_mov_b64 v[126:127], 0
	v_mov_b64 v[128:129], 0
	v_mov_b64 v[118:119], 0
	v_mov_b64 v[120:121], 0
	v_mov_b64 v[110:111], 0
	v_mov_b64 v[112:113], 0
	v_mov_b64 v[102:103], 0
	v_mov_b64 v[104:105], 0
	v_mov_b64 v[94:95], 0
	v_mov_b64 v[96:97], 0
	v_mov_b64 v[86:87], 0
	v_mov_b64 v[88:89], 0
	v_mov_b64 v[78:79], 0
	v_mov_b64 v[80:81], 0
	v_mov_b64 v[70:71], 0
	v_mov_b64 v[72:73], 0
	v_mov_b64 v[58:59], 0
	v_mov_b64 v[60:61], 0
	v_mov_b64 v[50:51], 0
	v_mov_b64 v[52:53], 0
	v_mov_b64 v[42:43], 0
	v_mov_b64 v[44:45], 0
	v_mov_b64 v[34:35], 0
	v_mov_b64 v[36:37], 0
	v_mov_b64 v[26:27], 0
	v_mov_b64 v[28:29], 0
	v_mov_b64 v[18:19], 0
	v_mov_b64 v[20:21], 0
	v_mov_b64 v[10:11], 0
	v_mov_b64 v[12:13], 0
	v_mov_b64 v[2:3], 0
	v_mov_b64 v[4:5], 0
	v_mov_b64 v[66:67], 0
	v_mov_b64 v[68:69], 0
	v_mov_b64 v[54:55], 0
	v_mov_b64 v[56:57], 0
	v_mov_b64 v[46:47], 0
	v_mov_b64 v[48:49], 0
	v_mov_b64 v[38:39], 0
	v_mov_b64 v[40:41], 0
	v_mov_b64 v[30:31], 0
	v_mov_b64 v[32:33], 0
	v_mov_b64 v[22:23], 0
	v_mov_b64 v[24:25], 0
	v_mov_b64 v[14:15], 0
	v_mov_b64 v[16:17], 0
	v_mov_b64 v[6:7], 0
	v_mov_b64 v[8:9], 0
	s_cbranch_vccnz .LBB0_1676
	s_barrier
	s_branch .LBB0_1676

; __device__ __forceinline__ unsigned cvt_pk_bf16(float lo, float hi) { unsigned r; asm volatile("v_cvt_pk_bf16_f32 %0, %1, %2" : "=v"(r) : "v"(lo), "v"(hi)); return r; }
; __device__ __forceinline__ unsigned cvt_pk_bf16(float lo, float hi) { unsigned r; asm volatile("v_cvt_pk_bf16_f32 %0, %1, %2" : "=v"(r) : "v"(lo), "v"(hi)); return r; }
;     __device__ __forceinline__ void operator()(const f32x4 (&acc)[2][2][4][2], const Unit& u, int wr, int wc, int fr, int fq) const {
;     ...
;                 for (int bj = 0; bj < 2; ++bj) { const size_t off = (size_t)(row0 + ai * HALF + m * 16) * ldc + col0 + bj * HALF;
;                     if (BASE_F32) { const float* bp = (const float*)base + off; b0[m][bj] = *(const f32x4*)bp; b1[m][bj] = *(const f32x4*)(bp + 4); }
;                     else { const u32x4 r = *(const u32x4*)((const bf16_t*)base + off);
;                         b0[m][bj] = (f32x4){__uint_as_float(r.x << 16), __uint_as_float(r.x & 0xffff0000u), __uint_as_float(r.y << 16), __uint_as_float(r.y & 0xffff0000u)};
;                         b1[m][bj] = (f32x4){__uint_as_float(r.z << 16), __uint_as_float(r.z & 0xffff0000u), __uint_as_float(r.w << 16), __uint_as_float(r.w & 0xffff0000u)}; } }
; #pragma unroll
;             for (int m = 0; m < 4; ++m) { const int row = row0 + ai * HALF + m * 16; const size_t off = (size_t)row * ldc + col0; f32x2 q2 = {0.f, 0.f};
; #pragma unroll
;                 for (int bj = 0; bj < 2; ++bj) { const f32x4 v0 = acc[ai][bj][m][0] + b0[m][bj], v1 = acc[ai][bj][m][1] + b1[m][bj];
;                     { const f32x2 e0 = {v0[0], v0[1]}, e1 = {v0[2], v0[3]}, e2 = {v1[0], v1[1]}, e3 = {v1[2], v1[3]}; q2 = e0 * e0 + q2; q2 = e1 * e1 + q2; q2 = e2 * e2 + q2; q2 = e3 * e3 + q2; }
;                     u32x4 w; w.x = cvt_pk_bf16(v0[0], v0[1]); w.y = cvt_pk_bf16(v0[2], v0[3]); w.z = cvt_pk_bf16(v1[0], v1[1]); w.w = cvt_pk_bf16(v1[2], v1[3]);
;                     *(u32x4*)(out + off + bj * HALF) = w; }
;                 float q = q2.x + q2.y; q += __shfl_xor(q, 16); q += __shfl_xor(q, 32);
;                 if (fq == 0) atomicAdd(ssq + row, (ssq_t)(q * SSQ_FIX + 0.5f)); }
.Lepi_rest_1804:
	v_and_b32_e32 v199, 64, v185
	v_xor_b32_e32 v198, 16, v185
	v_add_u32_e32 v199, 64, v199
	v_xor_b32_e32 v200, 32, v185
	v_cmp_lt_i32_e32 vcc, v198, v199
	s_waitcnt vmcnt(0)
	v_lshlrev_b32_e32 v202, 16, v192
	v_cndmask_b32_e32 v201, v185, v198, vcc
	v_cmp_lt_i32_e32 vcc, v200, v199
	v_lshl_add_u64 v[198:199], s[96:97], 0, v[186:187]
	v_lshl_add_u64 v[196:197], v[198:199], 0, v[196:197]
	v_lshlrev_b32_e32 v198, 16, v188
	v_and_b32_e32 v199, 0xffff0000, v188
	v_lshlrev_b32_e32 v188, 16, v189
	v_and_b32_e32 v189, 0xffff0000, v189
	v_cndmask_b32_e32 v206, v185, v200, vcc
	v_lshlrev_b32_e32 v186, 2, v201
	v_lshlrev_b32_e32 v200, 16, v190
	v_and_b32_e32 v201, 0xffff0000, v190
	v_lshlrev_b32_e32 v190, 16, v191
	v_and_b32_e32 v191, 0xffff0000, v191
	v_pk_add_f32 v[116:117], v[116:117], v[188:189]
	v_pk_add_f32 v[188:189], v[114:115], v[198:199]
	v_pk_add_f32 v[120:121], v[120:121], v[190:191]
	v_pk_mul_f32 v[190:191], v[116:117], v[116:117]
	v_pk_add_f32 v[118:119], v[118:119], v[200:201]
	v_cvt_pk_bf16_f32 v114, v188, v189
	v_cvt_pk_bf16_f32 v115, v116, v117
	v_pk_fma_f32 v[116:117], v[188:189], v[188:189], v[190:191]
	v_and_b32_e32 v203, 0xffff0000, v192
	v_pk_fma_f32 v[116:117], v[118:119], v[118:119], v[116:117]
	v_lshlrev_b32_e32 v192, 16, v193
	v_and_b32_e32 v193, 0xffff0000, v193
	v_pk_add_f32 v[122:123], v[122:123], v[202:203]
	v_pk_fma_f32 v[116:117], v[120:121], v[120:121], v[116:117]
	v_lshlrev_b32_e32 v204, 16, v194
	v_and_b32_e32 v205, 0xffff0000, v194
	v_pk_add_f32 v[124:125], v[124:125], v[192:193]
	v_pk_fma_f32 v[116:117], v[122:123], v[122:123], v[116:117]
	v_lshlrev_b32_e32 v194, 16, v195
	v_and_b32_e32 v195, 0xffff0000, v195
	v_pk_add_f32 v[126:127], v[126:127], v[204:205]
	v_pk_fma_f32 v[116:117], v[124:125], v[124:125], v[116:117]
	v_pk_add_f32 v[128:129], v[128:129], v[194:195]
	v_pk_fma_f32 v[116:117], v[126:127], v[126:127], v[116:117]
	s_nop 0
	v_pk_fma_f32 v[116:117], v[128:129], v[128:129], v[116:117]
	s_nop 0
	v_add_f32_e32 v187, v116, v117
	ds_bpermute_b32 v188, v186, v187
	v_cvt_pk_bf16_f32 v116, v118, v119
	v_cvt_pk_bf16_f32 v117, v120, v121
	global_store_dwordx4 v[196:197], v[114:117], off sc1
	v_cvt_pk_bf16_f32 v118, v122, v123
	v_cvt_pk_bf16_f32 v119, v124, v125
	v_cvt_pk_bf16_f32 v120, v126, v127
	v_cvt_pk_bf16_f32 v121, v128, v129
	global_store_dwordx4 v[196:197], v[118:121], off offset:256 sc1
	s_waitcnt lgkmcnt(0)
	v_add_f32_e32 v115, v187, v188
	v_lshlrev_b32_e32 v114, 2, v206
	ds_bpermute_b32 v116, v114, v115
	s_and_saveexec_b64 s[16:17], s[0:1]
	s_cbranch_execz .LBB0_1806
	s_waitcnt lgkmcnt(0)
	v_add_f32_e32 v115, v115, v116
	v_fma_f32 v115, v115, s40, 0.5
	v_trunc_f32_e32 v115, v115
	v_mul_f32_e32 v116, 0x2f800000, v115
	v_floor_f32_e32 v117, v116
	v_fmac_f32_e32 v115, 0xcf800000, v117
	v_cvt_u32_f32_e32 v116, v115
	v_cvt_u32_f32_e32 v117, v117
	v_lshl_add_u64 v[118:119], v[174:175], 3, s[8:9]
	global_atomic_add_x2 v[118:119], v[116:117], off
.LBB0_1806:
	s_or_b64 exec, exec, s[16:17]
	v_lshlrev_b32_e32 v120, 16, v151
	v_and_b32_e32 v121, 0xffff0000, v151
	v_lshlrev_b32_e32 v118, 16, v150
	v_and_b32_e32 v119, 0xffff0000, v150
	v_lshlrev_b32_e32 v122, 16, v152
	v_and_b32_e32 v123, 0xffff0000, v152
	v_lshlrev_b32_e32 v124, 16, v153
	v_and_b32_e32 v125, 0xffff0000, v153
	v_pk_add_f32 v[108:109], v[108:109], v[120:121]
	v_pk_add_f32 v[106:107], v[106:107], v[118:119]
	v_pk_add_f32 v[118:119], v[100:101], v[124:125]
	v_pk_add_f32 v[100:101], v[98:99], v[122:123]
	v_pk_mul_f32 v[98:99], v[108:109], v[108:109]
	v_lshlrev_b32_e32 v126, 16, v146
	v_pk_fma_f32 v[98:99], v[106:107], v[106:107], v[98:99]
	v_and_b32_e32 v127, 0xffff0000, v146
	v_pk_fma_f32 v[98:99], v[100:101], v[100:101], v[98:99]
	v_lshlrev_b32_e32 v128, 16, v147
	v_and_b32_e32 v129, 0xffff0000, v147
	v_pk_fma_f32 v[120:121], v[118:119], v[118:119], v[98:99]
	v_cvt_pk_bf16_f32 v98, v106, v107
	v_cvt_pk_bf16_f32 v99, v108, v109
	v_pk_add_f32 v[108:109], v[110:111], v[126:127]
	v_lshlrev_b32_e32 v146, 16, v148
	v_and_b32_e32 v147, 0xffff0000, v148
	v_pk_add_f32 v[106:107], v[112:113], v[128:129]
	v_pk_fma_f32 v[110:111], v[108:109], v[108:109], v[120:121]
	v_lshlrev_b32_e32 v148, 16, v149
	v_and_b32_e32 v149, 0xffff0000, v149
	v_pk_add_f32 v[102:103], v[102:103], v[146:147]
	v_pk_fma_f32 v[110:111], v[106:107], v[106:107], v[110:111]
	v_pk_add_f32 v[104:105], v[104:105], v[148:149]
	v_pk_fma_f32 v[110:111], v[102:103], v[102:103], v[110:111]
	s_waitcnt lgkmcnt(0)
	v_lshlrev_b64 v[116:117], 12, v[180:181]
	v_pk_fma_f32 v[110:111], v[104:105], v[104:105], v[110:111]
	v_cvt_pk_bf16_f32 v100, v100, v101
	v_cvt_pk_bf16_f32 v101, v118, v119
	s_nop 0
	v_add_f32_e32 v112, v110, v111
	ds_bpermute_b32 v113, v186, v112
	v_lshl_add_u64 v[110:111], v[116:117], 1, s[96:97]
	v_lshl_add_u64 v[110:111], v[170:171], 1, v[110:111]
	global_store_dwordx4 v[110:111], v[98:101], off sc1
	s_waitcnt lgkmcnt(0)
	s_nop 0
	v_add_f32_e32 v98, v112, v113
	ds_bpermute_b32 v99, v114, v98
	v_cvt_pk_bf16_f32 v100, v108, v109
	v_cvt_pk_bf16_f32 v101, v106, v107
	v_cvt_pk_bf16_f32 v102, v102, v103
	v_cvt_pk_bf16_f32 v103, v104, v105
	global_store_dwordx4 v[110:111], v[100:103], off offset:256 sc1
	s_and_saveexec_b64 s[16:17], s[0:1]
	s_cbranch_execz .LBB0_1808
	s_waitcnt lgkmcnt(0)
	v_add_f32_e32 v98, v98, v99
	v_fma_f32 v98, v98, s40, 0.5
	v_trunc_f32_e32 v98, v98
	v_mul_f32_e32 v99, 0x2f800000, v98
	v_floor_f32_e32 v99, v99
	v_fmac_f32_e32 v98, 0xcf800000, v99
	v_cvt_u32_f32_e32 v98, v98
	v_cvt_u32_f32_e32 v99, v99
	v_lshl_add_u64 v[100:101], v[180:181], 3, s[8:9]
	global_atomic_add_x2 v[100:101], v[98:99], off
; __device__ __forceinline__ unsigned cvt_pk_bf16(float lo, float hi) { unsigned r; asm volatile("v_cvt_pk_bf16_f32 %0, %1, %2" : "=v"(r) : "v"(lo), "v"(hi)); return r; }
; __device__ __forceinline__ unsigned cvt_pk_bf16(float lo, float hi) { unsigned r; asm volatile("v_cvt_pk_bf16_f32 %0, %1, %2" : "=v"(r) : "v"(lo), "v"(hi)); return r; }
;     __device__ __forceinline__ void operator()(const f32x4 (&acc)[2][2][4][2], const Unit& u, int wr, int wc, int fr, int fq) const {
;     ...
;                 for (int bj = 0; bj < 2; ++bj) { const size_t off = (size_t)(row0 + ai * HALF + m * 16) * ldc + col0 + bj * HALF;
;                     if (BASE_F32) { const float* bp = (const float*)base + off; b0[m][bj] = *(const f32x4*)bp; b1[m][bj] = *(const f32x4*)(bp + 4); }
;                     else { const u32x4 r = *(const u32x4*)((const bf16_t*)base + off);
;                         b0[m][bj] = (f32x4){__uint_as_float(r.x << 16), __uint_as_float(r.x & 0xffff0000u), __uint_as_float(r.y << 16), __uint_as_float(r.y & 0xffff0000u)};
;                         b1[m][bj] = (f32x4){__uint_as_float(r.z << 16), __uint_as_float(r.z & 0xffff0000u), __uint_as_float(r.w << 16), __uint_as_float(r.w & 0xffff0000u)}; } }
; #pragma unroll
;             for (int m = 0; m < 4; ++m) { const int row = row0 + ai * HALF + m * 16; const size_t off = (size_t)row * ldc + col0; f32x2 q2 = {0.f, 0.f};
; #pragma unroll
;                 for (int bj = 0; bj < 2; ++bj) { const f32x4 v0 = acc[ai][bj][m][0] + b0[m][bj], v1 = acc[ai][bj][m][1] + b1[m][bj];
;                     { const f32x2 e0 = {v0[0], v0[1]}, e1 = {v0[2], v0[3]}, e2 = {v1[0], v1[1]}, e3 = {v1[2], v1[3]}; q2 = e0 * e0 + q2; q2 = e1 * e1 + q2; q2 = e2 * e2 + q2; q2 = e3 * e3 + q2; }
;                     u32x4 w; w.x = cvt_pk_bf16(v0[0], v0[1]); w.y = cvt_pk_bf16(v0[2], v0[3]); w.z = cvt_pk_bf16(v1[0], v1[1]); w.w = cvt_pk_bf16(v1[2], v1[3]);
;                     *(u32x4*)(out + off + bj * HALF) = w; }
;                 float q = q2.x + q2.y; q += __shfl_xor(q, 16); q += __shfl_xor(q, 32);
;                 if (fq == 0) atomicAdd(ssq + row, (ssq_t)(q * SSQ_FIX + 0.5f)); }
.LBB0_1808:
	s_or_b64 exec, exec, s[16:17]
	v_lshlrev_b32_e32 v102, 16, v143
	v_and_b32_e32 v103, 0xffff0000, v143
	v_lshlrev_b32_e32 v100, 16, v142
	v_and_b32_e32 v101, 0xffff0000, v142
	v_lshlrev_b32_e32 v104, 16, v144
	v_and_b32_e32 v105, 0xffff0000, v144
	v_lshlrev_b32_e32 v106, 16, v145
	v_and_b32_e32 v107, 0xffff0000, v145
	v_pk_add_f32 v[92:93], v[92:93], v[102:103]
	v_pk_add_f32 v[90:91], v[90:91], v[100:101]
	v_pk_add_f32 v[100:101], v[84:85], v[106:107]
	v_pk_add_f32 v[84:85], v[82:83], v[104:105]
	v_pk_mul_f32 v[82:83], v[92:93], v[92:93]
	v_lshlrev_b32_e32 v108, 16, v138
	v_pk_fma_f32 v[82:83], v[90:91], v[90:91], v[82:83]
	v_and_b32_e32 v109, 0xffff0000, v138
	v_pk_fma_f32 v[82:83], v[84:85], v[84:85], v[82:83]
	v_lshlrev_b32_e32 v110, 16, v139
	v_and_b32_e32 v111, 0xffff0000, v139
	v_pk_fma_f32 v[102:103], v[100:101], v[100:101], v[82:83]
	v_cvt_pk_bf16_f32 v82, v90, v91
	v_cvt_pk_bf16_f32 v83, v92, v93
	v_pk_add_f32 v[92:93], v[94:95], v[108:109]
	v_lshlrev_b32_e32 v112, 16, v140
	v_and_b32_e32 v113, 0xffff0000, v140
	v_pk_add_f32 v[90:91], v[96:97], v[110:111]
	v_pk_fma_f32 v[94:95], v[92:93], v[92:93], v[102:103]
	v_lshlrev_b32_e32 v116, 16, v141
	v_and_b32_e32 v117, 0xffff0000, v141
	v_pk_add_f32 v[86:87], v[86:87], v[112:113]
	v_pk_fma_f32 v[94:95], v[90:91], v[90:91], v[94:95]
	v_pk_add_f32 v[88:89], v[88:89], v[116:117]
	v_pk_fma_f32 v[94:95], v[86:87], v[86:87], v[94:95]
	s_waitcnt lgkmcnt(0)
	v_lshlrev_b64 v[98:99], 12, v[178:179]
	v_pk_fma_f32 v[94:95], v[88:89], v[88:89], v[94:95]
	v_cvt_pk_bf16_f32 v84, v84, v85
	v_cvt_pk_bf16_f32 v85, v100, v101
	s_nop 0
	v_add_f32_e32 v96, v94, v95
	ds_bpermute_b32 v97, v186, v96
	v_lshl_add_u64 v[94:95], v[98:99], 1, s[96:97]
	v_lshl_add_u64 v[94:95], v[170:171], 1, v[94:95]
	global_store_dwordx4 v[94:95], v[82:85], off sc1
	s_waitcnt lgkmcnt(0)
	s_nop 0
	v_add_f32_e32 v82, v96, v97
	ds_bpermute_b32 v83, v114, v82
	v_cvt_pk_bf16_f32 v84, v92, v93
	v_cvt_pk_bf16_f32 v85, v90, v91
	v_cvt_pk_bf16_f32 v86, v86, v87
	v_cvt_pk_bf16_f32 v87, v88, v89
	global_store_dwordx4 v[94:95], v[84:87], off offset:256 sc1
	s_and_saveexec_b64 s[16:17], s[0:1]
	s_cbranch_execz .LBB0_1810
	s_waitcnt lgkmcnt(0)
	v_add_f32_e32 v82, v82, v83
	v_fma_f32 v82, v82, s40, 0.5
	v_trunc_f32_e32 v82, v82
	v_mul_f32_e32 v83, 0x2f800000, v82
	v_floor_f32_e32 v83, v83
	v_fmac_f32_e32 v82, 0xcf800000, v83
	v_cvt_u32_f32_e32 v82, v82
	v_cvt_u32_f32_e32 v83, v83
	v_lshl_add_u64 v[84:85], v[178:179], 3, s[8:9]
	global_atomic_add_x2 v[84:85], v[82:83], off
.LBB0_1810:
	s_or_b64 exec, exec, s[16:17]
	v_lshlrev_b32_e32 v86, 16, v135
	v_and_b32_e32 v87, 0xffff0000, v135
	v_lshlrev_b32_e32 v84, 16, v134
	v_and_b32_e32 v85, 0xffff0000, v134
	v_lshlrev_b32_e32 v88, 16, v136
	v_and_b32_e32 v89, 0xffff0000, v136
	v_lshlrev_b32_e32 v90, 16, v137
	v_and_b32_e32 v91, 0xffff0000, v137
	v_pk_add_f32 v[76:77], v[76:77], v[86:87]
	v_pk_add_f32 v[74:75], v[74:75], v[84:85]
	v_pk_add_f32 v[84:85], v[68:69], v[90:91]
	v_pk_add_f32 v[68:69], v[66:67], v[88:89]
	v_pk_mul_f32 v[66:67], v[76:77], v[76:77]
	v_lshlrev_b32_e32 v92, 16, v130
	v_pk_fma_f32 v[66:67], v[74:75], v[74:75], v[66:67]
	v_and_b32_e32 v93, 0xffff0000, v130
	v_pk_fma_f32 v[66:67], v[68:69], v[68:69], v[66:67]
	v_lshlrev_b32_e32 v94, 16, v131
	v_and_b32_e32 v95, 0xffff0000, v131
	v_pk_fma_f32 v[86:87], v[84:85], v[84:85], v[66:67]
	v_cvt_pk_bf16_f32 v66, v74, v75
	v_cvt_pk_bf16_f32 v67, v76, v77
	v_pk_add_f32 v[76:77], v[78:79], v[92:93]
	v_lshlrev_b32_e32 v96, 16, v132
	v_and_b32_e32 v97, 0xffff0000, v132
	v_pk_add_f32 v[74:75], v[80:81], v[94:95]
	v_pk_fma_f32 v[78:79], v[76:77], v[76:77], v[86:87]
	v_lshlrev_b32_e32 v98, 16, v133
	v_and_b32_e32 v99, 0xffff0000, v133
	v_pk_add_f32 v[70:71], v[70:71], v[96:97]
	v_pk_fma_f32 v[78:79], v[74:75], v[74:75], v[78:79]
	v_pk_add_f32 v[72:73], v[72:73], v[98:99]
	v_pk_fma_f32 v[78:79], v[70:71], v[70:71], v[78:79]
	s_waitcnt lgkmcnt(0)
	v_lshlrev_b64 v[82:83], 12, v[176:177]
	v_pk_fma_f32 v[78:79], v[72:73], v[72:73], v[78:79]
	v_cvt_pk_bf16_f32 v68, v68, v69
	v_cvt_pk_bf16_f32 v69, v84, v85
	s_nop 0
	v_add_f32_e32 v80, v78, v79
	ds_bpermute_b32 v81, v186, v80
	v_lshl_add_u64 v[78:79], v[82:83], 1, s[96:97]
	v_lshl_add_u64 v[78:79], v[170:171], 1, v[78:79]
	global_store_dwordx4 v[78:79], v[66:69], off sc1
	s_waitcnt lgkmcnt(0)
	s_nop 0
	v_add_f32_e32 v66, v80, v81
	ds_bpermute_b32 v67, v114, v66
	v_cvt_pk_bf16_f32 v68, v76, v77
	v_cvt_pk_bf16_f32 v69, v74, v75
	v_cvt_pk_bf16_f32 v70, v70, v71
	v_cvt_pk_bf16_f32 v71, v72, v73
	global_store_dwordx4 v[78:79], v[68:71], off offset:256 sc1
	s_and_saveexec_b64 s[16:17], s[0:1]
	s_cbranch_execz .LBB0_1812
	s_waitcnt lgkmcnt(0)
	v_add_f32_e32 v66, v66, v67
	v_fma_f32 v66, v66, s40, 0.5
	v_trunc_f32_e32 v66, v66
	v_mul_f32_e32 v67, 0x2f800000, v66
	v_floor_f32_e32 v67, v67
	v_fmac_f32_e32 v66, 0xcf800000, v67
	v_cvt_u32_f32_e32 v66, v66
	v_cvt_u32_f32_e32 v67, v67
	v_lshl_add_u64 v[68:69], v[176:177], 3, s[8:9]
	global_atomic_add_x2 v[68:69], v[66:67], off
; __device__ __forceinline__ unsigned cvt_pk_bf16(float lo, float hi) { unsigned r; asm volatile("v_cvt_pk_bf16_f32 %0, %1, %2" : "=v"(r) : "v"(lo), "v"(hi)); return r; }
; __device__ __forceinline__ unsigned cvt_pk_bf16(float lo, float hi) { unsigned r; asm volatile("v_cvt_pk_bf16_f32 %0, %1, %2" : "=v"(r) : "v"(lo), "v"(hi)); return r; }
;     __device__ __forceinline__ void operator()(const f32x4 (&acc)[2][2][4][2], const Unit& u, int wr, int wc, int fr, int fq) const {
;     ...
;                 for (int bj = 0; bj < 2; ++bj) { const size_t off = (size_t)(row0 + ai * HALF + m * 16) * ldc + col0 + bj * HALF;
;                     if (BASE_F32) { const float* bp = (const float*)base + off; b0[m][bj] = *(const f32x4*)bp; b1[m][bj] = *(const f32x4*)(bp + 4); }
;                     else { const u32x4 r = *(const u32x4*)((const bf16_t*)base + off);
;                         b0[m][bj] = (f32x4){__uint_as_float(r.x << 16), __uint_as_float(r.x & 0xffff0000u), __uint_as_float(r.y << 16), __uint_as_float(r.y & 0xffff0000u)};
;                         b1[m][bj] = (f32x4){__uint_as_float(r.z << 16), __uint_as_float(r.z & 0xffff0000u), __uint_as_float(r.w << 16), __uint_as_float(r.w & 0xffff0000u)}; } }
; #pragma unroll
;             for (int m = 0; m < 4; ++m) { const int row = row0 + ai * HALF + m * 16; const size_t off = (size_t)row * ldc + col0; f32x2 q2 = {0.f, 0.f};
; #pragma unroll
;                 for (int bj = 0; bj < 2; ++bj) { const f32x4 v0 = acc[ai][bj][m][0] + b0[m][bj], v1 = acc[ai][bj][m][1] + b1[m][bj];
;                     { const f32x2 e0 = {v0[0], v0[1]}, e1 = {v0[2], v0[3]}, e2 = {v1[0], v1[1]}, e3 = {v1[2], v1[3]}; q2 = e0 * e0 + q2; q2 = e1 * e1 + q2; q2 = e2 * e2 + q2; q2 = e3 * e3 + q2; }
;                     u32x4 w; w.x = cvt_pk_bf16(v0[0], v0[1]); w.y = cvt_pk_bf16(v0[2], v0[3]); w.z = cvt_pk_bf16(v1[0], v1[1]); w.w = cvt_pk_bf16(v1[2], v1[3]);
;                     *(u32x4*)(out + off + bj * HALF) = w; }
;                 float q = q2.x + q2.y; q += __shfl_xor(q, 16); q += __shfl_xor(q, 32);
;                 if (fq == 0) atomicAdd(ssq + row, (ssq_t)(q * SSQ_FIX + 0.5f)); }
.LBB0_1812:
	s_or_b64 exec, exec, s[16:17]
	v_add_u32_e32 v96, 0x80, v174
	v_ashrrev_i32_e32 v97, 31, v96
	v_lshlrev_b64 v[106:107], 13, v[96:97]
	s_waitcnt lgkmcnt(0)
	v_lshl_add_u64 v[66:67], v[172:173], 0, v[106:107]
	global_load_dwordx4 v[98:101], v[66:67], off
	global_load_dwordx4 v[102:105], v[66:67], off offset:256
	v_add_u32_e32 v94, 0x90, v174
	v_add_u32_e32 v92, 0xa0, v174
	v_add_u32_e32 v90, 0xb0, v174
	v_ashrrev_i32_e32 v95, 31, v94
	v_ashrrev_i32_e32 v93, 31, v92
	v_ashrrev_i32_e32 v91, 31, v90
	v_lshlrev_b64 v[66:67], 13, v[94:95]
	v_lshlrev_b64 v[68:69], 13, v[92:93]
	v_lshlrev_b64 v[70:71], 13, v[90:91]
	v_lshl_add_u64 v[66:67], v[172:173], 0, v[66:67]
	v_lshl_add_u64 v[68:69], v[172:173], 0, v[68:69]
	v_lshl_add_u64 v[108:109], v[172:173], 0, v[70:71]
	global_load_dwordx4 v[86:89], v[66:67], off
	global_load_dwordx4 v[82:85], v[66:67], off offset:256
	global_load_dwordx4 v[78:81], v[68:69], off
	global_load_dwordx4 v[74:77], v[68:69], off offset:256
	global_load_dwordx4 v[70:73], v[108:109], off
	s_nop 0
	global_load_dwordx4 v[66:69], v[108:109], off offset:256
	s_waitcnt vmcnt(7)
	v_lshlrev_b32_e32 v108, 16, v98
	v_and_b32_e32 v109, 0xffff0000, v98
	v_lshlrev_b32_e32 v98, 16, v99
	v_and_b32_e32 v99, 0xffff0000, v99
	s_waitcnt vmcnt(6)
	v_lshlrev_b32_e32 v112, 16, v102
	v_and_b32_e32 v113, 0xffff0000, v102
	v_lshlrev_b32_e32 v102, 16, v103
	v_and_b32_e32 v103, 0xffff0000, v103
	v_pk_add_f32 v[60:61], v[60:61], v[98:99]
	v_lshlrev_b32_e32 v110, 16, v100
	v_and_b32_e32 v111, 0xffff0000, v100
	v_lshlrev_b32_e32 v100, 16, v101
	v_and_b32_e32 v101, 0xffff0000, v101
	v_lshlrev_b32_e32 v116, 16, v104
	v_and_b32_e32 v117, 0xffff0000, v104
	v_lshlrev_b32_e32 v104, 16, v105
	v_and_b32_e32 v105, 0xffff0000, v105
	v_pk_add_f32 v[58:59], v[58:59], v[108:109]
	v_pk_add_f32 v[64:65], v[64:65], v[102:103]
	v_pk_mul_f32 v[102:103], v[60:61], v[60:61]
	v_pk_add_f32 v[56:57], v[56:57], v[100:101]
	v_pk_add_f32 v[98:99], v[54:55], v[110:111]
	v_pk_add_f32 v[100:101], v[52:53], v[104:105]
	v_cvt_pk_bf16_f32 v52, v58, v59
	v_pk_fma_f32 v[58:59], v[58:59], v[58:59], v[102:103]
	v_pk_add_f32 v[62:63], v[62:63], v[112:113]
	v_pk_fma_f32 v[58:59], v[98:99], v[98:99], v[58:59]
	v_cvt_pk_bf16_f32 v53, v60, v61
	v_cvt_pk_bf16_f32 v54, v98, v99
	v_cvt_pk_bf16_f32 v55, v56, v57
	s_nop 0
	v_pk_fma_f32 v[56:57], v[56:57], v[56:57], v[58:59]
	v_pk_add_f32 v[58:59], v[50:51], v[116:117]
	v_pk_fma_f32 v[50:51], v[62:63], v[62:63], v[56:57]
	s_nop 0
	v_pk_fma_f32 v[50:51], v[64:65], v[64:65], v[50:51]
	s_nop 0
	v_pk_fma_f32 v[50:51], v[58:59], v[58:59], v[50:51]
	s_nop 0
	v_pk_fma_f32 v[50:51], v[100:101], v[100:101], v[50:51]
	s_nop 0
	v_add_f32_e32 v60, v50, v51
	ds_bpermute_b32 v61, v186, v60
	v_lshl_add_u64 v[50:51], s[96:97], 0, v[106:107]
	v_lshl_add_u64 v[56:57], v[170:171], 1, v[50:51]
	global_store_dwordx4 v[56:57], v[52:55], off sc1
	s_waitcnt lgkmcnt(0)
	v_add_f32_e32 v50, v60, v61
	ds_bpermute_b32 v51, v114, v50
	v_cvt_pk_bf16_f32 v52, v62, v63
	v_cvt_pk_bf16_f32 v53, v64, v65
	v_cvt_pk_bf16_f32 v54, v58, v59
	v_cvt_pk_bf16_f32 v55, v100, v101
	global_store_dwordx4 v[56:57], v[52:55], off offset:256 sc1
	s_and_saveexec_b64 s[16:17], s[0:1]
	s_cbranch_execz .LBB0_1814
	s_waitcnt lgkmcnt(0)
	v_add_f32_e32 v50, v50, v51
	v_fma_f32 v50, v50, s40, 0.5
	v_trunc_f32_e32 v50, v50
	v_mul_f32_e32 v51, 0x2f800000, v50
	v_floor_f32_e32 v51, v51
	v_fmac_f32_e32 v50, 0xcf800000, v51
	v_cvt_u32_f32_e32 v50, v50
	v_cvt_u32_f32_e32 v51, v51
	v_lshl_add_u64 v[52:53], v[96:97], 3, s[8:9]
	global_atomic_add_x2 v[52:53], v[50:51], off
.LBB0_1814:
	s_or_b64 exec, exec, s[16:17]
	s_waitcnt vmcnt(7)
	v_lshlrev_b32_e32 v54, 16, v87
	v_and_b32_e32 v55, 0xffff0000, v87
	v_lshlrev_b32_e32 v52, 16, v86
	v_and_b32_e32 v53, 0xffff0000, v86
	v_lshlrev_b32_e32 v56, 16, v88
	v_and_b32_e32 v57, 0xffff0000, v88
	v_lshlrev_b32_e32 v58, 16, v89
	v_and_b32_e32 v59, 0xffff0000, v89
	v_pk_add_f32 v[44:45], v[44:45], v[54:55]
	v_pk_add_f32 v[42:43], v[42:43], v[52:53]
	v_pk_add_f32 v[52:53], v[36:37], v[58:59]
	v_pk_add_f32 v[36:37], v[34:35], v[56:57]
	v_pk_mul_f32 v[34:35], v[44:45], v[44:45]
	s_waitcnt vmcnt(6)
	v_lshlrev_b32_e32 v60, 16, v82
	v_pk_fma_f32 v[34:35], v[42:43], v[42:43], v[34:35]
	v_and_b32_e32 v61, 0xffff0000, v82
	v_pk_fma_f32 v[34:35], v[36:37], v[36:37], v[34:35]
	v_lshlrev_b32_e32 v62, 16, v83
	v_and_b32_e32 v63, 0xffff0000, v83
	v_pk_fma_f32 v[54:55], v[52:53], v[52:53], v[34:35]
	v_cvt_pk_bf16_f32 v34, v42, v43
	v_cvt_pk_bf16_f32 v35, v44, v45
	v_pk_add_f32 v[44:45], v[46:47], v[60:61]
	v_lshlrev_b32_e32 v64, 16, v84
	v_and_b32_e32 v65, 0xffff0000, v84
	v_pk_add_f32 v[42:43], v[48:49], v[62:63]
	v_pk_fma_f32 v[46:47], v[44:45], v[44:45], v[54:55]
	v_lshlrev_b32_e32 v82, 16, v85
	v_and_b32_e32 v83, 0xffff0000, v85
	v_pk_add_f32 v[38:39], v[38:39], v[64:65]
	v_pk_fma_f32 v[46:47], v[42:43], v[42:43], v[46:47]
	v_pk_add_f32 v[40:41], v[40:41], v[82:83]
	v_pk_fma_f32 v[46:47], v[38:39], v[38:39], v[46:47]
	s_waitcnt lgkmcnt(0)
	v_lshlrev_b64 v[50:51], 12, v[94:95]
	v_pk_fma_f32 v[46:47], v[40:41], v[40:41], v[46:47]
	v_cvt_pk_bf16_f32 v36, v36, v37
	v_cvt_pk_bf16_f32 v37, v52, v53
	s_nop 0
	v_add_f32_e32 v48, v46, v47
	ds_bpermute_b32 v49, v186, v48
	v_lshl_add_u64 v[46:47], v[50:51], 1, s[96:97]
	v_lshl_add_u64 v[46:47], v[170:171], 1, v[46:47]
	global_store_dwordx4 v[46:47], v[34:37], off sc1
	s_waitcnt lgkmcnt(0)
	s_nop 0
	v_add_f32_e32 v34, v48, v49
	ds_bpermute_b32 v35, v114, v34
	v_cvt_pk_bf16_f32 v36, v44, v45
	v_cvt_pk_bf16_f32 v37, v42, v43
	v_cvt_pk_bf16_f32 v38, v38, v39
	v_cvt_pk_bf16_f32 v39, v40, v41
	global_store_dwordx4 v[46:47], v[36:39], off offset:256 sc1
	s_and_saveexec_b64 s[16:17], s[0:1]
	s_cbranch_execz .LBB0_1816
	s_waitcnt lgkmcnt(0)
	v_add_f32_e32 v34, v34, v35
	v_fma_f32 v34, v34, s40, 0.5
	v_trunc_f32_e32 v34, v34
	v_mul_f32_e32 v35, 0x2f800000, v34
	v_floor_f32_e32 v35, v35
	v_fmac_f32_e32 v34, 0xcf800000, v35
	v_cvt_u32_f32_e32 v34, v34
	v_cvt_u32_f32_e32 v35, v35
	v_lshl_add_u64 v[36:37], v[94:95], 3, s[8:9]
	global_atomic_add_x2 v[36:37], v[34:35], off
; __device__ __forceinline__ unsigned cvt_pk_bf16(float lo, float hi) { unsigned r; asm volatile("v_cvt_pk_bf16_f32 %0, %1, %2" : "=v"(r) : "v"(lo), "v"(hi)); return r; }
; __device__ __forceinline__ unsigned cvt_pk_bf16(float lo, float hi) { unsigned r; asm volatile("v_cvt_pk_bf16_f32 %0, %1, %2" : "=v"(r) : "v"(lo), "v"(hi)); return r; }
;     __device__ __forceinline__ void operator()(const f32x4 (&acc)[2][2][4][2], const Unit& u, int wr, int wc, int fr, int fq) const {
;     ...
;                 for (int bj = 0; bj < 2; ++bj) { const size_t off = (size_t)(row0 + ai * HALF + m * 16) * ldc + col0 + bj * HALF;
;                     if (BASE_F32) { const float* bp = (const float*)base + off; b0[m][bj] = *(const f32x4*)bp; b1[m][bj] = *(const f32x4*)(bp + 4); }
;                     else { const u32x4 r = *(const u32x4*)((const bf16_t*)base + off);
;                         b0[m][bj] = (f32x4){__uint_as_float(r.x << 16), __uint_as_float(r.x & 0xffff0000u), __uint_as_float(r.y << 16), __uint_as_float(r.y & 0xffff0000u)};
;                         b1[m][bj] = (f32x4){__uint_as_float(r.z << 16), __uint_as_float(r.z & 0xffff0000u), __uint_as_float(r.w << 16), __uint_as_float(r.w & 0xffff0000u)}; } }
; #pragma unroll
;             for (int m = 0; m < 4; ++m) { const int row = row0 + ai * HALF + m * 16; const size_t off = (size_t)row * ldc + col0; f32x2 q2 = {0.f, 0.f};
; #pragma unroll
;                 for (int bj = 0; bj < 2; ++bj) { const f32x4 v0 = acc[ai][bj][m][0] + b0[m][bj], v1 = acc[ai][bj][m][1] + b1[m][bj];
;                     { const f32x2 e0 = {v0[0], v0[1]}, e1 = {v0[2], v0[3]}, e2 = {v1[0], v1[1]}, e3 = {v1[2], v1[3]}; q2 = e0 * e0 + q2; q2 = e1 * e1 + q2; q2 = e2 * e2 + q2; q2 = e3 * e3 + q2; }
;                     u32x4 w; w.x = cvt_pk_bf16(v0[0], v0[1]); w.y = cvt_pk_bf16(v0[2], v0[3]); w.z = cvt_pk_bf16(v1[0], v1[1]); w.w = cvt_pk_bf16(v1[2], v1[3]);
;                     *(u32x4*)(out + off + bj * HALF) = w; }
;                 float q = q2.x + q2.y; q += __shfl_xor(q, 16); q += __shfl_xor(q, 32);
;                 if (fq == 0) atomicAdd(ssq + row, (ssq_t)(q * SSQ_FIX + 0.5f)); }
.LBB0_1816:
	s_or_b64 exec, exec, s[16:17]
	s_waitcnt vmcnt(7)
	v_lshlrev_b32_e32 v38, 16, v79
	v_and_b32_e32 v39, 0xffff0000, v79
	v_lshlrev_b32_e32 v36, 16, v78
	v_and_b32_e32 v37, 0xffff0000, v78
	v_lshlrev_b32_e32 v40, 16, v80
	v_and_b32_e32 v41, 0xffff0000, v80
	v_lshlrev_b32_e32 v42, 16, v81
	v_and_b32_e32 v43, 0xffff0000, v81
	v_pk_add_f32 v[28:29], v[28:29], v[38:39]
	v_pk_add_f32 v[26:27], v[26:27], v[36:37]
	v_pk_add_f32 v[36:37], v[20:21], v[42:43]
	v_pk_add_f32 v[20:21], v[18:19], v[40:41]
	v_pk_mul_f32 v[18:19], v[28:29], v[28:29]
	s_waitcnt vmcnt(6)
	v_lshlrev_b32_e32 v44, 16, v74
	v_pk_fma_f32 v[18:19], v[26:27], v[26:27], v[18:19]
	v_and_b32_e32 v45, 0xffff0000, v74
	v_pk_fma_f32 v[18:19], v[20:21], v[20:21], v[18:19]
	v_lshlrev_b32_e32 v46, 16, v75
	v_and_b32_e32 v47, 0xffff0000, v75
	v_pk_fma_f32 v[38:39], v[36:37], v[36:37], v[18:19]
	v_cvt_pk_bf16_f32 v18, v26, v27
	v_cvt_pk_bf16_f32 v19, v28, v29
	v_pk_add_f32 v[28:29], v[30:31], v[44:45]
	v_lshlrev_b32_e32 v48, 16, v76
	v_and_b32_e32 v49, 0xffff0000, v76
	v_pk_add_f32 v[26:27], v[32:33], v[46:47]
	v_pk_fma_f32 v[30:31], v[28:29], v[28:29], v[38:39]
	v_lshlrev_b32_e32 v50, 16, v77
	v_and_b32_e32 v51, 0xffff0000, v77
	v_pk_add_f32 v[22:23], v[22:23], v[48:49]
	v_pk_fma_f32 v[30:31], v[26:27], v[26:27], v[30:31]
	v_pk_add_f32 v[24:25], v[24:25], v[50:51]
	v_pk_fma_f32 v[30:31], v[22:23], v[22:23], v[30:31]
	s_waitcnt lgkmcnt(0)
	v_lshlrev_b64 v[34:35], 12, v[92:93]
	v_pk_fma_f32 v[30:31], v[24:25], v[24:25], v[30:31]
	v_cvt_pk_bf16_f32 v20, v20, v21
	v_cvt_pk_bf16_f32 v21, v36, v37
	s_nop 0
	v_add_f32_e32 v32, v30, v31
	ds_bpermute_b32 v33, v186, v32
	v_lshl_add_u64 v[30:31], v[34:35], 1, s[96:97]
	v_lshl_add_u64 v[30:31], v[170:171], 1, v[30:31]
	global_store_dwordx4 v[30:31], v[18:21], off sc1
	s_waitcnt lgkmcnt(0)
	s_nop 0
	v_add_f32_e32 v18, v32, v33
	ds_bpermute_b32 v19, v114, v18
	v_cvt_pk_bf16_f32 v20, v28, v29
	v_cvt_pk_bf16_f32 v21, v26, v27
	v_cvt_pk_bf16_f32 v22, v22, v23
	v_cvt_pk_bf16_f32 v23, v24, v25
	global_store_dwordx4 v[30:31], v[20:23], off offset:256 sc1
	s_and_saveexec_b64 s[16:17], s[0:1]
	s_cbranch_execz .LBB0_1818
	s_waitcnt lgkmcnt(0)
	v_add_f32_e32 v18, v18, v19
	v_fma_f32 v18, v18, s40, 0.5
	v_trunc_f32_e32 v18, v18
	v_mul_f32_e32 v19, 0x2f800000, v18
	v_floor_f32_e32 v19, v19
	v_fmac_f32_e32 v18, 0xcf800000, v19
	v_cvt_u32_f32_e32 v18, v18
	v_cvt_u32_f32_e32 v19, v19
	v_lshl_add_u64 v[20:21], v[92:93], 3, s[8:9]
	global_atomic_add_x2 v[20:21], v[18:19], off
.LBB0_1818:
	s_or_b64 exec, exec, s[16:17]
	s_waitcnt vmcnt(7)
	v_lshlrev_b32_e32 v22, 16, v71
	v_and_b32_e32 v23, 0xffff0000, v71
	v_lshlrev_b32_e32 v20, 16, v70
	v_and_b32_e32 v21, 0xffff0000, v70
	v_lshlrev_b32_e32 v24, 16, v72
	v_and_b32_e32 v25, 0xffff0000, v72
	v_lshlrev_b32_e32 v26, 16, v73
	v_and_b32_e32 v27, 0xffff0000, v73
	v_pk_add_f32 v[8:9], v[8:9], v[22:23]
	v_pk_add_f32 v[6:7], v[6:7], v[20:21]
	v_pk_add_f32 v[20:21], v[4:5], v[26:27]
	v_pk_add_f32 v[4:5], v[2:3], v[24:25]
	v_pk_mul_f32 v[2:3], v[8:9], v[8:9]
	s_waitcnt vmcnt(6)
	v_lshlrev_b32_e32 v28, 16, v66
	v_pk_fma_f32 v[2:3], v[6:7], v[6:7], v[2:3]
	v_and_b32_e32 v29, 0xffff0000, v66
	v_pk_fma_f32 v[2:3], v[4:5], v[4:5], v[2:3]
	v_lshlrev_b32_e32 v30, 16, v67
	v_and_b32_e32 v31, 0xffff0000, v67
	v_lshlrev_b32_e32 v32, 16, v68
	v_and_b32_e32 v33, 0xffff0000, v68
	v_pk_fma_f32 v[22:23], v[20:21], v[20:21], v[2:3]
	v_cvt_pk_bf16_f32 v2, v6, v7
	v_cvt_pk_bf16_f32 v3, v8, v9
	v_pk_add_f32 v[8:9], v[10:11], v[28:29]
	v_pk_add_f32 v[6:7], v[12:13], v[30:31]
	v_pk_add_f32 v[12:13], v[14:15], v[32:33]
	v_pk_fma_f32 v[14:15], v[8:9], v[8:9], v[22:23]
	v_lshlrev_b32_e32 v34, 16, v69
	v_and_b32_e32 v35, 0xffff0000, v69
	v_pk_fma_f32 v[14:15], v[6:7], v[6:7], v[14:15]
	v_pk_add_f32 v[10:11], v[16:17], v[34:35]
	v_pk_fma_f32 v[14:15], v[12:13], v[12:13], v[14:15]
	s_waitcnt lgkmcnt(0)
	v_lshlrev_b64 v[18:19], 12, v[90:91]
	v_pk_fma_f32 v[14:15], v[10:11], v[10:11], v[14:15]
	v_cvt_pk_bf16_f32 v4, v4, v5
	v_cvt_pk_bf16_f32 v5, v20, v21
	s_nop 0
	v_add_f32_e32 v16, v14, v15
	ds_bpermute_b32 v17, v186, v16
	v_lshl_add_u64 v[14:15], v[18:19], 1, s[96:97]
	v_lshl_add_u64 v[14:15], v[170:171], 1, v[14:15]
	global_store_dwordx4 v[14:15], v[2:5], off sc1
	s_waitcnt lgkmcnt(0)
	s_nop 0
	v_add_f32_e32 v2, v16, v17
	ds_bpermute_b32 v3, v114, v2
	v_cvt_pk_bf16_f32 v4, v8, v9
	v_cvt_pk_bf16_f32 v5, v6, v7
	v_cvt_pk_bf16_f32 v6, v12, v13
	v_cvt_pk_bf16_f32 v7, v10, v11
	global_store_dwordx4 v[14:15], v[4:7], off offset:256 sc1
	s_and_saveexec_b64 s[16:17], s[0:1]
	s_cbranch_execz .LBB0_1820
	s_waitcnt lgkmcnt(0)
	v_add_f32_e32 v2, v2, v3
	v_fma_f32 v2, v2, s40, 0.5
	v_trunc_f32_e32 v2, v2
	v_mul_f32_e32 v3, 0x2f800000, v2
	v_floor_f32_e32 v3, v3
	v_fmac_f32_e32 v2, 0xcf800000, v3
	v_cvt_u32_f32_e32 v2, v2
	v_cvt_u32_f32_e32 v3, v3
	v_lshl_add_u64 v[4:5], v[90:91], 3, s[8:9]
	global_atomic_add_x2 v[4:5], v[2:3], off
